# loop-edge edit: K-loop trip counter and tile-pointer SALU moved before the loop-back barrier (15 K-loops), on top of the epilogue stack
# baseline (speedup 1.0000x reference)
.LBB0_103:
	ds_read_b128 v[128:131], v161
	ds_read_b128 v[154:157], v161 offset:1024
	ds_read_b128 v[166:169], v161 offset:2048
	ds_read_b128 v[170:173], v161 offset:3072
	ds_read_b128 v[174:177], v162
	ds_read_b128 v[178:181], v162 offset:1024
	ds_read_b128 v[182:185], v162 offset:2048
	ds_read_b128 v[186:189], v162 offset:3072
	s_add_u32 s52, s50, 0xfffc0080
	s_addc_u32 s53, s51, -1
	s_cmp_eq_u32 s77, 12
	s_cselect_b32 s55, s33, s53
	s_cselect_b32 s54, s39, s52
	s_cselect_b32 s53, s41, s76
	s_cselect_b32 s52, s43, s49
	v_lshl_add_u64 v[158:159], s[50:51], 0, v[146:147]
	s_add_i32 m0, s63, 0xc000
	ds_read_b128 v[192:195], v163
	ds_read_b128 v[196:199], v163 offset:1024
	ds_read_b128 v[200:203], v163 offset:2048
	ds_read_b128 v[204:207], v163 offset:3072
	ds_read_b128 v[208:211], v163 offset:4096
	ds_read_b128 v[212:215], v163 offset:5120
	ds_read_b128 v[216:219], v163 offset:6144
	ds_read_b128 v[220:223], v163 offset:7168
	global_load_lds_dwordx4 v[158:159], off
	v_lshl_add_u64 v[158:159], s[50:51], 0, v[144:145]
	s_add_i32 m0, s63, 0xe000
	s_nop 0
	global_load_lds_dwordx4 v[158:159], off
	s_waitcnt vmcnt(8)
	s_waitcnt lgkmcnt(0)
	s_barrier
	s_setprio 1
	s_waitcnt lgkmcnt(0)
	v_mfma_f32_16x16x32_bf16 v[124:127], v[128:131], v[192:195], v[124:127]
	v_mfma_f32_16x16x32_bf16 v[120:123], v[166:169], v[192:195], v[120:123]
	v_mfma_f32_16x16x32_bf16 v[108:111], v[128:131], v[200:203], v[108:111]
	v_mfma_f32_16x16x32_bf16 v[104:107], v[166:169], v[200:203], v[104:107]
	v_mfma_f32_16x16x32_bf16 v[92:95], v[128:131], v[208:211], v[92:95]
	v_mfma_f32_16x16x32_bf16 v[88:91], v[166:169], v[208:211], v[88:91]
	v_mfma_f32_16x16x32_bf16 v[76:79], v[128:131], v[216:219], v[76:79]
	v_mfma_f32_16x16x32_bf16 v[72:75], v[166:169], v[216:219], v[72:75]
	v_mfma_f32_16x16x32_bf16 v[124:127], v[154:157], v[196:199], v[124:127]
	v_mfma_f32_16x16x32_bf16 v[120:123], v[170:173], v[196:199], v[120:123]
	v_mfma_f32_16x16x32_bf16 v[108:111], v[154:157], v[204:207], v[108:111]
	v_mfma_f32_16x16x32_bf16 v[104:107], v[170:173], v[204:207], v[104:107]
	v_mfma_f32_16x16x32_bf16 v[92:95], v[154:157], v[212:215], v[92:95]
	v_mfma_f32_16x16x32_bf16 v[88:91], v[170:173], v[212:215], v[88:91]
	v_mfma_f32_16x16x32_bf16 v[76:79], v[154:157], v[220:223], v[76:79]
	v_mfma_f32_16x16x32_bf16 v[72:75], v[170:173], v[220:223], v[72:75]
	s_setprio 0
	s_setprio 1
	v_mfma_f32_16x16x32_bf16 v[116:119], v[174:177], v[192:195], v[116:119]
	v_mfma_f32_16x16x32_bf16 v[112:115], v[182:185], v[192:195], v[112:115]
	v_mfma_f32_16x16x32_bf16 v[100:103], v[174:177], v[200:203], v[100:103]
	v_mfma_f32_16x16x32_bf16 v[96:99], v[182:185], v[200:203], v[96:99]
	v_mfma_f32_16x16x32_bf16 v[84:87], v[174:177], v[208:211], v[84:87]
	v_mfma_f32_16x16x32_bf16 v[80:83], v[182:185], v[208:211], v[80:83]
	v_mfma_f32_16x16x32_bf16 v[68:71], v[174:177], v[216:219], v[68:71]
	v_mfma_f32_16x16x32_bf16 v[64:67], v[182:185], v[216:219], v[64:67]
	v_mfma_f32_16x16x32_bf16 v[116:119], v[178:181], v[196:199], v[116:119]
	v_mfma_f32_16x16x32_bf16 v[112:115], v[186:189], v[196:199], v[112:115]
	v_mfma_f32_16x16x32_bf16 v[100:103], v[178:181], v[204:207], v[100:103]
	v_mfma_f32_16x16x32_bf16 v[96:99], v[186:189], v[204:207], v[96:99]
	v_mfma_f32_16x16x32_bf16 v[84:87], v[178:181], v[212:215], v[84:87]
	v_mfma_f32_16x16x32_bf16 v[80:83], v[186:189], v[212:215], v[80:83]
	v_mfma_f32_16x16x32_bf16 v[68:71], v[178:181], v[220:223], v[68:71]
	v_mfma_f32_16x16x32_bf16 v[64:67], v[186:189], v[220:223], v[64:67]
	s_setprio 0
	s_barrier
	s_add_i32 s78, s71, s60
	v_lshl_add_u64 v[158:159], s[52:53], 0, v[136:137]
	s_mov_b32 m0, s78
	ds_read_b128 v[192:195], v163 offset:16384
	ds_read_b128 v[196:199], v163 offset:17408
	ds_read_b128 v[200:203], v163 offset:18432
	ds_read_b128 v[204:207], v163 offset:19456
	ds_read_b128 v[208:211], v163 offset:20480
	ds_read_b128 v[212:215], v163 offset:21504
	ds_read_b128 v[216:219], v163 offset:22528
	ds_read_b128 v[220:223], v163 offset:23552
	global_load_lds_dwordx4 v[158:159], off
	s_add_i32 m0, s78, 0x2000
	s_add_u32 s78, s52, 0x40000
	v_lshl_add_u64 v[224:225], s[52:53], 0, v[132:133]
	s_addc_u32 s79, s53, 0
	s_add_i32 s80, s72, s60
	global_load_lds_dwordx4 v[224:225], off
	v_lshl_add_u64 v[226:227], s[78:79], 0, v[136:137]
	s_mov_b32 m0, s80
	v_lshl_add_u64 v[228:229], s[54:55], 0, v[134:135]
	global_load_lds_dwordx4 v[226:227], off
	v_lshl_add_u64 v[226:227], s[78:79], 0, v[132:133]
	s_add_i32 m0, s80, 0x2000
	s_nop 0
	global_load_lds_dwordx4 v[226:227], off
	v_lshl_add_u64 v[226:227], s[54:55], 0, v[138:139]
	s_mov_b32 m0, s63
	s_nop 0
	global_load_lds_dwordx4 v[226:227], off
	s_mov_b32 m0, s64
	s_nop 0
	global_load_lds_dwordx4 v[228:229], off
	s_waitcnt vmcnt(8)
	s_waitcnt lgkmcnt(0)
	s_barrier
	s_setprio 1
	s_waitcnt lgkmcnt(0)
	v_mfma_f32_16x16x32_bf16 v[60:63], v[128:131], v[192:195], v[60:63]
	v_mfma_f32_16x16x32_bf16 v[56:59], v[166:169], v[192:195], v[56:59]
	v_mfma_f32_16x16x32_bf16 v[44:47], v[128:131], v[200:203], v[44:47]
	v_mfma_f32_16x16x32_bf16 v[40:43], v[166:169], v[200:203], v[40:43]
	v_mfma_f32_16x16x32_bf16 v[28:31], v[128:131], v[208:211], v[28:31]
	v_mfma_f32_16x16x32_bf16 v[24:27], v[166:169], v[208:211], v[24:27]
	v_mfma_f32_16x16x32_bf16 v[12:15], v[128:131], v[216:219], v[12:15]
	v_mfma_f32_16x16x32_bf16 v[8:11], v[166:169], v[216:219], v[8:11]
	v_mfma_f32_16x16x32_bf16 v[60:63], v[154:157], v[196:199], v[60:63]
	v_mfma_f32_16x16x32_bf16 v[56:59], v[170:173], v[196:199], v[56:59]
	v_mfma_f32_16x16x32_bf16 v[44:47], v[154:157], v[204:207], v[44:47]
	v_mfma_f32_16x16x32_bf16 v[40:43], v[170:173], v[204:207], v[40:43]
	v_mfma_f32_16x16x32_bf16 v[28:31], v[154:157], v[212:215], v[28:31]
	v_mfma_f32_16x16x32_bf16 v[24:27], v[170:173], v[212:215], v[24:27]
	v_mfma_f32_16x16x32_bf16 v[12:15], v[154:157], v[220:223], v[12:15]
	v_mfma_f32_16x16x32_bf16 v[8:11], v[170:173], v[220:223], v[8:11]
	s_setprio 0
	s_setprio 1
	v_mfma_f32_16x16x32_bf16 v[52:55], v[174:177], v[192:195], v[52:55]
	v_mfma_f32_16x16x32_bf16 v[48:51], v[182:185], v[192:195], v[48:51]
	v_mfma_f32_16x16x32_bf16 v[36:39], v[174:177], v[200:203], v[36:39]
	v_mfma_f32_16x16x32_bf16 v[32:35], v[182:185], v[200:203], v[32:35]
	v_mfma_f32_16x16x32_bf16 v[20:23], v[174:177], v[208:211], v[20:23]
	v_mfma_f32_16x16x32_bf16 v[16:19], v[182:185], v[208:211], v[16:19]
	v_mfma_f32_16x16x32_bf16 v[4:7], v[174:177], v[216:219], v[4:7]
	v_mfma_f32_16x16x32_bf16 v[0:3], v[182:185], v[216:219], v[0:3]
	v_mfma_f32_16x16x32_bf16 v[52:55], v[178:181], v[196:199], v[52:55]
	v_mfma_f32_16x16x32_bf16 v[48:51], v[186:189], v[196:199], v[48:51]
	v_mfma_f32_16x16x32_bf16 v[36:39], v[178:181], v[204:207], v[36:39]
	v_mfma_f32_16x16x32_bf16 v[32:35], v[186:189], v[204:207], v[32:35]
	v_mfma_f32_16x16x32_bf16 v[20:23], v[178:181], v[212:215], v[20:23]
	v_mfma_f32_16x16x32_bf16 v[16:19], v[186:189], v[212:215], v[16:19]
	v_mfma_f32_16x16x32_bf16 v[4:7], v[178:181], v[220:223], v[4:7]
	v_mfma_f32_16x16x32_bf16 v[0:3], v[186:189], v[220:223], v[0:3]
	s_setprio 0
	s_barrier
	s_add_i32 s78, 0, 0x18000
	v_add_u32_e32 v140, s78, v160
	s_add_i32 s79, 0, 0x1c000
	ds_read_b128 v[128:131], v140
	ds_read_b128 v[154:157], v140 offset:1024
	ds_read_b128 v[166:169], v140 offset:2048
	ds_read_b128 v[170:173], v140 offset:3072
	v_add_u32_e32 v140, s79, v160
	ds_read_b128 v[174:177], v140
	ds_read_b128 v[178:181], v140 offset:1024
	ds_read_b128 v[182:185], v140 offset:2048
	ds_read_b128 v[186:189], v140 offset:3072
	s_add_u32 s54, s54, 0x40000
	s_addc_u32 s55, s55, 0
	s_mov_b32 m0, s65
	v_lshl_add_u64 v[230:231], s[54:55], 0, v[138:139]
	ds_read_b128 v[192:195], v163 offset:32768
	ds_read_b128 v[196:199], v163 offset:33792
	ds_read_b128 v[200:203], v163 offset:34816
	ds_read_b128 v[204:207], v163 offset:35840
	ds_read_b128 v[208:211], v163 offset:36864
	ds_read_b128 v[212:215], v163 offset:37888
	ds_read_b128 v[216:219], v163 offset:38912
	ds_read_b128 v[220:223], v163 offset:39936
	global_load_lds_dwordx4 v[230:231], off
	v_lshl_add_u64 v[230:231], s[54:55], 0, v[134:135]
	s_mov_b32 m0, s66
	s_nop 0
	global_load_lds_dwordx4 v[230:231], off
	s_waitcnt vmcnt(8)
	s_waitcnt lgkmcnt(0)
	s_barrier
	s_setprio 1
	s_waitcnt lgkmcnt(0)
	v_mfma_f32_16x16x32_bf16 v[124:127], v[128:131], v[192:195], v[124:127]
	v_mfma_f32_16x16x32_bf16 v[120:123], v[166:169], v[192:195], v[120:123]
	v_mfma_f32_16x16x32_bf16 v[108:111], v[128:131], v[200:203], v[108:111]
	v_mfma_f32_16x16x32_bf16 v[104:107], v[166:169], v[200:203], v[104:107]
	v_mfma_f32_16x16x32_bf16 v[92:95], v[128:131], v[208:211], v[92:95]
	v_mfma_f32_16x16x32_bf16 v[88:91], v[166:169], v[208:211], v[88:91]
	v_mfma_f32_16x16x32_bf16 v[76:79], v[128:131], v[216:219], v[76:79]
	v_mfma_f32_16x16x32_bf16 v[72:75], v[166:169], v[216:219], v[72:75]
	v_mfma_f32_16x16x32_bf16 v[124:127], v[154:157], v[196:199], v[124:127]
	v_mfma_f32_16x16x32_bf16 v[120:123], v[170:173], v[196:199], v[120:123]
	v_mfma_f32_16x16x32_bf16 v[108:111], v[154:157], v[204:207], v[108:111]
	v_mfma_f32_16x16x32_bf16 v[104:107], v[170:173], v[204:207], v[104:107]
	v_mfma_f32_16x16x32_bf16 v[92:95], v[154:157], v[212:215], v[92:95]
	v_mfma_f32_16x16x32_bf16 v[88:91], v[170:173], v[212:215], v[88:91]
	v_mfma_f32_16x16x32_bf16 v[76:79], v[154:157], v[220:223], v[76:79]
	v_mfma_f32_16x16x32_bf16 v[72:75], v[170:173], v[220:223], v[72:75]
	s_setprio 0
	s_setprio 1
	v_mfma_f32_16x16x32_bf16 v[116:119], v[174:177], v[192:195], v[116:119]
	v_mfma_f32_16x16x32_bf16 v[112:115], v[182:185], v[192:195], v[112:115]
	v_mfma_f32_16x16x32_bf16 v[100:103], v[174:177], v[200:203], v[100:103]
	v_mfma_f32_16x16x32_bf16 v[96:99], v[182:185], v[200:203], v[96:99]
	v_mfma_f32_16x16x32_bf16 v[84:87], v[174:177], v[208:211], v[84:87]
	v_mfma_f32_16x16x32_bf16 v[80:83], v[182:185], v[208:211], v[80:83]
	v_mfma_f32_16x16x32_bf16 v[68:71], v[174:177], v[216:219], v[68:71]
	v_mfma_f32_16x16x32_bf16 v[64:67], v[182:185], v[216:219], v[64:67]
	v_mfma_f32_16x16x32_bf16 v[116:119], v[178:181], v[196:199], v[116:119]
	v_mfma_f32_16x16x32_bf16 v[112:115], v[186:189], v[196:199], v[112:115]
	v_mfma_f32_16x16x32_bf16 v[100:103], v[178:181], v[204:207], v[100:103]
	v_mfma_f32_16x16x32_bf16 v[96:99], v[186:189], v[204:207], v[96:99]
	v_mfma_f32_16x16x32_bf16 v[84:87], v[178:181], v[212:215], v[84:87]
	v_mfma_f32_16x16x32_bf16 v[80:83], v[186:189], v[212:215], v[80:83]
	v_mfma_f32_16x16x32_bf16 v[68:71], v[178:181], v[220:223], v[68:71]
	v_mfma_f32_16x16x32_bf16 v[64:67], v[186:189], v[220:223], v[64:67]
	s_setprio 0
	s_barrier
	s_add_i32 s54, s78, s60
	v_lshl_add_u64 v[158:159], v[158:159], 0, s[34:35]
	s_mov_b32 m0, s54
	ds_read_b128 v[192:195], v163 offset:49152
	ds_read_b128 v[196:199], v163 offset:50176
	ds_read_b128 v[200:203], v163 offset:51200
	ds_read_b128 v[204:207], v163 offset:52224
	ds_read_b128 v[208:211], v163 offset:53248
	ds_read_b128 v[212:215], v163 offset:54272
	ds_read_b128 v[216:219], v163 offset:55296
	ds_read_b128 v[220:223], v163 offset:56320
	global_load_lds_dwordx4 v[158:159], off
	s_add_i32 m0, s54, 0x2000
	s_add_u32 s52, s52, 0x40080
	v_lshl_add_u64 v[158:159], v[224:225], 0, s[34:35]
	s_addc_u32 s53, s53, 0
	s_add_i32 s54, s79, s60
	global_load_lds_dwordx4 v[158:159], off
	v_lshl_add_u64 v[158:159], s[52:53], 0, v[136:137]
	s_mov_b32 m0, s54
	s_nop 0
	global_load_lds_dwordx4 v[158:159], off
	v_lshl_add_u64 v[158:159], s[52:53], 0, v[132:133]
	s_add_i32 m0, s54, 0x2000
	s_nop 0
	global_load_lds_dwordx4 v[158:159], off
	v_lshl_add_u64 v[158:159], v[226:227], 0, s[34:35]
	s_mov_b32 m0, s67
	s_nop 0
	global_load_lds_dwordx4 v[158:159], off
	v_lshl_add_u64 v[158:159], v[228:229], 0, s[34:35]
	s_mov_b32 m0, s68
	s_nop 0
	global_load_lds_dwordx4 v[158:159], off
	s_waitcnt vmcnt(8)
	s_waitcnt lgkmcnt(0)
	s_barrier
	s_setprio 1
	s_waitcnt lgkmcnt(0)
	v_mfma_f32_16x16x32_bf16 v[60:63], v[128:131], v[192:195], v[60:63]
	v_mfma_f32_16x16x32_bf16 v[56:59], v[166:169], v[192:195], v[56:59]
	v_mfma_f32_16x16x32_bf16 v[44:47], v[128:131], v[200:203], v[44:47]
	v_mfma_f32_16x16x32_bf16 v[40:43], v[166:169], v[200:203], v[40:43]
	v_mfma_f32_16x16x32_bf16 v[28:31], v[128:131], v[208:211], v[28:31]
	v_mfma_f32_16x16x32_bf16 v[24:27], v[166:169], v[208:211], v[24:27]
	v_mfma_f32_16x16x32_bf16 v[12:15], v[128:131], v[216:219], v[12:15]
	v_mfma_f32_16x16x32_bf16 v[8:11], v[166:169], v[216:219], v[8:11]
	v_mfma_f32_16x16x32_bf16 v[60:63], v[154:157], v[196:199], v[60:63]
	v_mfma_f32_16x16x32_bf16 v[56:59], v[170:173], v[196:199], v[56:59]
	v_mfma_f32_16x16x32_bf16 v[44:47], v[154:157], v[204:207], v[44:47]
	v_mfma_f32_16x16x32_bf16 v[40:43], v[170:173], v[204:207], v[40:43]
	v_mfma_f32_16x16x32_bf16 v[28:31], v[154:157], v[212:215], v[28:31]
	v_mfma_f32_16x16x32_bf16 v[24:27], v[170:173], v[212:215], v[24:27]
	v_mfma_f32_16x16x32_bf16 v[12:15], v[154:157], v[220:223], v[12:15]
	v_mfma_f32_16x16x32_bf16 v[8:11], v[170:173], v[220:223], v[8:11]
	s_setprio 0
	s_setprio 1
	v_mfma_f32_16x16x32_bf16 v[52:55], v[174:177], v[192:195], v[52:55]
	v_mfma_f32_16x16x32_bf16 v[48:51], v[182:185], v[192:195], v[48:51]
	v_mfma_f32_16x16x32_bf16 v[36:39], v[174:177], v[200:203], v[36:39]
	v_mfma_f32_16x16x32_bf16 v[32:35], v[182:185], v[200:203], v[32:35]
	v_mfma_f32_16x16x32_bf16 v[20:23], v[174:177], v[208:211], v[20:23]
	v_mfma_f32_16x16x32_bf16 v[16:19], v[182:185], v[208:211], v[16:19]
	v_mfma_f32_16x16x32_bf16 v[4:7], v[174:177], v[216:219], v[4:7]
	v_mfma_f32_16x16x32_bf16 v[0:3], v[182:185], v[216:219], v[0:3]
	v_mfma_f32_16x16x32_bf16 v[52:55], v[178:181], v[196:199], v[52:55]
	v_mfma_f32_16x16x32_bf16 v[48:51], v[186:189], v[196:199], v[48:51]
	v_mfma_f32_16x16x32_bf16 v[36:39], v[178:181], v[204:207], v[36:39]
	v_mfma_f32_16x16x32_bf16 v[32:35], v[186:189], v[204:207], v[32:35]
	v_mfma_f32_16x16x32_bf16 v[20:23], v[178:181], v[212:215], v[20:23]
	v_mfma_f32_16x16x32_bf16 v[16:19], v[186:189], v[212:215], v[16:19]
	v_mfma_f32_16x16x32_bf16 v[4:7], v[178:181], v[220:223], v[4:7]
	v_mfma_f32_16x16x32_bf16 v[0:3], v[186:189], v[220:223], v[0:3]
	s_setprio 0
	s_add_i32 s77, s77, 2
	s_add_u32 s49, s49, 0x100
	s_addc_u32 s76, s76, 0
	s_add_u32 s50, s50, 0x100
	s_addc_u32 s51, s51, 0
	s_cmp_gt_u32 s77, 13
	s_barrier
	s_cbranch_scc0 .LBB0_103
	v_lshl_add_u32 v214, s48, 8, v143
	v_ashrrev_i32_e32 v215, 31, v214
	v_lshl_add_u64 v[212:213], v[214:215], 2, s[4:5]
	global_load_dword v204, v[212:213], off
	global_load_dword v205, v[212:213], off offset:64
	global_load_dword v206, v[212:213], off offset:128
	global_load_dword v207, v[212:213], off offset:192
	global_load_dword v208, v[212:213], off offset:512
	global_load_dword v209, v[212:213], off offset:576
	global_load_dword v210, v[212:213], off offset:640
	global_load_dword v211, v[212:213], off offset:704
	s_and_b64 vcc, exec, s[36:37]
	s_cbranch_vccz .LBB0_106
	s_barrier

.LBB0_250:
	ds_read_b128 v[128:131], v173
	ds_read_b128 v[132:135], v173 offset:1024
	ds_read_b128 v[136:139], v173 offset:2048
	ds_read_b128 v[140:143], v173 offset:3072
	ds_read_b128 v[156:159], v174
	ds_read_b128 v[160:163], v174 offset:1024
	ds_read_b128 v[164:167], v174 offset:2048
	ds_read_b128 v[178:181], v174 offset:3072
	s_add_u32 s56, s54, 0x100
	s_addc_u32 s57, s55, 0
	s_cmp_eq_u32 s86, 40
	s_cselect_b32 s61, s5, s57
	s_cselect_b32 s60, s4, s56
	s_cselect_b32 s59, s53, s85
	s_cselect_b32 s58, s52, s84
	v_lshl_add_u64 v[168:169], s[54:55], 0, v[150:151]
	s_add_i32 m0, s67, 0xc000
	ds_read_b128 v[182:185], v175
	ds_read_b128 v[186:189], v175 offset:1024
	ds_read_b128 v[192:195], v175 offset:2048
	ds_read_b128 v[196:199], v175 offset:3072
	ds_read_b128 v[200:203], v175 offset:4096
	ds_read_b128 v[204:207], v175 offset:5120
	ds_read_b128 v[208:211], v175 offset:6144
	ds_read_b128 v[212:215], v175 offset:7168
	global_load_lds_dwordx4 v[168:169], off
	v_lshl_add_u64 v[168:169], s[54:55], 0, v[148:149]
	s_add_i32 m0, s67, 0xe000
	s_nop 0
	global_load_lds_dwordx4 v[168:169], off
	s_waitcnt vmcnt(8)
	s_waitcnt lgkmcnt(0)
	s_barrier
	s_setprio 1
	s_waitcnt lgkmcnt(0)
	v_mfma_f32_16x16x32_bf16 v[124:127], v[128:131], v[182:185], v[124:127]
	v_mfma_f32_16x16x32_bf16 v[120:123], v[136:139], v[182:185], v[120:123]
	v_mfma_f32_16x16x32_bf16 v[108:111], v[128:131], v[192:195], v[108:111]
	v_mfma_f32_16x16x32_bf16 v[104:107], v[136:139], v[192:195], v[104:107]
	v_mfma_f32_16x16x32_bf16 v[92:95], v[128:131], v[200:203], v[92:95]
	v_mfma_f32_16x16x32_bf16 v[88:91], v[136:139], v[200:203], v[88:91]
	v_mfma_f32_16x16x32_bf16 v[76:79], v[128:131], v[208:211], v[76:79]
	v_mfma_f32_16x16x32_bf16 v[72:75], v[136:139], v[208:211], v[72:75]
	v_mfma_f32_16x16x32_bf16 v[124:127], v[132:135], v[186:189], v[124:127]
	v_mfma_f32_16x16x32_bf16 v[120:123], v[140:143], v[186:189], v[120:123]
	v_mfma_f32_16x16x32_bf16 v[108:111], v[132:135], v[196:199], v[108:111]
	v_mfma_f32_16x16x32_bf16 v[104:107], v[140:143], v[196:199], v[104:107]
	v_mfma_f32_16x16x32_bf16 v[92:95], v[132:135], v[204:207], v[92:95]
	v_mfma_f32_16x16x32_bf16 v[88:91], v[140:143], v[204:207], v[88:91]
	v_mfma_f32_16x16x32_bf16 v[76:79], v[132:135], v[212:215], v[76:79]
	v_mfma_f32_16x16x32_bf16 v[72:75], v[140:143], v[212:215], v[72:75]
	s_setprio 0
	s_setprio 1
	v_mfma_f32_16x16x32_bf16 v[116:119], v[156:159], v[182:185], v[116:119]
	v_mfma_f32_16x16x32_bf16 v[112:115], v[164:167], v[182:185], v[112:115]
	v_mfma_f32_16x16x32_bf16 v[100:103], v[156:159], v[192:195], v[100:103]
	v_mfma_f32_16x16x32_bf16 v[96:99], v[164:167], v[192:195], v[96:99]
	v_mfma_f32_16x16x32_bf16 v[84:87], v[156:159], v[200:203], v[84:87]
	v_mfma_f32_16x16x32_bf16 v[80:83], v[164:167], v[200:203], v[80:83]
	v_mfma_f32_16x16x32_bf16 v[68:71], v[156:159], v[208:211], v[68:71]
	v_mfma_f32_16x16x32_bf16 v[64:67], v[164:167], v[208:211], v[64:67]
	v_mfma_f32_16x16x32_bf16 v[116:119], v[160:163], v[186:189], v[116:119]
	v_mfma_f32_16x16x32_bf16 v[112:115], v[178:181], v[186:189], v[112:115]
	v_mfma_f32_16x16x32_bf16 v[100:103], v[160:163], v[196:199], v[100:103]
	v_mfma_f32_16x16x32_bf16 v[96:99], v[178:181], v[196:199], v[96:99]
	v_mfma_f32_16x16x32_bf16 v[84:87], v[160:163], v[204:207], v[84:87]
	v_mfma_f32_16x16x32_bf16 v[80:83], v[178:181], v[204:207], v[80:83]
	v_mfma_f32_16x16x32_bf16 v[68:71], v[160:163], v[212:215], v[68:71]
	v_mfma_f32_16x16x32_bf16 v[64:67], v[178:181], v[212:215], v[64:67]
	s_setprio 0
	s_barrier
	s_add_i32 s54, s79, s66
	v_lshl_add_u64 v[168:169], s[58:59], 0, v[144:145]
	s_mov_b32 m0, s54
	ds_read_b128 v[182:185], v175 offset:16384
	ds_read_b128 v[186:189], v175 offset:17408
	ds_read_b128 v[192:195], v175 offset:18432
	ds_read_b128 v[196:199], v175 offset:19456
	ds_read_b128 v[200:203], v175 offset:20480
	ds_read_b128 v[204:207], v175 offset:21504
	ds_read_b128 v[208:211], v175 offset:22528
	ds_read_b128 v[212:215], v175 offset:23552
	global_load_lds_dwordx4 v[168:169], off
	s_add_i32 m0, s54, 0x2000
	s_add_u32 s54, s58, 0xb0000
	v_lshl_add_u64 v[216:217], s[58:59], 0, v[146:147]
	s_addc_u32 s55, s59, 0
	s_add_i32 s87, s80, s66
	global_load_lds_dwordx4 v[216:217], off
	v_lshl_add_u64 v[218:219], s[54:55], 0, v[144:145]
	s_mov_b32 m0, s87
	v_lshl_add_u64 v[220:221], s[60:61], 0, v[146:147]
	global_load_lds_dwordx4 v[218:219], off
	v_lshl_add_u64 v[218:219], s[54:55], 0, v[146:147]
	s_add_i32 m0, s87, 0x2000
	s_nop 0
	global_load_lds_dwordx4 v[218:219], off
	v_lshl_add_u64 v[218:219], s[60:61], 0, v[144:145]
	s_mov_b32 m0, s67
	s_nop 0
	global_load_lds_dwordx4 v[218:219], off
	s_mov_b32 m0, s68
	s_nop 0
	global_load_lds_dwordx4 v[220:221], off
	s_waitcnt vmcnt(8)
	s_waitcnt lgkmcnt(0)
	s_barrier
	s_setprio 1
	s_waitcnt lgkmcnt(0)
	v_mfma_f32_16x16x32_bf16 v[60:63], v[128:131], v[182:185], v[60:63]
	v_mfma_f32_16x16x32_bf16 v[56:59], v[136:139], v[182:185], v[56:59]
	v_mfma_f32_16x16x32_bf16 v[44:47], v[128:131], v[192:195], v[44:47]
	v_mfma_f32_16x16x32_bf16 v[40:43], v[136:139], v[192:195], v[40:43]
	v_mfma_f32_16x16x32_bf16 v[28:31], v[128:131], v[200:203], v[28:31]
	v_mfma_f32_16x16x32_bf16 v[24:27], v[136:139], v[200:203], v[24:27]
	v_mfma_f32_16x16x32_bf16 v[12:15], v[128:131], v[208:211], v[12:15]
	v_mfma_f32_16x16x32_bf16 v[8:11], v[136:139], v[208:211], v[8:11]
	v_mfma_f32_16x16x32_bf16 v[60:63], v[132:135], v[186:189], v[60:63]
	v_mfma_f32_16x16x32_bf16 v[56:59], v[140:143], v[186:189], v[56:59]
	v_mfma_f32_16x16x32_bf16 v[44:47], v[132:135], v[196:199], v[44:47]
	v_mfma_f32_16x16x32_bf16 v[40:43], v[140:143], v[196:199], v[40:43]
	v_mfma_f32_16x16x32_bf16 v[28:31], v[132:135], v[204:207], v[28:31]
	v_mfma_f32_16x16x32_bf16 v[24:27], v[140:143], v[204:207], v[24:27]
	v_mfma_f32_16x16x32_bf16 v[12:15], v[132:135], v[212:215], v[12:15]
	v_mfma_f32_16x16x32_bf16 v[8:11], v[140:143], v[212:215], v[8:11]
	s_setprio 0
	s_setprio 1
	v_mfma_f32_16x16x32_bf16 v[52:55], v[156:159], v[182:185], v[52:55]
	v_mfma_f32_16x16x32_bf16 v[48:51], v[164:167], v[182:185], v[48:51]
	v_mfma_f32_16x16x32_bf16 v[36:39], v[156:159], v[192:195], v[36:39]
	v_mfma_f32_16x16x32_bf16 v[32:35], v[164:167], v[192:195], v[32:35]
	v_mfma_f32_16x16x32_bf16 v[20:23], v[156:159], v[200:203], v[20:23]
	v_mfma_f32_16x16x32_bf16 v[16:19], v[164:167], v[200:203], v[16:19]
	v_mfma_f32_16x16x32_bf16 v[4:7], v[156:159], v[208:211], v[4:7]
	v_mfma_f32_16x16x32_bf16 v[0:3], v[164:167], v[208:211], v[0:3]
	v_mfma_f32_16x16x32_bf16 v[52:55], v[160:163], v[186:189], v[52:55]
	v_mfma_f32_16x16x32_bf16 v[48:51], v[178:181], v[186:189], v[48:51]
	v_mfma_f32_16x16x32_bf16 v[36:39], v[160:163], v[196:199], v[36:39]
	v_mfma_f32_16x16x32_bf16 v[32:35], v[178:181], v[196:199], v[32:35]
	v_mfma_f32_16x16x32_bf16 v[20:23], v[160:163], v[204:207], v[20:23]
	v_mfma_f32_16x16x32_bf16 v[16:19], v[178:181], v[204:207], v[16:19]
	v_mfma_f32_16x16x32_bf16 v[4:7], v[160:163], v[212:215], v[4:7]
	v_mfma_f32_16x16x32_bf16 v[0:3], v[178:181], v[212:215], v[0:3]
	s_setprio 0
	s_barrier
	s_add_i32 s87, 0, 0x18000
	s_add_i32 s88, 0, 0x1c000
	v_add_u32_e32 v140, s87, v171
	v_add_u32_e32 v177, s88, v171
	ds_read_b128 v[128:131], v140
	ds_read_b128 v[132:135], v140 offset:1024
	ds_read_b128 v[136:139], v140 offset:2048
	ds_read_b128 v[140:143], v140 offset:3072
	ds_read_b128 v[156:159], v177
	ds_read_b128 v[160:163], v177 offset:1024
	ds_read_b128 v[164:167], v177 offset:2048
	ds_read_b128 v[178:181], v177 offset:3072
	s_add_u32 s54, s60, 0xb0000
	s_addc_u32 s55, s61, 0
	s_mov_b32 m0, s69
	v_lshl_add_u64 v[222:223], s[54:55], 0, v[144:145]
	ds_read_b128 v[182:185], v175 offset:32768
	ds_read_b128 v[186:189], v175 offset:33792
	ds_read_b128 v[192:195], v175 offset:34816
	ds_read_b128 v[196:199], v175 offset:35840
	ds_read_b128 v[200:203], v175 offset:36864
	ds_read_b128 v[204:207], v175 offset:37888
	ds_read_b128 v[208:211], v175 offset:38912
	ds_read_b128 v[212:215], v175 offset:39936
	global_load_lds_dwordx4 v[222:223], off
	v_lshl_add_u64 v[222:223], s[54:55], 0, v[146:147]
	s_mov_b32 m0, s70
	s_nop 0
	global_load_lds_dwordx4 v[222:223], off
	s_waitcnt vmcnt(8)
	s_waitcnt lgkmcnt(0)
	s_barrier
	s_setprio 1
	s_waitcnt lgkmcnt(0)
	v_mfma_f32_16x16x32_bf16 v[124:127], v[128:131], v[182:185], v[124:127]
	v_mfma_f32_16x16x32_bf16 v[120:123], v[136:139], v[182:185], v[120:123]
	v_mfma_f32_16x16x32_bf16 v[108:111], v[128:131], v[192:195], v[108:111]
	v_mfma_f32_16x16x32_bf16 v[104:107], v[136:139], v[192:195], v[104:107]
	v_mfma_f32_16x16x32_bf16 v[92:95], v[128:131], v[200:203], v[92:95]
	v_mfma_f32_16x16x32_bf16 v[88:91], v[136:139], v[200:203], v[88:91]
	v_mfma_f32_16x16x32_bf16 v[76:79], v[128:131], v[208:211], v[76:79]
	v_mfma_f32_16x16x32_bf16 v[72:75], v[136:139], v[208:211], v[72:75]
	v_mfma_f32_16x16x32_bf16 v[124:127], v[132:135], v[186:189], v[124:127]
	v_mfma_f32_16x16x32_bf16 v[120:123], v[140:143], v[186:189], v[120:123]
	v_mfma_f32_16x16x32_bf16 v[108:111], v[132:135], v[196:199], v[108:111]
	v_mfma_f32_16x16x32_bf16 v[104:107], v[140:143], v[196:199], v[104:107]
	v_mfma_f32_16x16x32_bf16 v[92:95], v[132:135], v[204:207], v[92:95]
	v_mfma_f32_16x16x32_bf16 v[88:91], v[140:143], v[204:207], v[88:91]
	v_mfma_f32_16x16x32_bf16 v[76:79], v[132:135], v[212:215], v[76:79]
	v_mfma_f32_16x16x32_bf16 v[72:75], v[140:143], v[212:215], v[72:75]
	s_setprio 0
	s_setprio 1
	v_mfma_f32_16x16x32_bf16 v[116:119], v[156:159], v[182:185], v[116:119]
	v_mfma_f32_16x16x32_bf16 v[112:115], v[164:167], v[182:185], v[112:115]
	v_mfma_f32_16x16x32_bf16 v[100:103], v[156:159], v[192:195], v[100:103]
	v_mfma_f32_16x16x32_bf16 v[96:99], v[164:167], v[192:195], v[96:99]
	v_mfma_f32_16x16x32_bf16 v[84:87], v[156:159], v[200:203], v[84:87]
	v_mfma_f32_16x16x32_bf16 v[80:83], v[164:167], v[200:203], v[80:83]
	v_mfma_f32_16x16x32_bf16 v[68:71], v[156:159], v[208:211], v[68:71]
	v_mfma_f32_16x16x32_bf16 v[64:67], v[164:167], v[208:211], v[64:67]
	v_mfma_f32_16x16x32_bf16 v[116:119], v[160:163], v[186:189], v[116:119]
	v_mfma_f32_16x16x32_bf16 v[112:115], v[178:181], v[186:189], v[112:115]
	v_mfma_f32_16x16x32_bf16 v[100:103], v[160:163], v[196:199], v[100:103]
	v_mfma_f32_16x16x32_bf16 v[96:99], v[178:181], v[196:199], v[96:99]
	v_mfma_f32_16x16x32_bf16 v[84:87], v[160:163], v[204:207], v[84:87]
	v_mfma_f32_16x16x32_bf16 v[80:83], v[178:181], v[204:207], v[80:83]
	v_mfma_f32_16x16x32_bf16 v[68:71], v[160:163], v[212:215], v[68:71]
	v_mfma_f32_16x16x32_bf16 v[64:67], v[178:181], v[212:215], v[64:67]
	s_setprio 0
	s_barrier
	s_add_i32 s54, s87, s66
	v_lshl_add_u64 v[168:169], v[168:169], 0, s[30:31]
	s_mov_b32 m0, s54
	ds_read_b128 v[182:185], v175 offset:49152
	ds_read_b128 v[186:189], v175 offset:50176
	ds_read_b128 v[192:195], v175 offset:51200
	ds_read_b128 v[196:199], v175 offset:52224
	ds_read_b128 v[200:203], v175 offset:53248
	ds_read_b128 v[204:207], v175 offset:54272
	ds_read_b128 v[208:211], v175 offset:55296
	ds_read_b128 v[212:215], v175 offset:56320
	global_load_lds_dwordx4 v[168:169], off
	s_add_i32 m0, s54, 0x2000
	s_add_u32 s54, s58, 0xb0080
	v_lshl_add_u64 v[168:169], v[216:217], 0, s[30:31]
	s_addc_u32 s55, s59, 0
	s_add_i32 s58, s88, s66
	global_load_lds_dwordx4 v[168:169], off
	v_lshl_add_u64 v[168:169], s[54:55], 0, v[144:145]
	s_mov_b32 m0, s58
	s_nop 0
	global_load_lds_dwordx4 v[168:169], off
	v_lshl_add_u64 v[168:169], s[54:55], 0, v[146:147]
	s_add_i32 m0, s58, 0x2000
	s_nop 0
	global_load_lds_dwordx4 v[168:169], off
	v_lshl_add_u64 v[168:169], v[218:219], 0, s[30:31]
	s_mov_b32 m0, s72
	s_nop 0
	global_load_lds_dwordx4 v[168:169], off
	v_lshl_add_u64 v[168:169], v[220:221], 0, s[30:31]
	s_mov_b32 m0, s73
	s_nop 0
	global_load_lds_dwordx4 v[168:169], off
	s_waitcnt vmcnt(8)
	s_waitcnt lgkmcnt(0)
	s_barrier
	s_setprio 1
	s_waitcnt lgkmcnt(0)
	v_mfma_f32_16x16x32_bf16 v[60:63], v[128:131], v[182:185], v[60:63]
	v_mfma_f32_16x16x32_bf16 v[56:59], v[136:139], v[182:185], v[56:59]
	v_mfma_f32_16x16x32_bf16 v[44:47], v[128:131], v[192:195], v[44:47]
	v_mfma_f32_16x16x32_bf16 v[40:43], v[136:139], v[192:195], v[40:43]
	v_mfma_f32_16x16x32_bf16 v[28:31], v[128:131], v[200:203], v[28:31]
	v_mfma_f32_16x16x32_bf16 v[24:27], v[136:139], v[200:203], v[24:27]
	v_mfma_f32_16x16x32_bf16 v[12:15], v[128:131], v[208:211], v[12:15]
	v_mfma_f32_16x16x32_bf16 v[8:11], v[136:139], v[208:211], v[8:11]
	v_mfma_f32_16x16x32_bf16 v[60:63], v[132:135], v[186:189], v[60:63]
	v_mfma_f32_16x16x32_bf16 v[56:59], v[140:143], v[186:189], v[56:59]
	v_mfma_f32_16x16x32_bf16 v[44:47], v[132:135], v[196:199], v[44:47]
	v_mfma_f32_16x16x32_bf16 v[40:43], v[140:143], v[196:199], v[40:43]
	v_mfma_f32_16x16x32_bf16 v[28:31], v[132:135], v[204:207], v[28:31]
	v_mfma_f32_16x16x32_bf16 v[24:27], v[140:143], v[204:207], v[24:27]
	v_mfma_f32_16x16x32_bf16 v[12:15], v[132:135], v[212:215], v[12:15]
	v_mfma_f32_16x16x32_bf16 v[8:11], v[140:143], v[212:215], v[8:11]
	s_setprio 0
	s_setprio 1
	v_mfma_f32_16x16x32_bf16 v[52:55], v[156:159], v[182:185], v[52:55]
	v_mfma_f32_16x16x32_bf16 v[48:51], v[164:167], v[182:185], v[48:51]
	v_mfma_f32_16x16x32_bf16 v[36:39], v[156:159], v[192:195], v[36:39]
	v_mfma_f32_16x16x32_bf16 v[32:35], v[164:167], v[192:195], v[32:35]
	v_mfma_f32_16x16x32_bf16 v[20:23], v[156:159], v[200:203], v[20:23]
	v_mfma_f32_16x16x32_bf16 v[16:19], v[164:167], v[200:203], v[16:19]
	v_mfma_f32_16x16x32_bf16 v[4:7], v[156:159], v[208:211], v[4:7]
	v_mfma_f32_16x16x32_bf16 v[0:3], v[164:167], v[208:211], v[0:3]
	v_mfma_f32_16x16x32_bf16 v[52:55], v[160:163], v[186:189], v[52:55]
	v_mfma_f32_16x16x32_bf16 v[48:51], v[178:181], v[186:189], v[48:51]
	v_mfma_f32_16x16x32_bf16 v[36:39], v[160:163], v[196:199], v[36:39]
	v_mfma_f32_16x16x32_bf16 v[32:35], v[178:181], v[196:199], v[32:35]
	v_mfma_f32_16x16x32_bf16 v[20:23], v[160:163], v[204:207], v[20:23]
	v_mfma_f32_16x16x32_bf16 v[16:19], v[178:181], v[204:207], v[16:19]
	v_mfma_f32_16x16x32_bf16 v[4:7], v[160:163], v[212:215], v[4:7]
	v_mfma_f32_16x16x32_bf16 v[0:3], v[178:181], v[212:215], v[0:3]
	s_setprio 0
	s_add_i32 s86, s86, 2
	s_add_u32 s84, s84, 0x100
	s_addc_u32 s85, s85, 0
	s_cmp_gt_u32 s86, 41
	s_mov_b64 s[54:55], s[56:57]
	s_barrier
	s_cbranch_scc0 .LBB0_250
	v_mbcnt_lo_u32_b32 v235, -1, 0
	v_mbcnt_hi_u32_b32 v235, -1, v235
	v_lshrrev_b32_e32 v236, 2, v235
	v_and_b32_e32 v237, 3, v235
	v_lshl_add_u32 v232, v237, 4, v236
	v_lshlrev_b32_e32 v232, 2, v232
	v_and_b32_e32 v233, -16, v170
	v_or_b32_e32 v233, v233, v236
	v_lshlrev_b32_e32 v237, 2, v237
	v_and_b32_e32 v234, -13, v172
	v_or_b32_e32 v234, v234, v237
	v_readlane_b32 s12, v254, 0
	v_lshl_add_u32 v160, s82, 8, v233
	v_lshl_or_b32 v156, s83, 8, v234
	s_cmpk_lt_i32 s82, 0x100
	v_readlane_b32 s13, v254, 1
	v_ashrrev_i32_e32 v161, 31, v160
	s_cselect_b32 s55, s13, s78
	s_cselect_b32 s54, s12, s77
	v_lshlrev_b64 v[192:193], 12, v[160:161]
	v_ashrrev_i32_e32 v157, 31, v156
	v_lshl_add_u64 v[128:129], s[54:55], 0, v[192:193]
	v_lshlrev_b64 v[158:159], 2, v[156:157]
	v_lshl_add_u64 v[128:129], v[128:129], 0, v[158:159]
	global_load_dwordx4 v[166:169], v[128:129], off
	global_load_dwordx4 v[178:181], v[128:129], off offset:64
	global_load_dwordx4 v[182:185], v[128:129], off offset:512
	global_load_dwordx4 v[186:189], v[128:129], off offset:576
	v_or_b32_e32 v162, 16, v160
	v_ashrrev_i32_e32 v163, 31, v162
	v_lshlrev_b64 v[164:165], 12, v[162:163]
	v_lshl_add_u64 v[128:129], s[54:55], 0, v[164:165]
	v_lshl_add_u64 v[128:129], v[128:129], 0, v[158:159]
	global_load_dwordx4 v[140:143], v[128:129], off
	global_load_dwordx4 v[136:139], v[128:129], off offset:64
	global_load_dwordx4 v[132:135], v[128:129], off offset:512
	s_nop 0
	global_load_dwordx4 v[128:131], v[128:129], off offset:576
	v_readlane_b32 s14, v254, 2
	v_readlane_b32 s15, v254, 3
	v_readlane_b32 s16, v254, 4
	v_readlane_b32 s17, v254, 5
	v_readlane_b32 s18, v254, 6
	v_readlane_b32 s19, v254, 7
	v_readlane_b32 s20, v254, 8
	v_readlane_b32 s21, v254, 9
	v_readlane_b32 s22, v254, 10
	v_readlane_b32 s23, v254, 11
	v_readlane_b32 s24, v254, 12
	v_readlane_b32 s25, v254, 13
	v_readlane_b32 s26, v254, 14
	v_readlane_b32 s27, v254, 15
	ds_bpermute_b32 v127, v232, v127
	ds_bpermute_b32 v126, v232, v126
	ds_bpermute_b32 v125, v232, v125
	ds_bpermute_b32 v124, v232, v124
	ds_bpermute_b32 v123, v232, v123
	ds_bpermute_b32 v122, v232, v122
	ds_bpermute_b32 v121, v232, v121
	ds_bpermute_b32 v120, v232, v120
	ds_bpermute_b32 v119, v232, v119
	ds_bpermute_b32 v118, v232, v118
	ds_bpermute_b32 v117, v232, v117
	ds_bpermute_b32 v116, v232, v116
	ds_bpermute_b32 v115, v232, v115
	ds_bpermute_b32 v114, v232, v114
	ds_bpermute_b32 v113, v232, v113
	ds_bpermute_b32 v112, v232, v112
	ds_bpermute_b32 v111, v232, v111
	ds_bpermute_b32 v110, v232, v110
	ds_bpermute_b32 v109, v232, v109
	ds_bpermute_b32 v108, v232, v108
	ds_bpermute_b32 v107, v232, v107
	ds_bpermute_b32 v106, v232, v106
	ds_bpermute_b32 v105, v232, v105
	ds_bpermute_b32 v104, v232, v104
	ds_bpermute_b32 v103, v232, v103
	ds_bpermute_b32 v102, v232, v102
	ds_bpermute_b32 v101, v232, v101
	ds_bpermute_b32 v100, v232, v100
	ds_bpermute_b32 v99, v232, v99
	ds_bpermute_b32 v98, v232, v98
	ds_bpermute_b32 v97, v232, v97
	ds_bpermute_b32 v96, v232, v96
	ds_bpermute_b32 v95, v232, v95
	ds_bpermute_b32 v94, v232, v94
	ds_bpermute_b32 v93, v232, v93
	ds_bpermute_b32 v92, v232, v92
	ds_bpermute_b32 v91, v232, v91
	ds_bpermute_b32 v90, v232, v90
	ds_bpermute_b32 v89, v232, v89
	ds_bpermute_b32 v88, v232, v88
	ds_bpermute_b32 v87, v232, v87
	ds_bpermute_b32 v86, v232, v86
	ds_bpermute_b32 v85, v232, v85
	ds_bpermute_b32 v84, v232, v84
	ds_bpermute_b32 v83, v232, v83
	ds_bpermute_b32 v82, v232, v82
	ds_bpermute_b32 v81, v232, v81
	ds_bpermute_b32 v80, v232, v80
	ds_bpermute_b32 v79, v232, v79
	ds_bpermute_b32 v78, v232, v78
	ds_bpermute_b32 v77, v232, v77
	ds_bpermute_b32 v76, v232, v76
	ds_bpermute_b32 v75, v232, v75
	ds_bpermute_b32 v74, v232, v74
	ds_bpermute_b32 v73, v232, v73
	ds_bpermute_b32 v72, v232, v72
	ds_bpermute_b32 v71, v232, v71
	ds_bpermute_b32 v70, v232, v70
	ds_bpermute_b32 v69, v232, v69
	ds_bpermute_b32 v68, v232, v68
	ds_bpermute_b32 v67, v232, v67
	ds_bpermute_b32 v66, v232, v66
	ds_bpermute_b32 v65, v232, v65
	ds_bpermute_b32 v64, v232, v64
	ds_bpermute_b32 v63, v232, v63
	ds_bpermute_b32 v62, v232, v62
	ds_bpermute_b32 v61, v232, v61
	ds_bpermute_b32 v60, v232, v60
	ds_bpermute_b32 v59, v232, v59
	ds_bpermute_b32 v58, v232, v58
	ds_bpermute_b32 v57, v232, v57
	ds_bpermute_b32 v56, v232, v56
	ds_bpermute_b32 v55, v232, v55
	ds_bpermute_b32 v54, v232, v54
	ds_bpermute_b32 v53, v232, v53
	ds_bpermute_b32 v52, v232, v52
	ds_bpermute_b32 v51, v232, v51
	ds_bpermute_b32 v50, v232, v50
	ds_bpermute_b32 v49, v232, v49
	ds_bpermute_b32 v48, v232, v48
	ds_bpermute_b32 v47, v232, v47
	ds_bpermute_b32 v46, v232, v46
	ds_bpermute_b32 v45, v232, v45
	ds_bpermute_b32 v44, v232, v44
	ds_bpermute_b32 v43, v232, v43
	ds_bpermute_b32 v42, v232, v42
	ds_bpermute_b32 v41, v232, v41
	ds_bpermute_b32 v40, v232, v40
	ds_bpermute_b32 v39, v232, v39
	ds_bpermute_b32 v38, v232, v38
	ds_bpermute_b32 v37, v232, v37
	ds_bpermute_b32 v36, v232, v36
	ds_bpermute_b32 v35, v232, v35
	ds_bpermute_b32 v34, v232, v34
	ds_bpermute_b32 v33, v232, v33
	ds_bpermute_b32 v32, v232, v32
	ds_bpermute_b32 v31, v232, v31
	ds_bpermute_b32 v30, v232, v30
	ds_bpermute_b32 v29, v232, v29
	ds_bpermute_b32 v28, v232, v28
	ds_bpermute_b32 v27, v232, v27
	ds_bpermute_b32 v26, v232, v26
	ds_bpermute_b32 v25, v232, v25
	ds_bpermute_b32 v24, v232, v24
	ds_bpermute_b32 v23, v232, v23
	ds_bpermute_b32 v22, v232, v22
	ds_bpermute_b32 v21, v232, v21
	ds_bpermute_b32 v20, v232, v20
	ds_bpermute_b32 v19, v232, v19
	ds_bpermute_b32 v18, v232, v18
	ds_bpermute_b32 v17, v232, v17
	ds_bpermute_b32 v16, v232, v16
	ds_bpermute_b32 v15, v232, v15
	ds_bpermute_b32 v14, v232, v14
	ds_bpermute_b32 v13, v232, v13
	ds_bpermute_b32 v12, v232, v12
	ds_bpermute_b32 v11, v232, v11
	ds_bpermute_b32 v10, v232, v10
	ds_bpermute_b32 v9, v232, v9
	ds_bpermute_b32 v8, v232, v8
	ds_bpermute_b32 v7, v232, v7
	ds_bpermute_b32 v6, v232, v6
	ds_bpermute_b32 v5, v232, v5
	ds_bpermute_b32 v4, v232, v4
	ds_bpermute_b32 v3, v232, v3
	ds_bpermute_b32 v2, v232, v2
	ds_bpermute_b32 v1, v232, v1
	ds_bpermute_b32 v0, v232, v0
	s_waitcnt lgkmcnt(0)
	s_and_b64 vcc, exec, s[34:35]
	s_cbranch_vccz .LBB0_253
	s_barrier

.LBB0_571:
	ds_read_b128 v[150:153], v163
	ds_read_b128 v[154:157], v163 offset:1024
	ds_read_b128 v[158:161], v163 offset:2048
	ds_read_b128 v[168:171], v163 offset:3072
	ds_read_b128 v[172:175], v164
	ds_read_b128 v[176:179], v164 offset:1024
	ds_read_b128 v[180:183], v164 offset:2048
	ds_read_b128 v[184:187], v164 offset:3072
	s_add_u32 s8, s6, 0xfffc0080
	s_addc_u32 s9, s7, -1
	s_cmp_eq_u32 s65, 12
	s_cselect_b32 s11, s3, s9
	s_cselect_b32 s10, s5, s8
	s_cselect_b32 s9, s20, s64
	s_cselect_b32 s8, s57, s59
	v_lshl_add_u64 v[188:189], s[6:7], 0, v[144:145]
	s_add_i32 m0, s73, 0xc000
	ds_read_b128 v[192:195], v165
	ds_read_b128 v[196:199], v165 offset:1024
	ds_read_b128 v[200:203], v165 offset:2048
	ds_read_b128 v[204:207], v165 offset:3072
	ds_read_b128 v[208:211], v165 offset:4096
	ds_read_b128 v[212:215], v165 offset:5120
	ds_read_b128 v[216:219], v165 offset:6144
	ds_read_b128 v[220:223], v165 offset:7168
	global_load_lds_dwordx4 v[188:189], off
	v_lshl_add_u64 v[188:189], s[6:7], 0, v[142:143]
	s_add_i32 m0, s73, 0xe000
	s_nop 0
	global_load_lds_dwordx4 v[188:189], off
	s_waitcnt vmcnt(8)
	s_waitcnt lgkmcnt(0)
	s_barrier
	s_setprio 1
	s_waitcnt lgkmcnt(0)
	v_mfma_f32_16x16x32_bf16 v[124:127], v[150:153], v[192:195], v[124:127]
	v_mfma_f32_16x16x32_bf16 v[120:123], v[158:161], v[192:195], v[120:123]
	v_mfma_f32_16x16x32_bf16 v[108:111], v[150:153], v[200:203], v[108:111]
	v_mfma_f32_16x16x32_bf16 v[104:107], v[158:161], v[200:203], v[104:107]
	v_mfma_f32_16x16x32_bf16 v[92:95], v[150:153], v[208:211], v[92:95]
	v_mfma_f32_16x16x32_bf16 v[88:91], v[158:161], v[208:211], v[88:91]
	v_mfma_f32_16x16x32_bf16 v[76:79], v[150:153], v[216:219], v[76:79]
	v_mfma_f32_16x16x32_bf16 v[72:75], v[158:161], v[216:219], v[72:75]
	v_mfma_f32_16x16x32_bf16 v[124:127], v[154:157], v[196:199], v[124:127]
	v_mfma_f32_16x16x32_bf16 v[120:123], v[168:171], v[196:199], v[120:123]
	v_mfma_f32_16x16x32_bf16 v[108:111], v[154:157], v[204:207], v[108:111]
	v_mfma_f32_16x16x32_bf16 v[104:107], v[168:171], v[204:207], v[104:107]
	v_mfma_f32_16x16x32_bf16 v[92:95], v[154:157], v[212:215], v[92:95]
	v_mfma_f32_16x16x32_bf16 v[88:91], v[168:171], v[212:215], v[88:91]
	v_mfma_f32_16x16x32_bf16 v[76:79], v[154:157], v[220:223], v[76:79]
	v_mfma_f32_16x16x32_bf16 v[72:75], v[168:171], v[220:223], v[72:75]
	s_setprio 0
	s_setprio 1
	v_mfma_f32_16x16x32_bf16 v[116:119], v[172:175], v[192:195], v[116:119]
	v_mfma_f32_16x16x32_bf16 v[112:115], v[180:183], v[192:195], v[112:115]
	v_mfma_f32_16x16x32_bf16 v[100:103], v[172:175], v[200:203], v[100:103]
	v_mfma_f32_16x16x32_bf16 v[96:99], v[180:183], v[200:203], v[96:99]
	v_mfma_f32_16x16x32_bf16 v[84:87], v[172:175], v[208:211], v[84:87]
	v_mfma_f32_16x16x32_bf16 v[80:83], v[180:183], v[208:211], v[80:83]
	v_mfma_f32_16x16x32_bf16 v[68:71], v[172:175], v[216:219], v[68:71]
	v_mfma_f32_16x16x32_bf16 v[64:67], v[180:183], v[216:219], v[64:67]
	v_mfma_f32_16x16x32_bf16 v[116:119], v[176:179], v[196:199], v[116:119]
	v_mfma_f32_16x16x32_bf16 v[112:115], v[184:187], v[196:199], v[112:115]
	v_mfma_f32_16x16x32_bf16 v[100:103], v[176:179], v[204:207], v[100:103]
	v_mfma_f32_16x16x32_bf16 v[96:99], v[184:187], v[204:207], v[96:99]
	v_mfma_f32_16x16x32_bf16 v[84:87], v[176:179], v[212:215], v[84:87]
	v_mfma_f32_16x16x32_bf16 v[80:83], v[184:187], v[212:215], v[80:83]
	v_mfma_f32_16x16x32_bf16 v[68:71], v[176:179], v[220:223], v[68:71]
	v_mfma_f32_16x16x32_bf16 v[64:67], v[184:187], v[220:223], v[64:67]
	s_setprio 0
	s_barrier
	s_add_i32 s66, s82, s72
	v_lshl_add_u64 v[188:189], s[8:9], 0, v[130:131]
	s_mov_b32 m0, s66
	ds_read_b128 v[192:195], v165 offset:16384
	ds_read_b128 v[196:199], v165 offset:17408
	ds_read_b128 v[200:203], v165 offset:18432
	ds_read_b128 v[204:207], v165 offset:19456
	ds_read_b128 v[208:211], v165 offset:20480
	ds_read_b128 v[212:215], v165 offset:21504
	ds_read_b128 v[216:219], v165 offset:22528
	ds_read_b128 v[220:223], v165 offset:23552
	global_load_lds_dwordx4 v[188:189], off
	s_add_i32 m0, s66, 0x2000
	s_add_u32 s66, s8, 0x40000
	v_lshl_add_u64 v[224:225], s[8:9], 0, v[134:135]
	s_addc_u32 s67, s9, 0
	s_add_i32 s86, s83, s72
	global_load_lds_dwordx4 v[224:225], off
	v_lshl_add_u64 v[226:227], s[66:67], 0, v[130:131]
	s_mov_b32 m0, s86
	v_lshl_add_u64 v[228:229], s[10:11], 0, v[132:133]
	global_load_lds_dwordx4 v[226:227], off
	v_lshl_add_u64 v[226:227], s[66:67], 0, v[134:135]
	s_add_i32 m0, s86, 0x2000
	s_nop 0
	global_load_lds_dwordx4 v[226:227], off
	v_lshl_add_u64 v[226:227], s[10:11], 0, v[128:129]
	s_mov_b32 m0, s73
	s_nop 0
	global_load_lds_dwordx4 v[226:227], off
	s_mov_b32 m0, s74
	s_nop 0
	global_load_lds_dwordx4 v[228:229], off
	s_waitcnt vmcnt(8)
	s_waitcnt lgkmcnt(0)
	s_barrier
	s_setprio 1
	s_waitcnt lgkmcnt(0)
	v_mfma_f32_16x16x32_bf16 v[60:63], v[150:153], v[192:195], v[60:63]
	v_mfma_f32_16x16x32_bf16 v[56:59], v[158:161], v[192:195], v[56:59]
	v_mfma_f32_16x16x32_bf16 v[44:47], v[150:153], v[200:203], v[44:47]
	v_mfma_f32_16x16x32_bf16 v[40:43], v[158:161], v[200:203], v[40:43]
	v_mfma_f32_16x16x32_bf16 v[28:31], v[150:153], v[208:211], v[28:31]
	v_mfma_f32_16x16x32_bf16 v[24:27], v[158:161], v[208:211], v[24:27]
	v_mfma_f32_16x16x32_bf16 v[12:15], v[150:153], v[216:219], v[12:15]
	v_mfma_f32_16x16x32_bf16 v[8:11], v[158:161], v[216:219], v[8:11]
	v_mfma_f32_16x16x32_bf16 v[60:63], v[154:157], v[196:199], v[60:63]
	v_mfma_f32_16x16x32_bf16 v[56:59], v[168:171], v[196:199], v[56:59]
	v_mfma_f32_16x16x32_bf16 v[44:47], v[154:157], v[204:207], v[44:47]
	v_mfma_f32_16x16x32_bf16 v[40:43], v[168:171], v[204:207], v[40:43]
	v_mfma_f32_16x16x32_bf16 v[28:31], v[154:157], v[212:215], v[28:31]
	v_mfma_f32_16x16x32_bf16 v[24:27], v[168:171], v[212:215], v[24:27]
	v_mfma_f32_16x16x32_bf16 v[12:15], v[154:157], v[220:223], v[12:15]
	v_mfma_f32_16x16x32_bf16 v[8:11], v[168:171], v[220:223], v[8:11]
	s_setprio 0
	s_setprio 1
	v_mfma_f32_16x16x32_bf16 v[52:55], v[172:175], v[192:195], v[52:55]
	v_mfma_f32_16x16x32_bf16 v[48:51], v[180:183], v[192:195], v[48:51]
	v_mfma_f32_16x16x32_bf16 v[36:39], v[172:175], v[200:203], v[36:39]
	v_mfma_f32_16x16x32_bf16 v[32:35], v[180:183], v[200:203], v[32:35]
	v_mfma_f32_16x16x32_bf16 v[20:23], v[172:175], v[208:211], v[20:23]
	v_mfma_f32_16x16x32_bf16 v[16:19], v[180:183], v[208:211], v[16:19]
	v_mfma_f32_16x16x32_bf16 v[4:7], v[172:175], v[216:219], v[4:7]
	v_mfma_f32_16x16x32_bf16 v[0:3], v[180:183], v[216:219], v[0:3]
	v_mfma_f32_16x16x32_bf16 v[52:55], v[176:179], v[196:199], v[52:55]
	v_mfma_f32_16x16x32_bf16 v[48:51], v[184:187], v[196:199], v[48:51]
	v_mfma_f32_16x16x32_bf16 v[36:39], v[176:179], v[204:207], v[36:39]
	v_mfma_f32_16x16x32_bf16 v[32:35], v[184:187], v[204:207], v[32:35]
	v_mfma_f32_16x16x32_bf16 v[20:23], v[176:179], v[212:215], v[20:23]
	v_mfma_f32_16x16x32_bf16 v[16:19], v[184:187], v[212:215], v[16:19]
	v_mfma_f32_16x16x32_bf16 v[4:7], v[176:179], v[220:223], v[4:7]
	v_mfma_f32_16x16x32_bf16 v[0:3], v[184:187], v[220:223], v[0:3]
	s_setprio 0
	s_barrier
	s_add_i32 s66, 0, 0x18000
	v_add_u32_e32 v136, s66, v162
	s_add_i32 s67, 0, 0x1c000
	ds_read_b128 v[150:153], v136
	ds_read_b128 v[154:157], v136 offset:1024
	ds_read_b128 v[158:161], v136 offset:2048
	ds_read_b128 v[168:171], v136 offset:3072
	v_add_u32_e32 v136, s67, v162
	ds_read_b128 v[172:175], v136
	ds_read_b128 v[176:179], v136 offset:1024
	ds_read_b128 v[180:183], v136 offset:2048
	ds_read_b128 v[184:187], v136 offset:3072
	s_add_u32 s10, s10, 0x40000
	s_addc_u32 s11, s11, 0
	s_mov_b32 m0, s75
	v_lshl_add_u64 v[230:231], s[10:11], 0, v[128:129]
	ds_read_b128 v[192:195], v165 offset:32768
	ds_read_b128 v[196:199], v165 offset:33792
	ds_read_b128 v[200:203], v165 offset:34816
	ds_read_b128 v[204:207], v165 offset:35840
	ds_read_b128 v[208:211], v165 offset:36864
	ds_read_b128 v[212:215], v165 offset:37888
	ds_read_b128 v[216:219], v165 offset:38912
	ds_read_b128 v[220:223], v165 offset:39936
	global_load_lds_dwordx4 v[230:231], off
	v_lshl_add_u64 v[230:231], s[10:11], 0, v[132:133]
	s_mov_b32 m0, s76
	s_nop 0
	global_load_lds_dwordx4 v[230:231], off
	s_waitcnt vmcnt(8)
	s_waitcnt lgkmcnt(0)
	s_barrier
	s_setprio 1
	s_waitcnt lgkmcnt(0)
	v_mfma_f32_16x16x32_bf16 v[124:127], v[150:153], v[192:195], v[124:127]
	v_mfma_f32_16x16x32_bf16 v[120:123], v[158:161], v[192:195], v[120:123]
	v_mfma_f32_16x16x32_bf16 v[108:111], v[150:153], v[200:203], v[108:111]
	v_mfma_f32_16x16x32_bf16 v[104:107], v[158:161], v[200:203], v[104:107]
	v_mfma_f32_16x16x32_bf16 v[92:95], v[150:153], v[208:211], v[92:95]
	v_mfma_f32_16x16x32_bf16 v[88:91], v[158:161], v[208:211], v[88:91]
	v_mfma_f32_16x16x32_bf16 v[76:79], v[150:153], v[216:219], v[76:79]
	v_mfma_f32_16x16x32_bf16 v[72:75], v[158:161], v[216:219], v[72:75]
	v_mfma_f32_16x16x32_bf16 v[124:127], v[154:157], v[196:199], v[124:127]
	v_mfma_f32_16x16x32_bf16 v[120:123], v[168:171], v[196:199], v[120:123]
	v_mfma_f32_16x16x32_bf16 v[108:111], v[154:157], v[204:207], v[108:111]
	v_mfma_f32_16x16x32_bf16 v[104:107], v[168:171], v[204:207], v[104:107]
	v_mfma_f32_16x16x32_bf16 v[92:95], v[154:157], v[212:215], v[92:95]
	v_mfma_f32_16x16x32_bf16 v[88:91], v[168:171], v[212:215], v[88:91]
	v_mfma_f32_16x16x32_bf16 v[76:79], v[154:157], v[220:223], v[76:79]
	v_mfma_f32_16x16x32_bf16 v[72:75], v[168:171], v[220:223], v[72:75]
	s_setprio 0
	s_setprio 1
	v_mfma_f32_16x16x32_bf16 v[116:119], v[172:175], v[192:195], v[116:119]
	v_mfma_f32_16x16x32_bf16 v[112:115], v[180:183], v[192:195], v[112:115]
	v_mfma_f32_16x16x32_bf16 v[100:103], v[172:175], v[200:203], v[100:103]
	v_mfma_f32_16x16x32_bf16 v[96:99], v[180:183], v[200:203], v[96:99]
	v_mfma_f32_16x16x32_bf16 v[84:87], v[172:175], v[208:211], v[84:87]
	v_mfma_f32_16x16x32_bf16 v[80:83], v[180:183], v[208:211], v[80:83]
	v_mfma_f32_16x16x32_bf16 v[68:71], v[172:175], v[216:219], v[68:71]
	v_mfma_f32_16x16x32_bf16 v[64:67], v[180:183], v[216:219], v[64:67]
	v_mfma_f32_16x16x32_bf16 v[116:119], v[176:179], v[196:199], v[116:119]
	v_mfma_f32_16x16x32_bf16 v[112:115], v[184:187], v[196:199], v[112:115]
	v_mfma_f32_16x16x32_bf16 v[100:103], v[176:179], v[204:207], v[100:103]
	v_mfma_f32_16x16x32_bf16 v[96:99], v[184:187], v[204:207], v[96:99]
	v_mfma_f32_16x16x32_bf16 v[84:87], v[176:179], v[212:215], v[84:87]
	v_mfma_f32_16x16x32_bf16 v[80:83], v[184:187], v[212:215], v[80:83]
	v_mfma_f32_16x16x32_bf16 v[68:71], v[176:179], v[220:223], v[68:71]
	v_mfma_f32_16x16x32_bf16 v[64:67], v[184:187], v[220:223], v[64:67]
	s_setprio 0
	s_barrier
	s_add_i32 s10, s66, s72
	v_lshl_add_u64 v[188:189], v[188:189], 0, s[48:49]
	s_mov_b32 m0, s10
	ds_read_b128 v[192:195], v165 offset:49152
	ds_read_b128 v[196:199], v165 offset:50176
	ds_read_b128 v[200:203], v165 offset:51200
	ds_read_b128 v[204:207], v165 offset:52224
	ds_read_b128 v[208:211], v165 offset:53248
	ds_read_b128 v[212:215], v165 offset:54272
	ds_read_b128 v[216:219], v165 offset:55296
	ds_read_b128 v[220:223], v165 offset:56320
	global_load_lds_dwordx4 v[188:189], off
	s_add_i32 m0, s10, 0x2000
	s_add_u32 s8, s8, 0x40080
	v_lshl_add_u64 v[188:189], v[224:225], 0, s[48:49]
	s_addc_u32 s9, s9, 0
	s_add_i32 s10, s67, s72
	global_load_lds_dwordx4 v[188:189], off
	v_lshl_add_u64 v[188:189], s[8:9], 0, v[130:131]
	s_mov_b32 m0, s10
	s_nop 0
	global_load_lds_dwordx4 v[188:189], off
	v_lshl_add_u64 v[188:189], s[8:9], 0, v[134:135]
	s_add_i32 m0, s10, 0x2000
	s_nop 0
	global_load_lds_dwordx4 v[188:189], off
	v_lshl_add_u64 v[188:189], v[226:227], 0, s[48:49]
	s_mov_b32 m0, s77
	s_nop 0
	global_load_lds_dwordx4 v[188:189], off
	v_lshl_add_u64 v[188:189], v[228:229], 0, s[48:49]
	s_mov_b32 m0, s78
	s_nop 0
	global_load_lds_dwordx4 v[188:189], off
	s_waitcnt vmcnt(8)
	s_waitcnt lgkmcnt(0)
	s_barrier
	s_setprio 1
	s_waitcnt lgkmcnt(0)
	v_mfma_f32_16x16x32_bf16 v[60:63], v[150:153], v[192:195], v[60:63]
	v_mfma_f32_16x16x32_bf16 v[56:59], v[158:161], v[192:195], v[56:59]
	v_mfma_f32_16x16x32_bf16 v[44:47], v[150:153], v[200:203], v[44:47]
	v_mfma_f32_16x16x32_bf16 v[40:43], v[158:161], v[200:203], v[40:43]
	v_mfma_f32_16x16x32_bf16 v[28:31], v[150:153], v[208:211], v[28:31]
	v_mfma_f32_16x16x32_bf16 v[24:27], v[158:161], v[208:211], v[24:27]
	v_mfma_f32_16x16x32_bf16 v[12:15], v[150:153], v[216:219], v[12:15]
	v_mfma_f32_16x16x32_bf16 v[8:11], v[158:161], v[216:219], v[8:11]
	v_mfma_f32_16x16x32_bf16 v[60:63], v[154:157], v[196:199], v[60:63]
	v_mfma_f32_16x16x32_bf16 v[56:59], v[168:171], v[196:199], v[56:59]
	v_mfma_f32_16x16x32_bf16 v[44:47], v[154:157], v[204:207], v[44:47]
	v_mfma_f32_16x16x32_bf16 v[40:43], v[168:171], v[204:207], v[40:43]
	v_mfma_f32_16x16x32_bf16 v[28:31], v[154:157], v[212:215], v[28:31]
	v_mfma_f32_16x16x32_bf16 v[24:27], v[168:171], v[212:215], v[24:27]
	v_mfma_f32_16x16x32_bf16 v[12:15], v[154:157], v[220:223], v[12:15]
	v_mfma_f32_16x16x32_bf16 v[8:11], v[168:171], v[220:223], v[8:11]
	s_setprio 0
	s_setprio 1
	v_mfma_f32_16x16x32_bf16 v[52:55], v[172:175], v[192:195], v[52:55]
	v_mfma_f32_16x16x32_bf16 v[48:51], v[180:183], v[192:195], v[48:51]
	v_mfma_f32_16x16x32_bf16 v[36:39], v[172:175], v[200:203], v[36:39]
	v_mfma_f32_16x16x32_bf16 v[32:35], v[180:183], v[200:203], v[32:35]
	v_mfma_f32_16x16x32_bf16 v[20:23], v[172:175], v[208:211], v[20:23]
	v_mfma_f32_16x16x32_bf16 v[16:19], v[180:183], v[208:211], v[16:19]
	v_mfma_f32_16x16x32_bf16 v[4:7], v[172:175], v[216:219], v[4:7]
	v_mfma_f32_16x16x32_bf16 v[0:3], v[180:183], v[216:219], v[0:3]
	v_mfma_f32_16x16x32_bf16 v[52:55], v[176:179], v[196:199], v[52:55]
	v_mfma_f32_16x16x32_bf16 v[48:51], v[184:187], v[196:199], v[48:51]
	v_mfma_f32_16x16x32_bf16 v[36:39], v[176:179], v[204:207], v[36:39]
	v_mfma_f32_16x16x32_bf16 v[32:35], v[184:187], v[204:207], v[32:35]
	v_mfma_f32_16x16x32_bf16 v[20:23], v[176:179], v[212:215], v[20:23]
	v_mfma_f32_16x16x32_bf16 v[16:19], v[184:187], v[212:215], v[16:19]
	v_mfma_f32_16x16x32_bf16 v[4:7], v[176:179], v[220:223], v[4:7]
	v_mfma_f32_16x16x32_bf16 v[0:3], v[184:187], v[220:223], v[0:3]
	s_setprio 0
	s_add_i32 s65, s65, 2
	s_add_u32 s59, s59, 0x100
	s_addc_u32 s64, s64, 0
	s_add_u32 s6, s6, 0x100
	s_addc_u32 s7, s7, 0
	s_cmp_gt_u32 s65, 13
	s_barrier
	s_cbranch_scc0 .LBB0_571
	v_lshl_add_u32 v210, s2, 8, v139
	v_ashrrev_i32_e32 v211, 31, v210
	v_lshl_add_u64 v[208:209], v[210:211], 2, s[46:47]
	global_load_dword v200, v[208:209], off
	global_load_dword v201, v[208:209], off offset:64
	global_load_dword v202, v[208:209], off offset:128
	global_load_dword v203, v[208:209], off offset:192
	global_load_dword v204, v[208:209], off offset:512
	global_load_dword v205, v[208:209], off offset:576
	global_load_dword v206, v[208:209], off offset:640
	global_load_dword v207, v[208:209], off offset:704
	s_and_b64 vcc, exec, s[50:51]
	s_cbranch_vccz .LBB0_574
	s_barrier

.LBB0_1106:
	ds_read_b128 v[150:153], v163
	ds_read_b128 v[154:157], v163 offset:1024
	ds_read_b128 v[158:161], v163 offset:2048
	ds_read_b128 v[168:171], v163 offset:3072
	ds_read_b128 v[172:175], v164
	ds_read_b128 v[176:179], v164 offset:1024
	ds_read_b128 v[180:183], v164 offset:2048
	ds_read_b128 v[184:187], v164 offset:3072
	s_add_u32 s36, s34, 0xfffc0080
	s_addc_u32 s37, s35, -1
	s_cmp_eq_u32 s63, 12
	s_cselect_b32 s39, s19, s37
	s_cselect_b32 s38, s23, s36
	s_cselect_b32 s37, s21, s62
	s_cselect_b32 s36, s31, s33
	v_lshl_add_u64 v[188:189], s[34:35], 0, v[142:143]
	s_add_i32 m0, s47, 0xc000
	ds_read_b128 v[192:195], v165
	ds_read_b128 v[196:199], v165 offset:1024
	ds_read_b128 v[200:203], v165 offset:2048
	ds_read_b128 v[204:207], v165 offset:3072
	ds_read_b128 v[208:211], v165 offset:4096
	ds_read_b128 v[212:215], v165 offset:5120
	ds_read_b128 v[216:219], v165 offset:6144
	ds_read_b128 v[220:223], v165 offset:7168
	global_load_lds_dwordx4 v[188:189], off
	v_lshl_add_u64 v[188:189], s[34:35], 0, v[140:141]
	s_add_i32 m0, s47, 0xe000
	s_nop 0
	global_load_lds_dwordx4 v[188:189], off
	s_waitcnt vmcnt(8)
	s_waitcnt lgkmcnt(0)
	s_barrier
	s_setprio 1
	s_waitcnt lgkmcnt(0)
	v_mfma_f32_16x16x32_bf16 v[124:127], v[150:153], v[192:195], v[124:127]
	v_mfma_f32_16x16x32_bf16 v[120:123], v[158:161], v[192:195], v[120:123]
	v_mfma_f32_16x16x32_bf16 v[108:111], v[150:153], v[200:203], v[108:111]
	v_mfma_f32_16x16x32_bf16 v[104:107], v[158:161], v[200:203], v[104:107]
	v_mfma_f32_16x16x32_bf16 v[92:95], v[150:153], v[208:211], v[92:95]
	v_mfma_f32_16x16x32_bf16 v[88:91], v[158:161], v[208:211], v[88:91]
	v_mfma_f32_16x16x32_bf16 v[76:79], v[150:153], v[216:219], v[76:79]
	v_mfma_f32_16x16x32_bf16 v[72:75], v[158:161], v[216:219], v[72:75]
	v_mfma_f32_16x16x32_bf16 v[124:127], v[154:157], v[196:199], v[124:127]
	v_mfma_f32_16x16x32_bf16 v[120:123], v[168:171], v[196:199], v[120:123]
	v_mfma_f32_16x16x32_bf16 v[108:111], v[154:157], v[204:207], v[108:111]
	v_mfma_f32_16x16x32_bf16 v[104:107], v[168:171], v[204:207], v[104:107]
	v_mfma_f32_16x16x32_bf16 v[92:95], v[154:157], v[212:215], v[92:95]
	v_mfma_f32_16x16x32_bf16 v[88:91], v[168:171], v[212:215], v[88:91]
	v_mfma_f32_16x16x32_bf16 v[76:79], v[154:157], v[220:223], v[76:79]
	v_mfma_f32_16x16x32_bf16 v[72:75], v[168:171], v[220:223], v[72:75]
	s_setprio 0
	s_setprio 1
	v_mfma_f32_16x16x32_bf16 v[116:119], v[172:175], v[192:195], v[116:119]
	v_mfma_f32_16x16x32_bf16 v[112:115], v[180:183], v[192:195], v[112:115]
	v_mfma_f32_16x16x32_bf16 v[100:103], v[172:175], v[200:203], v[100:103]
	v_mfma_f32_16x16x32_bf16 v[96:99], v[180:183], v[200:203], v[96:99]
	v_mfma_f32_16x16x32_bf16 v[84:87], v[172:175], v[208:211], v[84:87]
	v_mfma_f32_16x16x32_bf16 v[80:83], v[180:183], v[208:211], v[80:83]
	v_mfma_f32_16x16x32_bf16 v[68:71], v[172:175], v[216:219], v[68:71]
	v_mfma_f32_16x16x32_bf16 v[64:67], v[180:183], v[216:219], v[64:67]
	v_mfma_f32_16x16x32_bf16 v[116:119], v[176:179], v[196:199], v[116:119]
	v_mfma_f32_16x16x32_bf16 v[112:115], v[184:187], v[196:199], v[112:115]
	v_mfma_f32_16x16x32_bf16 v[100:103], v[176:179], v[204:207], v[100:103]
	v_mfma_f32_16x16x32_bf16 v[96:99], v[184:187], v[204:207], v[96:99]
	v_mfma_f32_16x16x32_bf16 v[84:87], v[176:179], v[212:215], v[84:87]
	v_mfma_f32_16x16x32_bf16 v[80:83], v[184:187], v[212:215], v[80:83]
	v_mfma_f32_16x16x32_bf16 v[68:71], v[176:179], v[220:223], v[68:71]
	v_mfma_f32_16x16x32_bf16 v[64:67], v[184:187], v[220:223], v[64:67]
	s_setprio 0
	s_barrier
	s_add_i32 s64, s55, s44
	v_lshl_add_u64 v[188:189], s[36:37], 0, v[132:133]
	s_mov_b32 m0, s64
	ds_read_b128 v[192:195], v165 offset:16384
	ds_read_b128 v[196:199], v165 offset:17408
	ds_read_b128 v[200:203], v165 offset:18432
	ds_read_b128 v[204:207], v165 offset:19456
	ds_read_b128 v[208:211], v165 offset:20480
	ds_read_b128 v[212:215], v165 offset:21504
	ds_read_b128 v[216:219], v165 offset:22528
	ds_read_b128 v[220:223], v165 offset:23552
	global_load_lds_dwordx4 v[188:189], off
	s_add_i32 m0, s64, 0x2000
	s_add_u32 s64, s36, 0x40000
	v_lshl_add_u64 v[224:225], s[36:37], 0, v[128:129]
	s_addc_u32 s65, s37, 0
	s_add_i32 s66, s56, s44
	global_load_lds_dwordx4 v[224:225], off
	v_lshl_add_u64 v[226:227], s[64:65], 0, v[132:133]
	s_mov_b32 m0, s66
	v_lshl_add_u64 v[228:229], s[38:39], 0, v[130:131]
	global_load_lds_dwordx4 v[226:227], off
	v_lshl_add_u64 v[226:227], s[64:65], 0, v[128:129]
	s_add_i32 m0, s66, 0x2000
	s_nop 0
	global_load_lds_dwordx4 v[226:227], off
	v_lshl_add_u64 v[226:227], s[38:39], 0, v[134:135]
	s_mov_b32 m0, s47
	s_nop 0
	global_load_lds_dwordx4 v[226:227], off
	s_mov_b32 m0, s48
	s_nop 0
	global_load_lds_dwordx4 v[228:229], off
	s_waitcnt vmcnt(8)
	s_waitcnt lgkmcnt(0)
	s_barrier
	s_setprio 1
	s_waitcnt lgkmcnt(0)
	v_mfma_f32_16x16x32_bf16 v[60:63], v[150:153], v[192:195], v[60:63]
	v_mfma_f32_16x16x32_bf16 v[56:59], v[158:161], v[192:195], v[56:59]
	v_mfma_f32_16x16x32_bf16 v[44:47], v[150:153], v[200:203], v[44:47]
	v_mfma_f32_16x16x32_bf16 v[40:43], v[158:161], v[200:203], v[40:43]
	v_mfma_f32_16x16x32_bf16 v[28:31], v[150:153], v[208:211], v[28:31]
	v_mfma_f32_16x16x32_bf16 v[24:27], v[158:161], v[208:211], v[24:27]
	v_mfma_f32_16x16x32_bf16 v[12:15], v[150:153], v[216:219], v[12:15]
	v_mfma_f32_16x16x32_bf16 v[8:11], v[158:161], v[216:219], v[8:11]
	v_mfma_f32_16x16x32_bf16 v[60:63], v[154:157], v[196:199], v[60:63]
	v_mfma_f32_16x16x32_bf16 v[56:59], v[168:171], v[196:199], v[56:59]
	v_mfma_f32_16x16x32_bf16 v[44:47], v[154:157], v[204:207], v[44:47]
	v_mfma_f32_16x16x32_bf16 v[40:43], v[168:171], v[204:207], v[40:43]
	v_mfma_f32_16x16x32_bf16 v[28:31], v[154:157], v[212:215], v[28:31]
	v_mfma_f32_16x16x32_bf16 v[24:27], v[168:171], v[212:215], v[24:27]
	v_mfma_f32_16x16x32_bf16 v[12:15], v[154:157], v[220:223], v[12:15]
	v_mfma_f32_16x16x32_bf16 v[8:11], v[168:171], v[220:223], v[8:11]
	s_setprio 0
	s_setprio 1
	v_mfma_f32_16x16x32_bf16 v[52:55], v[172:175], v[192:195], v[52:55]
	v_mfma_f32_16x16x32_bf16 v[48:51], v[180:183], v[192:195], v[48:51]
	v_mfma_f32_16x16x32_bf16 v[36:39], v[172:175], v[200:203], v[36:39]
	v_mfma_f32_16x16x32_bf16 v[32:35], v[180:183], v[200:203], v[32:35]
	v_mfma_f32_16x16x32_bf16 v[20:23], v[172:175], v[208:211], v[20:23]
	v_mfma_f32_16x16x32_bf16 v[16:19], v[180:183], v[208:211], v[16:19]
	v_mfma_f32_16x16x32_bf16 v[4:7], v[172:175], v[216:219], v[4:7]
	v_mfma_f32_16x16x32_bf16 v[0:3], v[180:183], v[216:219], v[0:3]
	v_mfma_f32_16x16x32_bf16 v[52:55], v[176:179], v[196:199], v[52:55]
	v_mfma_f32_16x16x32_bf16 v[48:51], v[184:187], v[196:199], v[48:51]
	v_mfma_f32_16x16x32_bf16 v[36:39], v[176:179], v[204:207], v[36:39]
	v_mfma_f32_16x16x32_bf16 v[32:35], v[184:187], v[204:207], v[32:35]
	v_mfma_f32_16x16x32_bf16 v[20:23], v[176:179], v[212:215], v[20:23]
	v_mfma_f32_16x16x32_bf16 v[16:19], v[184:187], v[212:215], v[16:19]
	v_mfma_f32_16x16x32_bf16 v[4:7], v[176:179], v[220:223], v[4:7]
	v_mfma_f32_16x16x32_bf16 v[0:3], v[184:187], v[220:223], v[0:3]
	s_setprio 0
	s_barrier
	s_add_i32 s64, 0, 0x18000
	v_add_u32_e32 v136, s64, v162
	s_add_i32 s65, 0, 0x1c000
	ds_read_b128 v[150:153], v136
	ds_read_b128 v[154:157], v136 offset:1024
	ds_read_b128 v[158:161], v136 offset:2048
	ds_read_b128 v[168:171], v136 offset:3072
	v_add_u32_e32 v136, s65, v162
	ds_read_b128 v[172:175], v136
	ds_read_b128 v[176:179], v136 offset:1024
	ds_read_b128 v[180:183], v136 offset:2048
	ds_read_b128 v[184:187], v136 offset:3072
	s_add_u32 s38, s38, 0x40000
	s_addc_u32 s39, s39, 0
	s_mov_b32 m0, s49
	v_lshl_add_u64 v[230:231], s[38:39], 0, v[134:135]
	ds_read_b128 v[192:195], v165 offset:32768
	ds_read_b128 v[196:199], v165 offset:33792
	ds_read_b128 v[200:203], v165 offset:34816
	ds_read_b128 v[204:207], v165 offset:35840
	ds_read_b128 v[208:211], v165 offset:36864
	ds_read_b128 v[212:215], v165 offset:37888
	ds_read_b128 v[216:219], v165 offset:38912
	ds_read_b128 v[220:223], v165 offset:39936
	global_load_lds_dwordx4 v[230:231], off
	v_lshl_add_u64 v[230:231], s[38:39], 0, v[130:131]
	s_mov_b32 m0, s50
	s_nop 0
	global_load_lds_dwordx4 v[230:231], off
	s_waitcnt vmcnt(8)
	s_waitcnt lgkmcnt(0)
	s_barrier
	s_setprio 1
	s_waitcnt lgkmcnt(0)
	v_mfma_f32_16x16x32_bf16 v[124:127], v[150:153], v[192:195], v[124:127]
	v_mfma_f32_16x16x32_bf16 v[120:123], v[158:161], v[192:195], v[120:123]
	v_mfma_f32_16x16x32_bf16 v[108:111], v[150:153], v[200:203], v[108:111]
	v_mfma_f32_16x16x32_bf16 v[104:107], v[158:161], v[200:203], v[104:107]
	v_mfma_f32_16x16x32_bf16 v[92:95], v[150:153], v[208:211], v[92:95]
	v_mfma_f32_16x16x32_bf16 v[88:91], v[158:161], v[208:211], v[88:91]
	v_mfma_f32_16x16x32_bf16 v[76:79], v[150:153], v[216:219], v[76:79]
	v_mfma_f32_16x16x32_bf16 v[72:75], v[158:161], v[216:219], v[72:75]
	v_mfma_f32_16x16x32_bf16 v[124:127], v[154:157], v[196:199], v[124:127]
	v_mfma_f32_16x16x32_bf16 v[120:123], v[168:171], v[196:199], v[120:123]
	v_mfma_f32_16x16x32_bf16 v[108:111], v[154:157], v[204:207], v[108:111]
	v_mfma_f32_16x16x32_bf16 v[104:107], v[168:171], v[204:207], v[104:107]
	v_mfma_f32_16x16x32_bf16 v[92:95], v[154:157], v[212:215], v[92:95]
	v_mfma_f32_16x16x32_bf16 v[88:91], v[168:171], v[212:215], v[88:91]
	v_mfma_f32_16x16x32_bf16 v[76:79], v[154:157], v[220:223], v[76:79]
	v_mfma_f32_16x16x32_bf16 v[72:75], v[168:171], v[220:223], v[72:75]
	s_setprio 0
	s_setprio 1
	v_mfma_f32_16x16x32_bf16 v[116:119], v[172:175], v[192:195], v[116:119]
	v_mfma_f32_16x16x32_bf16 v[112:115], v[180:183], v[192:195], v[112:115]
	v_mfma_f32_16x16x32_bf16 v[100:103], v[172:175], v[200:203], v[100:103]
	v_mfma_f32_16x16x32_bf16 v[96:99], v[180:183], v[200:203], v[96:99]
	v_mfma_f32_16x16x32_bf16 v[84:87], v[172:175], v[208:211], v[84:87]
	v_mfma_f32_16x16x32_bf16 v[80:83], v[180:183], v[208:211], v[80:83]
	v_mfma_f32_16x16x32_bf16 v[68:71], v[172:175], v[216:219], v[68:71]
	v_mfma_f32_16x16x32_bf16 v[64:67], v[180:183], v[216:219], v[64:67]
	v_mfma_f32_16x16x32_bf16 v[116:119], v[176:179], v[196:199], v[116:119]
	v_mfma_f32_16x16x32_bf16 v[112:115], v[184:187], v[196:199], v[112:115]
	v_mfma_f32_16x16x32_bf16 v[100:103], v[176:179], v[204:207], v[100:103]
	v_mfma_f32_16x16x32_bf16 v[96:99], v[184:187], v[204:207], v[96:99]
	v_mfma_f32_16x16x32_bf16 v[84:87], v[176:179], v[212:215], v[84:87]
	v_mfma_f32_16x16x32_bf16 v[80:83], v[184:187], v[212:215], v[80:83]
	v_mfma_f32_16x16x32_bf16 v[68:71], v[176:179], v[220:223], v[68:71]
	v_mfma_f32_16x16x32_bf16 v[64:67], v[184:187], v[220:223], v[64:67]
	s_setprio 0
	s_barrier
	s_add_i32 s38, s64, s44
	v_lshl_add_u64 v[188:189], v[188:189], 0, s[14:15]
	s_mov_b32 m0, s38
	ds_read_b128 v[192:195], v165 offset:49152
	ds_read_b128 v[196:199], v165 offset:50176
	ds_read_b128 v[200:203], v165 offset:51200
	ds_read_b128 v[204:207], v165 offset:52224
	ds_read_b128 v[208:211], v165 offset:53248
	ds_read_b128 v[212:215], v165 offset:54272
	ds_read_b128 v[216:219], v165 offset:55296
	ds_read_b128 v[220:223], v165 offset:56320
	global_load_lds_dwordx4 v[188:189], off
	s_add_i32 m0, s38, 0x2000
	s_add_u32 s36, s36, 0x40080
	v_lshl_add_u64 v[188:189], v[224:225], 0, s[14:15]
	s_addc_u32 s37, s37, 0
	s_add_i32 s38, s65, s44
	global_load_lds_dwordx4 v[188:189], off
	v_lshl_add_u64 v[188:189], s[36:37], 0, v[132:133]
	s_mov_b32 m0, s38
	s_nop 0
	global_load_lds_dwordx4 v[188:189], off
	v_lshl_add_u64 v[188:189], s[36:37], 0, v[128:129]
	s_add_i32 m0, s38, 0x2000
	s_nop 0
	global_load_lds_dwordx4 v[188:189], off
	v_lshl_add_u64 v[188:189], v[226:227], 0, s[14:15]
	s_mov_b32 m0, s51
	s_nop 0
	global_load_lds_dwordx4 v[188:189], off
	v_lshl_add_u64 v[188:189], v[228:229], 0, s[14:15]
	s_mov_b32 m0, s52
	s_nop 0
	global_load_lds_dwordx4 v[188:189], off
	s_waitcnt vmcnt(8)
	s_waitcnt lgkmcnt(0)
	s_barrier
	s_setprio 1
	s_waitcnt lgkmcnt(0)
	v_mfma_f32_16x16x32_bf16 v[60:63], v[150:153], v[192:195], v[60:63]
	v_mfma_f32_16x16x32_bf16 v[56:59], v[158:161], v[192:195], v[56:59]
	v_mfma_f32_16x16x32_bf16 v[44:47], v[150:153], v[200:203], v[44:47]
	v_mfma_f32_16x16x32_bf16 v[40:43], v[158:161], v[200:203], v[40:43]
	v_mfma_f32_16x16x32_bf16 v[28:31], v[150:153], v[208:211], v[28:31]
	v_mfma_f32_16x16x32_bf16 v[24:27], v[158:161], v[208:211], v[24:27]
	v_mfma_f32_16x16x32_bf16 v[12:15], v[150:153], v[216:219], v[12:15]
	v_mfma_f32_16x16x32_bf16 v[8:11], v[158:161], v[216:219], v[8:11]
	v_mfma_f32_16x16x32_bf16 v[60:63], v[154:157], v[196:199], v[60:63]
	v_mfma_f32_16x16x32_bf16 v[56:59], v[168:171], v[196:199], v[56:59]
	v_mfma_f32_16x16x32_bf16 v[44:47], v[154:157], v[204:207], v[44:47]
	v_mfma_f32_16x16x32_bf16 v[40:43], v[168:171], v[204:207], v[40:43]
	v_mfma_f32_16x16x32_bf16 v[28:31], v[154:157], v[212:215], v[28:31]
	v_mfma_f32_16x16x32_bf16 v[24:27], v[168:171], v[212:215], v[24:27]
	v_mfma_f32_16x16x32_bf16 v[12:15], v[154:157], v[220:223], v[12:15]
	v_mfma_f32_16x16x32_bf16 v[8:11], v[168:171], v[220:223], v[8:11]
	s_setprio 0
	s_setprio 1
	v_mfma_f32_16x16x32_bf16 v[52:55], v[172:175], v[192:195], v[52:55]
	v_mfma_f32_16x16x32_bf16 v[48:51], v[180:183], v[192:195], v[48:51]
	v_mfma_f32_16x16x32_bf16 v[36:39], v[172:175], v[200:203], v[36:39]
	v_mfma_f32_16x16x32_bf16 v[32:35], v[180:183], v[200:203], v[32:35]
	v_mfma_f32_16x16x32_bf16 v[20:23], v[172:175], v[208:211], v[20:23]
	v_mfma_f32_16x16x32_bf16 v[16:19], v[180:183], v[208:211], v[16:19]
	v_mfma_f32_16x16x32_bf16 v[4:7], v[172:175], v[216:219], v[4:7]
	v_mfma_f32_16x16x32_bf16 v[0:3], v[180:183], v[216:219], v[0:3]
	v_mfma_f32_16x16x32_bf16 v[52:55], v[176:179], v[196:199], v[52:55]
	v_mfma_f32_16x16x32_bf16 v[48:51], v[184:187], v[196:199], v[48:51]
	v_mfma_f32_16x16x32_bf16 v[36:39], v[176:179], v[204:207], v[36:39]
	v_mfma_f32_16x16x32_bf16 v[32:35], v[184:187], v[204:207], v[32:35]
	v_mfma_f32_16x16x32_bf16 v[20:23], v[176:179], v[212:215], v[20:23]
	v_mfma_f32_16x16x32_bf16 v[16:19], v[184:187], v[212:215], v[16:19]
	v_mfma_f32_16x16x32_bf16 v[4:7], v[176:179], v[220:223], v[4:7]
	v_mfma_f32_16x16x32_bf16 v[0:3], v[184:187], v[220:223], v[0:3]
	s_setprio 0
	s_add_i32 s63, s63, 2
	s_add_u32 s33, s33, 0x100
	s_addc_u32 s62, s62, 0
	s_add_u32 s34, s34, 0x100
	s_addc_u32 s35, s35, 0
	s_cmp_gt_u32 s63, 13
	s_barrier
	s_cbranch_scc0 .LBB0_1106
	v_lshl_add_u32 v214, s30, 8, v139
	v_ashrrev_i32_e32 v215, 31, v214
	v_lshl_add_u64 v[212:213], v[214:215], 2, s[12:13]
	global_load_dword v204, v[212:213], off
	global_load_dword v205, v[212:213], off offset:64
	global_load_dword v206, v[212:213], off offset:128
	global_load_dword v207, v[212:213], off offset:192
	global_load_dword v208, v[212:213], off offset:512
	global_load_dword v209, v[212:213], off offset:576
	global_load_dword v210, v[212:213], off offset:640
	global_load_dword v211, v[212:213], off offset:704
	s_and_b64 vcc, exec, s[16:17]
	s_cbranch_vccz .LBB0_1109
	s_barrier

.LBB0_1187:
	ds_read_b128 v[128:131], v171
	ds_read_b128 v[132:135], v171 offset:1024
	ds_read_b128 v[136:139], v171 offset:2048
	ds_read_b128 v[140:143], v171 offset:3072
	ds_read_b128 v[156:159], v172
	ds_read_b128 v[160:163], v172 offset:1024
	ds_read_b128 v[164:167], v172 offset:2048
	ds_read_b128 v[176:179], v172 offset:3072
	s_add_u32 s24, s22, 0x100
	s_addc_u32 s25, s23, 0
	s_cmp_eq_u32 s57, 40
	s_cselect_b32 s31, s5, s25
	s_cselect_b32 s30, s4, s24
	s_cselect_b32 s27, s21, s56
	s_cselect_b32 s26, s20, s55
	v_lshl_add_u64 v[188:189], s[22:23], 0, v[150:151]
	s_add_i32 m0, s38, 0xc000
	ds_read_b128 v[180:183], v173
	ds_read_b128 v[184:187], v173 offset:1024
	ds_read_b128 v[192:195], v173 offset:2048
	ds_read_b128 v[196:199], v173 offset:3072
	ds_read_b128 v[200:203], v173 offset:4096
	ds_read_b128 v[204:207], v173 offset:5120
	ds_read_b128 v[208:211], v173 offset:6144
	ds_read_b128 v[212:215], v173 offset:7168
	global_load_lds_dwordx4 v[188:189], off
	v_lshl_add_u64 v[188:189], s[22:23], 0, v[148:149]
	s_add_i32 m0, s38, 0xe000
	s_nop 0
	global_load_lds_dwordx4 v[188:189], off
	s_waitcnt vmcnt(8)
	s_waitcnt lgkmcnt(0)
	s_barrier
	s_setprio 1
	s_waitcnt lgkmcnt(0)
	v_mfma_f32_16x16x32_bf16 v[124:127], v[128:131], v[180:183], v[124:127]
	v_mfma_f32_16x16x32_bf16 v[120:123], v[136:139], v[180:183], v[120:123]
	v_mfma_f32_16x16x32_bf16 v[108:111], v[128:131], v[192:195], v[108:111]
	v_mfma_f32_16x16x32_bf16 v[104:107], v[136:139], v[192:195], v[104:107]
	v_mfma_f32_16x16x32_bf16 v[92:95], v[128:131], v[200:203], v[92:95]
	v_mfma_f32_16x16x32_bf16 v[88:91], v[136:139], v[200:203], v[88:91]
	v_mfma_f32_16x16x32_bf16 v[76:79], v[128:131], v[208:211], v[76:79]
	v_mfma_f32_16x16x32_bf16 v[72:75], v[136:139], v[208:211], v[72:75]
	v_mfma_f32_16x16x32_bf16 v[124:127], v[132:135], v[184:187], v[124:127]
	v_mfma_f32_16x16x32_bf16 v[120:123], v[140:143], v[184:187], v[120:123]
	v_mfma_f32_16x16x32_bf16 v[108:111], v[132:135], v[196:199], v[108:111]
	v_mfma_f32_16x16x32_bf16 v[104:107], v[140:143], v[196:199], v[104:107]
	v_mfma_f32_16x16x32_bf16 v[92:95], v[132:135], v[204:207], v[92:95]
	v_mfma_f32_16x16x32_bf16 v[88:91], v[140:143], v[204:207], v[88:91]
	v_mfma_f32_16x16x32_bf16 v[76:79], v[132:135], v[212:215], v[76:79]
	v_mfma_f32_16x16x32_bf16 v[72:75], v[140:143], v[212:215], v[72:75]
	s_setprio 0
	s_setprio 1
	v_mfma_f32_16x16x32_bf16 v[116:119], v[156:159], v[180:183], v[116:119]
	v_mfma_f32_16x16x32_bf16 v[112:115], v[164:167], v[180:183], v[112:115]
	v_mfma_f32_16x16x32_bf16 v[100:103], v[156:159], v[192:195], v[100:103]
	v_mfma_f32_16x16x32_bf16 v[96:99], v[164:167], v[192:195], v[96:99]
	v_mfma_f32_16x16x32_bf16 v[84:87], v[156:159], v[200:203], v[84:87]
	v_mfma_f32_16x16x32_bf16 v[80:83], v[164:167], v[200:203], v[80:83]
	v_mfma_f32_16x16x32_bf16 v[68:71], v[156:159], v[208:211], v[68:71]
	v_mfma_f32_16x16x32_bf16 v[64:67], v[164:167], v[208:211], v[64:67]
	v_mfma_f32_16x16x32_bf16 v[116:119], v[160:163], v[184:187], v[116:119]
	v_mfma_f32_16x16x32_bf16 v[112:115], v[176:179], v[184:187], v[112:115]
	v_mfma_f32_16x16x32_bf16 v[100:103], v[160:163], v[196:199], v[100:103]
	v_mfma_f32_16x16x32_bf16 v[96:99], v[176:179], v[196:199], v[96:99]
	v_mfma_f32_16x16x32_bf16 v[84:87], v[160:163], v[204:207], v[84:87]
	v_mfma_f32_16x16x32_bf16 v[80:83], v[176:179], v[204:207], v[80:83]
	v_mfma_f32_16x16x32_bf16 v[68:71], v[160:163], v[212:215], v[68:71]
	v_mfma_f32_16x16x32_bf16 v[64:67], v[176:179], v[212:215], v[64:67]
	s_setprio 0
	s_barrier
	s_add_i32 s22, s49, s37
	v_lshl_add_u64 v[188:189], s[26:27], 0, v[144:145]
	s_mov_b32 m0, s22
	ds_read_b128 v[180:183], v173 offset:16384
	ds_read_b128 v[184:187], v173 offset:17408
	ds_read_b128 v[192:195], v173 offset:18432
	ds_read_b128 v[196:199], v173 offset:19456
	ds_read_b128 v[200:203], v173 offset:20480
	ds_read_b128 v[204:207], v173 offset:21504
	ds_read_b128 v[208:211], v173 offset:22528
	ds_read_b128 v[212:215], v173 offset:23552
	global_load_lds_dwordx4 v[188:189], off
	s_add_i32 m0, s22, 0x2000
	s_add_u32 s22, s26, 0xb0000
	v_lshl_add_u64 v[216:217], s[26:27], 0, v[146:147]
	s_addc_u32 s23, s27, 0
	s_add_i32 s58, s50, s37
	global_load_lds_dwordx4 v[216:217], off
	v_lshl_add_u64 v[218:219], s[22:23], 0, v[144:145]
	s_mov_b32 m0, s58
	v_lshl_add_u64 v[220:221], s[30:31], 0, v[146:147]
	global_load_lds_dwordx4 v[218:219], off
	v_lshl_add_u64 v[218:219], s[22:23], 0, v[146:147]
	s_add_i32 m0, s58, 0x2000
	s_nop 0
	global_load_lds_dwordx4 v[218:219], off
	v_lshl_add_u64 v[218:219], s[30:31], 0, v[144:145]
	s_mov_b32 m0, s38
	s_nop 0
	global_load_lds_dwordx4 v[218:219], off
	s_mov_b32 m0, s39
	s_nop 0
	global_load_lds_dwordx4 v[220:221], off
	s_waitcnt vmcnt(8)
	s_waitcnt lgkmcnt(0)
	s_barrier
	s_setprio 1
	s_waitcnt lgkmcnt(0)
	v_mfma_f32_16x16x32_bf16 v[60:63], v[128:131], v[180:183], v[60:63]
	v_mfma_f32_16x16x32_bf16 v[56:59], v[136:139], v[180:183], v[56:59]
	v_mfma_f32_16x16x32_bf16 v[44:47], v[128:131], v[192:195], v[44:47]
	v_mfma_f32_16x16x32_bf16 v[40:43], v[136:139], v[192:195], v[40:43]
	v_mfma_f32_16x16x32_bf16 v[28:31], v[128:131], v[200:203], v[28:31]
	v_mfma_f32_16x16x32_bf16 v[24:27], v[136:139], v[200:203], v[24:27]
	v_mfma_f32_16x16x32_bf16 v[12:15], v[128:131], v[208:211], v[12:15]
	v_mfma_f32_16x16x32_bf16 v[8:11], v[136:139], v[208:211], v[8:11]
	v_mfma_f32_16x16x32_bf16 v[60:63], v[132:135], v[184:187], v[60:63]
	v_mfma_f32_16x16x32_bf16 v[56:59], v[140:143], v[184:187], v[56:59]
	v_mfma_f32_16x16x32_bf16 v[44:47], v[132:135], v[196:199], v[44:47]
	v_mfma_f32_16x16x32_bf16 v[40:43], v[140:143], v[196:199], v[40:43]
	v_mfma_f32_16x16x32_bf16 v[28:31], v[132:135], v[204:207], v[28:31]
	v_mfma_f32_16x16x32_bf16 v[24:27], v[140:143], v[204:207], v[24:27]
	v_mfma_f32_16x16x32_bf16 v[12:15], v[132:135], v[212:215], v[12:15]
	v_mfma_f32_16x16x32_bf16 v[8:11], v[140:143], v[212:215], v[8:11]
	s_setprio 0
	s_setprio 1
	v_mfma_f32_16x16x32_bf16 v[52:55], v[156:159], v[180:183], v[52:55]
	v_mfma_f32_16x16x32_bf16 v[48:51], v[164:167], v[180:183], v[48:51]
	v_mfma_f32_16x16x32_bf16 v[36:39], v[156:159], v[192:195], v[36:39]
	v_mfma_f32_16x16x32_bf16 v[32:35], v[164:167], v[192:195], v[32:35]
	v_mfma_f32_16x16x32_bf16 v[20:23], v[156:159], v[200:203], v[20:23]
	v_mfma_f32_16x16x32_bf16 v[16:19], v[164:167], v[200:203], v[16:19]
	v_mfma_f32_16x16x32_bf16 v[4:7], v[156:159], v[208:211], v[4:7]
	v_mfma_f32_16x16x32_bf16 v[0:3], v[164:167], v[208:211], v[0:3]
	v_mfma_f32_16x16x32_bf16 v[52:55], v[160:163], v[184:187], v[52:55]
	v_mfma_f32_16x16x32_bf16 v[48:51], v[176:179], v[184:187], v[48:51]
	v_mfma_f32_16x16x32_bf16 v[36:39], v[160:163], v[196:199], v[36:39]
	v_mfma_f32_16x16x32_bf16 v[32:35], v[176:179], v[196:199], v[32:35]
	v_mfma_f32_16x16x32_bf16 v[20:23], v[160:163], v[204:207], v[20:23]
	v_mfma_f32_16x16x32_bf16 v[16:19], v[176:179], v[204:207], v[16:19]
	v_mfma_f32_16x16x32_bf16 v[4:7], v[160:163], v[212:215], v[4:7]
	v_mfma_f32_16x16x32_bf16 v[0:3], v[176:179], v[212:215], v[0:3]
	s_setprio 0
	s_barrier
	s_add_i32 s58, 0, 0x18000
	s_add_i32 s59, 0, 0x1c000
	v_add_u32_e32 v140, s58, v169
	v_add_u32_e32 v175, s59, v169
	ds_read_b128 v[128:131], v140
	ds_read_b128 v[132:135], v140 offset:1024
	ds_read_b128 v[136:139], v140 offset:2048
	ds_read_b128 v[140:143], v140 offset:3072
	ds_read_b128 v[156:159], v175
	ds_read_b128 v[160:163], v175 offset:1024
	ds_read_b128 v[164:167], v175 offset:2048
	ds_read_b128 v[176:179], v175 offset:3072
	s_add_u32 s22, s30, 0xb0000
	s_addc_u32 s23, s31, 0
	s_mov_b32 m0, s40
	v_lshl_add_u64 v[222:223], s[22:23], 0, v[144:145]
	ds_read_b128 v[180:183], v173 offset:32768
	ds_read_b128 v[184:187], v173 offset:33792
	ds_read_b128 v[192:195], v173 offset:34816
	ds_read_b128 v[196:199], v173 offset:35840
	ds_read_b128 v[200:203], v173 offset:36864
	ds_read_b128 v[204:207], v173 offset:37888
	ds_read_b128 v[208:211], v173 offset:38912
	ds_read_b128 v[212:215], v173 offset:39936
	global_load_lds_dwordx4 v[222:223], off
	v_lshl_add_u64 v[222:223], s[22:23], 0, v[146:147]
	s_mov_b32 m0, s41
	s_nop 0
	global_load_lds_dwordx4 v[222:223], off
	s_waitcnt vmcnt(8)
	s_waitcnt lgkmcnt(0)
	s_barrier
	s_setprio 1
	s_waitcnt lgkmcnt(0)
	v_mfma_f32_16x16x32_bf16 v[124:127], v[128:131], v[180:183], v[124:127]
	v_mfma_f32_16x16x32_bf16 v[120:123], v[136:139], v[180:183], v[120:123]
	v_mfma_f32_16x16x32_bf16 v[108:111], v[128:131], v[192:195], v[108:111]
	v_mfma_f32_16x16x32_bf16 v[104:107], v[136:139], v[192:195], v[104:107]
	v_mfma_f32_16x16x32_bf16 v[92:95], v[128:131], v[200:203], v[92:95]
	v_mfma_f32_16x16x32_bf16 v[88:91], v[136:139], v[200:203], v[88:91]
	v_mfma_f32_16x16x32_bf16 v[76:79], v[128:131], v[208:211], v[76:79]
	v_mfma_f32_16x16x32_bf16 v[72:75], v[136:139], v[208:211], v[72:75]
	v_mfma_f32_16x16x32_bf16 v[124:127], v[132:135], v[184:187], v[124:127]
	v_mfma_f32_16x16x32_bf16 v[120:123], v[140:143], v[184:187], v[120:123]
	v_mfma_f32_16x16x32_bf16 v[108:111], v[132:135], v[196:199], v[108:111]
	v_mfma_f32_16x16x32_bf16 v[104:107], v[140:143], v[196:199], v[104:107]
	v_mfma_f32_16x16x32_bf16 v[92:95], v[132:135], v[204:207], v[92:95]
	v_mfma_f32_16x16x32_bf16 v[88:91], v[140:143], v[204:207], v[88:91]
	v_mfma_f32_16x16x32_bf16 v[76:79], v[132:135], v[212:215], v[76:79]
	v_mfma_f32_16x16x32_bf16 v[72:75], v[140:143], v[212:215], v[72:75]
	s_setprio 0
	s_setprio 1
	v_mfma_f32_16x16x32_bf16 v[116:119], v[156:159], v[180:183], v[116:119]
	v_mfma_f32_16x16x32_bf16 v[112:115], v[164:167], v[180:183], v[112:115]
	v_mfma_f32_16x16x32_bf16 v[100:103], v[156:159], v[192:195], v[100:103]
	v_mfma_f32_16x16x32_bf16 v[96:99], v[164:167], v[192:195], v[96:99]
	v_mfma_f32_16x16x32_bf16 v[84:87], v[156:159], v[200:203], v[84:87]
	v_mfma_f32_16x16x32_bf16 v[80:83], v[164:167], v[200:203], v[80:83]
	v_mfma_f32_16x16x32_bf16 v[68:71], v[156:159], v[208:211], v[68:71]
	v_mfma_f32_16x16x32_bf16 v[64:67], v[164:167], v[208:211], v[64:67]
	v_mfma_f32_16x16x32_bf16 v[116:119], v[160:163], v[184:187], v[116:119]
	v_mfma_f32_16x16x32_bf16 v[112:115], v[176:179], v[184:187], v[112:115]
	v_mfma_f32_16x16x32_bf16 v[100:103], v[160:163], v[196:199], v[100:103]
	v_mfma_f32_16x16x32_bf16 v[96:99], v[176:179], v[196:199], v[96:99]
	v_mfma_f32_16x16x32_bf16 v[84:87], v[160:163], v[204:207], v[84:87]
	v_mfma_f32_16x16x32_bf16 v[80:83], v[176:179], v[204:207], v[80:83]
	v_mfma_f32_16x16x32_bf16 v[68:71], v[160:163], v[212:215], v[68:71]
	v_mfma_f32_16x16x32_bf16 v[64:67], v[176:179], v[212:215], v[64:67]
	s_setprio 0
	s_barrier
	s_add_i32 s22, s58, s37
	v_lshl_add_u64 v[188:189], v[188:189], 0, s[16:17]
	s_mov_b32 m0, s22
	ds_read_b128 v[180:183], v173 offset:49152
	ds_read_b128 v[184:187], v173 offset:50176
	ds_read_b128 v[192:195], v173 offset:51200
	ds_read_b128 v[196:199], v173 offset:52224
	ds_read_b128 v[200:203], v173 offset:53248
	ds_read_b128 v[204:207], v173 offset:54272
	ds_read_b128 v[208:211], v173 offset:55296
	ds_read_b128 v[212:215], v173 offset:56320
	global_load_lds_dwordx4 v[188:189], off
	s_add_i32 m0, s22, 0x2000
	s_add_u32 s22, s26, 0xb0080
	v_lshl_add_u64 v[188:189], v[216:217], 0, s[16:17]
	s_addc_u32 s23, s27, 0
	s_add_i32 s26, s59, s37
	global_load_lds_dwordx4 v[188:189], off
	v_lshl_add_u64 v[188:189], s[22:23], 0, v[144:145]
	s_mov_b32 m0, s26
	s_nop 0
	global_load_lds_dwordx4 v[188:189], off
	v_lshl_add_u64 v[188:189], s[22:23], 0, v[146:147]
	s_add_i32 m0, s26, 0x2000
	s_nop 0
	global_load_lds_dwordx4 v[188:189], off
	v_lshl_add_u64 v[188:189], v[218:219], 0, s[16:17]
	s_mov_b32 m0, s43
	s_nop 0
	global_load_lds_dwordx4 v[188:189], off
	v_lshl_add_u64 v[188:189], v[220:221], 0, s[16:17]
	s_mov_b32 m0, s44
	s_nop 0
	global_load_lds_dwordx4 v[188:189], off
	s_waitcnt vmcnt(8)
	s_waitcnt lgkmcnt(0)
	s_barrier
	s_setprio 1
	s_waitcnt lgkmcnt(0)
	v_mfma_f32_16x16x32_bf16 v[60:63], v[128:131], v[180:183], v[60:63]
	v_mfma_f32_16x16x32_bf16 v[56:59], v[136:139], v[180:183], v[56:59]
	v_mfma_f32_16x16x32_bf16 v[44:47], v[128:131], v[192:195], v[44:47]
	v_mfma_f32_16x16x32_bf16 v[40:43], v[136:139], v[192:195], v[40:43]
	v_mfma_f32_16x16x32_bf16 v[28:31], v[128:131], v[200:203], v[28:31]
	v_mfma_f32_16x16x32_bf16 v[24:27], v[136:139], v[200:203], v[24:27]
	v_mfma_f32_16x16x32_bf16 v[12:15], v[128:131], v[208:211], v[12:15]
	v_mfma_f32_16x16x32_bf16 v[8:11], v[136:139], v[208:211], v[8:11]
	v_mfma_f32_16x16x32_bf16 v[60:63], v[132:135], v[184:187], v[60:63]
	v_mfma_f32_16x16x32_bf16 v[56:59], v[140:143], v[184:187], v[56:59]
	v_mfma_f32_16x16x32_bf16 v[44:47], v[132:135], v[196:199], v[44:47]
	v_mfma_f32_16x16x32_bf16 v[40:43], v[140:143], v[196:199], v[40:43]
	v_mfma_f32_16x16x32_bf16 v[28:31], v[132:135], v[204:207], v[28:31]
	v_mfma_f32_16x16x32_bf16 v[24:27], v[140:143], v[204:207], v[24:27]
	v_mfma_f32_16x16x32_bf16 v[12:15], v[132:135], v[212:215], v[12:15]
	v_mfma_f32_16x16x32_bf16 v[8:11], v[140:143], v[212:215], v[8:11]
	s_setprio 0
	s_setprio 1
	v_mfma_f32_16x16x32_bf16 v[52:55], v[156:159], v[180:183], v[52:55]
	v_mfma_f32_16x16x32_bf16 v[48:51], v[164:167], v[180:183], v[48:51]
	v_mfma_f32_16x16x32_bf16 v[36:39], v[156:159], v[192:195], v[36:39]
	v_mfma_f32_16x16x32_bf16 v[32:35], v[164:167], v[192:195], v[32:35]
	v_mfma_f32_16x16x32_bf16 v[20:23], v[156:159], v[200:203], v[20:23]
	v_mfma_f32_16x16x32_bf16 v[16:19], v[164:167], v[200:203], v[16:19]
	v_mfma_f32_16x16x32_bf16 v[4:7], v[156:159], v[208:211], v[4:7]
	v_mfma_f32_16x16x32_bf16 v[0:3], v[164:167], v[208:211], v[0:3]
	v_mfma_f32_16x16x32_bf16 v[52:55], v[160:163], v[184:187], v[52:55]
	v_mfma_f32_16x16x32_bf16 v[48:51], v[176:179], v[184:187], v[48:51]
	v_mfma_f32_16x16x32_bf16 v[36:39], v[160:163], v[196:199], v[36:39]
	v_mfma_f32_16x16x32_bf16 v[32:35], v[176:179], v[196:199], v[32:35]
	v_mfma_f32_16x16x32_bf16 v[20:23], v[160:163], v[204:207], v[20:23]
	v_mfma_f32_16x16x32_bf16 v[16:19], v[176:179], v[204:207], v[16:19]
	v_mfma_f32_16x16x32_bf16 v[4:7], v[160:163], v[212:215], v[4:7]
	v_mfma_f32_16x16x32_bf16 v[0:3], v[176:179], v[212:215], v[0:3]
	s_setprio 0
	s_add_i32 s57, s57, 2
	s_add_u32 s55, s55, 0x100
	s_addc_u32 s56, s56, 0
	s_cmp_gt_u32 s57, 41
	s_mov_b64 s[22:23], s[24:25]
	s_barrier
	s_cbranch_scc0 .LBB0_1187
	v_mbcnt_lo_u32_b32 v235, -1, 0
	v_mbcnt_hi_u32_b32 v235, -1, v235
	v_lshrrev_b32_e32 v236, 2, v235
	v_and_b32_e32 v237, 3, v235
	v_lshl_add_u32 v232, v237, 4, v236
	v_lshlrev_b32_e32 v232, 2, v232
	v_and_b32_e32 v233, -16, v168
	v_or_b32_e32 v233, v233, v236
	v_lshlrev_b32_e32 v237, 2, v237
	v_and_b32_e32 v234, -13, v170
	v_or_b32_e32 v234, v234, v237
	v_lshl_add_u32 v158, s54, 8, v233
	v_lshl_or_b32 v156, s53, 8, v234
	v_ashrrev_i32_e32 v159, 31, v158
	v_lshlrev_b64 v[128:129], 12, v[158:159]
	v_ashrrev_i32_e32 v157, 31, v156
	v_lshl_add_u64 v[128:129], s[8:9], 0, v[128:129]
	v_lshlrev_b64 v[130:131], 2, v[156:157]
	v_lshl_add_u64 v[188:189], v[128:129], 0, v[130:131]
	global_load_dwordx4 v[164:167], v[188:189], off
	global_load_dwordx4 v[176:179], v[188:189], off offset:64
	global_load_dwordx4 v[180:183], v[188:189], off offset:512
	global_load_dwordx4 v[184:187], v[188:189], off offset:576
	v_or_b32_e32 v160, 16, v158
	v_ashrrev_i32_e32 v161, 31, v160
	v_lshlrev_b64 v[128:129], 12, v[160:161]
	v_lshl_add_u64 v[128:129], s[8:9], 0, v[128:129]
	v_lshl_add_u64 v[162:163], v[128:129], 0, v[130:131]
	global_load_dwordx4 v[140:143], v[162:163], off
	global_load_dwordx4 v[136:139], v[162:163], off offset:64
	global_load_dwordx4 v[132:135], v[162:163], off offset:512
	global_load_dwordx4 v[128:131], v[162:163], off offset:576
	v_lshlrev_b64 v[192:193], 11, v[158:159]
	v_lshl_add_u64 v[192:193], s[12:13], 0, v[192:193]
	v_and_b32_e32 v191, 64, v174
	v_lshl_add_u64 v[192:193], v[156:157], 1, v[192:193]
	v_xor_b32_e32 v175, 1, v174
	v_add_u32_e32 v191, 64, v191
	v_cmp_lt_i32_e32 vcc, v175, v191
	v_xor_b32_e32 v194, 2, v174
	ds_bpermute_b32 v127, v232, v127
	ds_bpermute_b32 v126, v232, v126
	ds_bpermute_b32 v125, v232, v125
	ds_bpermute_b32 v124, v232, v124
	ds_bpermute_b32 v123, v232, v123
	ds_bpermute_b32 v122, v232, v122
	ds_bpermute_b32 v121, v232, v121
	ds_bpermute_b32 v120, v232, v120
	ds_bpermute_b32 v119, v232, v119
	ds_bpermute_b32 v118, v232, v118
	ds_bpermute_b32 v117, v232, v117
	ds_bpermute_b32 v116, v232, v116
	ds_bpermute_b32 v115, v232, v115
	ds_bpermute_b32 v114, v232, v114
	ds_bpermute_b32 v113, v232, v113
	ds_bpermute_b32 v112, v232, v112
	ds_bpermute_b32 v111, v232, v111
	ds_bpermute_b32 v110, v232, v110
	ds_bpermute_b32 v109, v232, v109
	ds_bpermute_b32 v108, v232, v108
	ds_bpermute_b32 v107, v232, v107
	ds_bpermute_b32 v106, v232, v106
	ds_bpermute_b32 v105, v232, v105
	ds_bpermute_b32 v104, v232, v104
	ds_bpermute_b32 v103, v232, v103
	ds_bpermute_b32 v102, v232, v102
	ds_bpermute_b32 v101, v232, v101
	ds_bpermute_b32 v100, v232, v100
	ds_bpermute_b32 v99, v232, v99
	ds_bpermute_b32 v98, v232, v98
	ds_bpermute_b32 v97, v232, v97
	ds_bpermute_b32 v96, v232, v96
	ds_bpermute_b32 v95, v232, v95
	ds_bpermute_b32 v94, v232, v94
	ds_bpermute_b32 v93, v232, v93
	ds_bpermute_b32 v92, v232, v92
	ds_bpermute_b32 v91, v232, v91
	ds_bpermute_b32 v90, v232, v90
	ds_bpermute_b32 v89, v232, v89
	ds_bpermute_b32 v88, v232, v88
	ds_bpermute_b32 v87, v232, v87
	ds_bpermute_b32 v86, v232, v86
	ds_bpermute_b32 v85, v232, v85
	ds_bpermute_b32 v84, v232, v84
	ds_bpermute_b32 v83, v232, v83
	ds_bpermute_b32 v82, v232, v82
	ds_bpermute_b32 v81, v232, v81
	ds_bpermute_b32 v80, v232, v80
	ds_bpermute_b32 v79, v232, v79
	ds_bpermute_b32 v78, v232, v78
	ds_bpermute_b32 v77, v232, v77
	ds_bpermute_b32 v76, v232, v76
	ds_bpermute_b32 v75, v232, v75
	ds_bpermute_b32 v74, v232, v74
	ds_bpermute_b32 v73, v232, v73
	ds_bpermute_b32 v72, v232, v72
	ds_bpermute_b32 v71, v232, v71
	ds_bpermute_b32 v70, v232, v70
	ds_bpermute_b32 v69, v232, v69
	ds_bpermute_b32 v68, v232, v68
	ds_bpermute_b32 v67, v232, v67
	ds_bpermute_b32 v66, v232, v66
	ds_bpermute_b32 v65, v232, v65
	ds_bpermute_b32 v64, v232, v64
	ds_bpermute_b32 v63, v232, v63
	ds_bpermute_b32 v62, v232, v62
	ds_bpermute_b32 v61, v232, v61
	ds_bpermute_b32 v60, v232, v60
	ds_bpermute_b32 v59, v232, v59
	ds_bpermute_b32 v58, v232, v58
	ds_bpermute_b32 v57, v232, v57
	ds_bpermute_b32 v56, v232, v56
	ds_bpermute_b32 v55, v232, v55
	ds_bpermute_b32 v54, v232, v54
	ds_bpermute_b32 v53, v232, v53
	ds_bpermute_b32 v52, v232, v52
	ds_bpermute_b32 v51, v232, v51
	ds_bpermute_b32 v50, v232, v50
	ds_bpermute_b32 v49, v232, v49
	ds_bpermute_b32 v48, v232, v48
	ds_bpermute_b32 v47, v232, v47
	ds_bpermute_b32 v46, v232, v46
	ds_bpermute_b32 v45, v232, v45
	ds_bpermute_b32 v44, v232, v44
	ds_bpermute_b32 v43, v232, v43
	ds_bpermute_b32 v42, v232, v42
	ds_bpermute_b32 v41, v232, v41
	ds_bpermute_b32 v40, v232, v40
	ds_bpermute_b32 v39, v232, v39
	ds_bpermute_b32 v38, v232, v38
	ds_bpermute_b32 v37, v232, v37
	ds_bpermute_b32 v36, v232, v36
	ds_bpermute_b32 v35, v232, v35
	ds_bpermute_b32 v34, v232, v34
	ds_bpermute_b32 v33, v232, v33
	ds_bpermute_b32 v32, v232, v32
	ds_bpermute_b32 v31, v232, v31
	ds_bpermute_b32 v30, v232, v30
	ds_bpermute_b32 v29, v232, v29
	ds_bpermute_b32 v28, v232, v28
	ds_bpermute_b32 v27, v232, v27
	ds_bpermute_b32 v26, v232, v26
	ds_bpermute_b32 v25, v232, v25
	ds_bpermute_b32 v24, v232, v24
	ds_bpermute_b32 v23, v232, v23
	ds_bpermute_b32 v22, v232, v22
	ds_bpermute_b32 v21, v232, v21
	ds_bpermute_b32 v20, v232, v20
	ds_bpermute_b32 v19, v232, v19
	ds_bpermute_b32 v18, v232, v18
	ds_bpermute_b32 v17, v232, v17
	ds_bpermute_b32 v16, v232, v16
	ds_bpermute_b32 v15, v232, v15
	ds_bpermute_b32 v14, v232, v14
	ds_bpermute_b32 v13, v232, v13
	ds_bpermute_b32 v12, v232, v12
	ds_bpermute_b32 v11, v232, v11
	ds_bpermute_b32 v10, v232, v10
	ds_bpermute_b32 v9, v232, v9
	ds_bpermute_b32 v8, v232, v8
	ds_bpermute_b32 v7, v232, v7
	ds_bpermute_b32 v6, v232, v6
	ds_bpermute_b32 v5, v232, v5
	ds_bpermute_b32 v4, v232, v4
	ds_bpermute_b32 v3, v232, v3
	ds_bpermute_b32 v2, v232, v2
	ds_bpermute_b32 v1, v232, v1
	ds_bpermute_b32 v0, v232, v0
	s_waitcnt lgkmcnt(0)
	s_waitcnt lgkmcnt(0)
	s_cmp_eq_u64 s[18:19], 0
	s_cbranch_scc1 .LBB0_1190
	s_barrier

.LBB0_1307:
	ds_read_b128 v[128:131], v194
	ds_read_b128 v[132:135], v194 offset:1024
	ds_read_b128 v[136:139], v194 offset:2048
	ds_read_b128 v[140:143], v194 offset:3072
	ds_read_b128 v[144:147], v195
	ds_read_b128 v[160:163], v195 offset:1024
	ds_read_b128 v[164:167], v195 offset:2048
	ds_read_b128 v[168:171], v195 offset:3072
	s_add_u32 s36, s0, 0xfffc0080
	s_addc_u32 s37, s1, -1
	s_cmp_eq_u32 s60, 12
	s_cselect_b32 s39, s23, s37
	s_cselect_b32 s38, s33, s36
	s_cselect_b32 s37, s21, s59
	s_cselect_b32 s36, s57, s58
	v_lshl_add_u64 v[188:189], s[0:1], 0, v[154:155]
	s_add_i32 m0, s31, 0xc000
	ds_read_b128 v[172:175], v196
	ds_read_b128 v[176:179], v196 offset:1024
	ds_read_b128 v[180:183], v196 offset:2048
	ds_read_b128 v[184:187], v196 offset:3072
	ds_read_b128 v[200:203], v196 offset:4096
	ds_read_b128 v[204:207], v196 offset:5120
	ds_read_b128 v[208:211], v196 offset:6144
	ds_read_b128 v[212:215], v196 offset:7168
	global_load_lds_dwordx4 v[188:189], off
	v_lshl_add_u64 v[188:189], s[0:1], 0, v[152:153]
	s_add_i32 m0, s31, 0xe000
	s_nop 0
	global_load_lds_dwordx4 v[188:189], off
	s_waitcnt vmcnt(8)
	s_waitcnt lgkmcnt(0)
	s_barrier
	s_setprio 1
	s_waitcnt lgkmcnt(0)
	v_mfma_f32_16x16x32_bf16 v[124:127], v[128:131], v[172:175], v[124:127]
	v_mfma_f32_16x16x32_bf16 v[120:123], v[136:139], v[172:175], v[120:123]
	v_mfma_f32_16x16x32_bf16 v[108:111], v[128:131], v[180:183], v[108:111]
	v_mfma_f32_16x16x32_bf16 v[104:107], v[136:139], v[180:183], v[104:107]
	v_mfma_f32_16x16x32_bf16 v[92:95], v[128:131], v[200:203], v[92:95]
	v_mfma_f32_16x16x32_bf16 v[88:91], v[136:139], v[200:203], v[88:91]
	v_mfma_f32_16x16x32_bf16 v[76:79], v[128:131], v[208:211], v[76:79]
	v_mfma_f32_16x16x32_bf16 v[72:75], v[136:139], v[208:211], v[72:75]
	v_mfma_f32_16x16x32_bf16 v[124:127], v[132:135], v[176:179], v[124:127]
	v_mfma_f32_16x16x32_bf16 v[120:123], v[140:143], v[176:179], v[120:123]
	v_mfma_f32_16x16x32_bf16 v[108:111], v[132:135], v[184:187], v[108:111]
	v_mfma_f32_16x16x32_bf16 v[104:107], v[140:143], v[184:187], v[104:107]
	v_mfma_f32_16x16x32_bf16 v[92:95], v[132:135], v[204:207], v[92:95]
	v_mfma_f32_16x16x32_bf16 v[88:91], v[140:143], v[204:207], v[88:91]
	v_mfma_f32_16x16x32_bf16 v[76:79], v[132:135], v[212:215], v[76:79]
	v_mfma_f32_16x16x32_bf16 v[72:75], v[140:143], v[212:215], v[72:75]
	s_setprio 0
	s_setprio 1
	v_mfma_f32_16x16x32_bf16 v[116:119], v[144:147], v[172:175], v[116:119]
	v_mfma_f32_16x16x32_bf16 v[112:115], v[164:167], v[172:175], v[112:115]
	v_mfma_f32_16x16x32_bf16 v[100:103], v[144:147], v[180:183], v[100:103]
	v_mfma_f32_16x16x32_bf16 v[96:99], v[164:167], v[180:183], v[96:99]
	v_mfma_f32_16x16x32_bf16 v[84:87], v[144:147], v[200:203], v[84:87]
	v_mfma_f32_16x16x32_bf16 v[80:83], v[164:167], v[200:203], v[80:83]
	v_mfma_f32_16x16x32_bf16 v[68:71], v[144:147], v[208:211], v[68:71]
	v_mfma_f32_16x16x32_bf16 v[64:67], v[164:167], v[208:211], v[64:67]
	v_mfma_f32_16x16x32_bf16 v[116:119], v[160:163], v[176:179], v[116:119]
	v_mfma_f32_16x16x32_bf16 v[112:115], v[168:171], v[176:179], v[112:115]
	v_mfma_f32_16x16x32_bf16 v[100:103], v[160:163], v[184:187], v[100:103]
	v_mfma_f32_16x16x32_bf16 v[96:99], v[168:171], v[184:187], v[96:99]
	v_mfma_f32_16x16x32_bf16 v[84:87], v[160:163], v[204:207], v[84:87]
	v_mfma_f32_16x16x32_bf16 v[80:83], v[168:171], v[204:207], v[80:83]
	v_mfma_f32_16x16x32_bf16 v[68:71], v[160:163], v[212:215], v[68:71]
	v_mfma_f32_16x16x32_bf16 v[64:67], v[168:171], v[212:215], v[64:67]
	s_setprio 0
	s_barrier
	s_add_i32 s61, s54, s42
	v_lshl_add_u64 v[188:189], s[36:37], 0, v[148:149]
	s_mov_b32 m0, s61
	ds_read_b128 v[172:175], v196 offset:16384
	ds_read_b128 v[176:179], v196 offset:17408
	ds_read_b128 v[180:183], v196 offset:18432
	ds_read_b128 v[184:187], v196 offset:19456
	ds_read_b128 v[200:203], v196 offset:20480
	ds_read_b128 v[204:207], v196 offset:21504
	ds_read_b128 v[208:211], v196 offset:22528
	ds_read_b128 v[212:215], v196 offset:23552
	global_load_lds_dwordx4 v[188:189], off
	s_add_i32 m0, s61, 0x2000
	s_add_u32 s62, s36, 0x40000
	v_lshl_add_u64 v[216:217], s[36:37], 0, v[150:151]
	s_addc_u32 s63, s37, 0
	s_add_i32 s61, s55, s42
	global_load_lds_dwordx4 v[216:217], off
	v_lshl_add_u64 v[218:219], s[62:63], 0, v[148:149]
	s_mov_b32 m0, s61
	v_lshl_add_u64 v[220:221], s[38:39], 0, v[150:151]
	global_load_lds_dwordx4 v[218:219], off
	v_lshl_add_u64 v[218:219], s[62:63], 0, v[150:151]
	s_add_i32 m0, s61, 0x2000
	s_nop 0
	global_load_lds_dwordx4 v[218:219], off
	v_lshl_add_u64 v[218:219], s[38:39], 0, v[148:149]
	s_mov_b32 m0, s31
	s_nop 0
	global_load_lds_dwordx4 v[218:219], off
	s_mov_b32 m0, s35
	s_nop 0
	global_load_lds_dwordx4 v[220:221], off
	s_waitcnt vmcnt(8)
	s_waitcnt lgkmcnt(0)
	s_barrier
	s_setprio 1
	s_waitcnt lgkmcnt(0)
	v_mfma_f32_16x16x32_bf16 v[60:63], v[128:131], v[172:175], v[60:63]
	v_mfma_f32_16x16x32_bf16 v[56:59], v[136:139], v[172:175], v[56:59]
	v_mfma_f32_16x16x32_bf16 v[44:47], v[128:131], v[180:183], v[44:47]
	v_mfma_f32_16x16x32_bf16 v[40:43], v[136:139], v[180:183], v[40:43]
	v_mfma_f32_16x16x32_bf16 v[28:31], v[128:131], v[200:203], v[28:31]
	v_mfma_f32_16x16x32_bf16 v[24:27], v[136:139], v[200:203], v[24:27]
	v_mfma_f32_16x16x32_bf16 v[12:15], v[128:131], v[208:211], v[12:15]
	v_mfma_f32_16x16x32_bf16 v[8:11], v[136:139], v[208:211], v[8:11]
	v_mfma_f32_16x16x32_bf16 v[60:63], v[132:135], v[176:179], v[60:63]
	v_mfma_f32_16x16x32_bf16 v[56:59], v[140:143], v[176:179], v[56:59]
	v_mfma_f32_16x16x32_bf16 v[44:47], v[132:135], v[184:187], v[44:47]
	v_mfma_f32_16x16x32_bf16 v[40:43], v[140:143], v[184:187], v[40:43]
	v_mfma_f32_16x16x32_bf16 v[28:31], v[132:135], v[204:207], v[28:31]
	v_mfma_f32_16x16x32_bf16 v[24:27], v[140:143], v[204:207], v[24:27]
	v_mfma_f32_16x16x32_bf16 v[12:15], v[132:135], v[212:215], v[12:15]
	v_mfma_f32_16x16x32_bf16 v[8:11], v[140:143], v[212:215], v[8:11]
	s_setprio 0
	s_setprio 1
	v_mfma_f32_16x16x32_bf16 v[52:55], v[144:147], v[172:175], v[52:55]
	v_mfma_f32_16x16x32_bf16 v[48:51], v[164:167], v[172:175], v[48:51]
	v_mfma_f32_16x16x32_bf16 v[36:39], v[144:147], v[180:183], v[36:39]
	v_mfma_f32_16x16x32_bf16 v[32:35], v[164:167], v[180:183], v[32:35]
	v_mfma_f32_16x16x32_bf16 v[20:23], v[144:147], v[200:203], v[20:23]
	v_mfma_f32_16x16x32_bf16 v[16:19], v[164:167], v[200:203], v[16:19]
	v_mfma_f32_16x16x32_bf16 v[4:7], v[144:147], v[208:211], v[4:7]
	v_mfma_f32_16x16x32_bf16 v[0:3], v[164:167], v[208:211], v[0:3]
	v_mfma_f32_16x16x32_bf16 v[52:55], v[160:163], v[176:179], v[52:55]
	v_mfma_f32_16x16x32_bf16 v[48:51], v[168:171], v[176:179], v[48:51]
	v_mfma_f32_16x16x32_bf16 v[36:39], v[160:163], v[184:187], v[36:39]
	v_mfma_f32_16x16x32_bf16 v[32:35], v[168:171], v[184:187], v[32:35]
	v_mfma_f32_16x16x32_bf16 v[20:23], v[160:163], v[204:207], v[20:23]
	v_mfma_f32_16x16x32_bf16 v[16:19], v[168:171], v[204:207], v[16:19]
	v_mfma_f32_16x16x32_bf16 v[4:7], v[160:163], v[212:215], v[4:7]
	v_mfma_f32_16x16x32_bf16 v[0:3], v[168:171], v[212:215], v[0:3]
	s_setprio 0
	s_barrier
	s_add_i32 s61, 0, 0x18000
	s_add_i32 s62, 0, 0x1c000
	v_add_u32_e32 v140, s61, v192
	v_add_u32_e32 v168, s62, v192
	ds_read_b128 v[128:131], v140
	ds_read_b128 v[132:135], v140 offset:1024
	ds_read_b128 v[136:139], v140 offset:2048
	ds_read_b128 v[140:143], v140 offset:3072
	ds_read_b128 v[144:147], v168
	ds_read_b128 v[160:163], v168 offset:1024
	ds_read_b128 v[164:167], v168 offset:2048
	ds_read_b128 v[168:171], v168 offset:3072
	s_add_u32 s38, s38, 0x40000
	s_addc_u32 s39, s39, 0
	s_mov_b32 m0, s45
	v_lshl_add_u64 v[222:223], s[38:39], 0, v[148:149]
	ds_read_b128 v[172:175], v196 offset:32768
	ds_read_b128 v[176:179], v196 offset:33792
	ds_read_b128 v[180:183], v196 offset:34816
	ds_read_b128 v[184:187], v196 offset:35840
	ds_read_b128 v[200:203], v196 offset:36864
	ds_read_b128 v[204:207], v196 offset:37888
	ds_read_b128 v[208:211], v196 offset:38912
	ds_read_b128 v[212:215], v196 offset:39936
	global_load_lds_dwordx4 v[222:223], off
	v_lshl_add_u64 v[222:223], s[38:39], 0, v[150:151]
	s_mov_b32 m0, s46
	s_nop 0
	global_load_lds_dwordx4 v[222:223], off
	s_waitcnt vmcnt(8)
	s_waitcnt lgkmcnt(0)
	s_barrier
	s_setprio 1
	s_waitcnt lgkmcnt(0)
	v_mfma_f32_16x16x32_bf16 v[124:127], v[128:131], v[172:175], v[124:127]
	v_mfma_f32_16x16x32_bf16 v[120:123], v[136:139], v[172:175], v[120:123]
	v_mfma_f32_16x16x32_bf16 v[108:111], v[128:131], v[180:183], v[108:111]
	v_mfma_f32_16x16x32_bf16 v[104:107], v[136:139], v[180:183], v[104:107]
	v_mfma_f32_16x16x32_bf16 v[92:95], v[128:131], v[200:203], v[92:95]
	v_mfma_f32_16x16x32_bf16 v[88:91], v[136:139], v[200:203], v[88:91]
	v_mfma_f32_16x16x32_bf16 v[76:79], v[128:131], v[208:211], v[76:79]
	v_mfma_f32_16x16x32_bf16 v[72:75], v[136:139], v[208:211], v[72:75]
	v_mfma_f32_16x16x32_bf16 v[124:127], v[132:135], v[176:179], v[124:127]
	v_mfma_f32_16x16x32_bf16 v[120:123], v[140:143], v[176:179], v[120:123]
	v_mfma_f32_16x16x32_bf16 v[108:111], v[132:135], v[184:187], v[108:111]
	v_mfma_f32_16x16x32_bf16 v[104:107], v[140:143], v[184:187], v[104:107]
	v_mfma_f32_16x16x32_bf16 v[92:95], v[132:135], v[204:207], v[92:95]
	v_mfma_f32_16x16x32_bf16 v[88:91], v[140:143], v[204:207], v[88:91]
	v_mfma_f32_16x16x32_bf16 v[76:79], v[132:135], v[212:215], v[76:79]
	v_mfma_f32_16x16x32_bf16 v[72:75], v[140:143], v[212:215], v[72:75]
	s_setprio 0
	s_setprio 1
	v_mfma_f32_16x16x32_bf16 v[116:119], v[144:147], v[172:175], v[116:119]
	v_mfma_f32_16x16x32_bf16 v[112:115], v[164:167], v[172:175], v[112:115]
	v_mfma_f32_16x16x32_bf16 v[100:103], v[144:147], v[180:183], v[100:103]
	v_mfma_f32_16x16x32_bf16 v[96:99], v[164:167], v[180:183], v[96:99]
	v_mfma_f32_16x16x32_bf16 v[84:87], v[144:147], v[200:203], v[84:87]
	v_mfma_f32_16x16x32_bf16 v[80:83], v[164:167], v[200:203], v[80:83]
	v_mfma_f32_16x16x32_bf16 v[68:71], v[144:147], v[208:211], v[68:71]
	v_mfma_f32_16x16x32_bf16 v[64:67], v[164:167], v[208:211], v[64:67]
	v_mfma_f32_16x16x32_bf16 v[116:119], v[160:163], v[176:179], v[116:119]
	v_mfma_f32_16x16x32_bf16 v[112:115], v[168:171], v[176:179], v[112:115]
	v_mfma_f32_16x16x32_bf16 v[100:103], v[160:163], v[184:187], v[100:103]
	v_mfma_f32_16x16x32_bf16 v[96:99], v[168:171], v[184:187], v[96:99]
	v_mfma_f32_16x16x32_bf16 v[84:87], v[160:163], v[204:207], v[84:87]
	v_mfma_f32_16x16x32_bf16 v[80:83], v[168:171], v[204:207], v[80:83]
	v_mfma_f32_16x16x32_bf16 v[68:71], v[160:163], v[212:215], v[68:71]
	v_mfma_f32_16x16x32_bf16 v[64:67], v[168:171], v[212:215], v[64:67]
	s_setprio 0
	s_barrier
	s_add_i32 s38, s61, s42
	v_lshl_add_u64 v[188:189], v[188:189], 0, s[16:17]
	s_mov_b32 m0, s38
	ds_read_b128 v[172:175], v196 offset:49152
	ds_read_b128 v[176:179], v196 offset:50176
	ds_read_b128 v[180:183], v196 offset:51200
	ds_read_b128 v[184:187], v196 offset:52224
	ds_read_b128 v[200:203], v196 offset:53248
	ds_read_b128 v[204:207], v196 offset:54272
	ds_read_b128 v[208:211], v196 offset:55296
	ds_read_b128 v[212:215], v196 offset:56320
	global_load_lds_dwordx4 v[188:189], off
	s_add_i32 m0, s38, 0x2000
	s_add_u32 s36, s36, 0x40080
	v_lshl_add_u64 v[188:189], v[216:217], 0, s[16:17]
	s_addc_u32 s37, s37, 0
	s_add_i32 s38, s62, s42
	global_load_lds_dwordx4 v[188:189], off
	v_lshl_add_u64 v[188:189], s[36:37], 0, v[148:149]
	s_mov_b32 m0, s38
	s_nop 0
	global_load_lds_dwordx4 v[188:189], off
	v_lshl_add_u64 v[188:189], s[36:37], 0, v[150:151]
	s_add_i32 m0, s38, 0x2000
	s_nop 0
	global_load_lds_dwordx4 v[188:189], off
	v_lshl_add_u64 v[188:189], v[218:219], 0, s[16:17]
	s_mov_b32 m0, s48
	s_nop 0
	global_load_lds_dwordx4 v[188:189], off
	v_lshl_add_u64 v[188:189], v[220:221], 0, s[16:17]
	s_mov_b32 m0, s49
	s_nop 0
	global_load_lds_dwordx4 v[188:189], off
	s_waitcnt vmcnt(8)
	s_waitcnt lgkmcnt(0)
	s_barrier
	s_setprio 1
	s_waitcnt lgkmcnt(0)
	v_mfma_f32_16x16x32_bf16 v[60:63], v[128:131], v[172:175], v[60:63]
	v_mfma_f32_16x16x32_bf16 v[56:59], v[136:139], v[172:175], v[56:59]
	v_mfma_f32_16x16x32_bf16 v[44:47], v[128:131], v[180:183], v[44:47]
	v_mfma_f32_16x16x32_bf16 v[40:43], v[136:139], v[180:183], v[40:43]
	v_mfma_f32_16x16x32_bf16 v[28:31], v[128:131], v[200:203], v[28:31]
	v_mfma_f32_16x16x32_bf16 v[24:27], v[136:139], v[200:203], v[24:27]
	v_mfma_f32_16x16x32_bf16 v[12:15], v[128:131], v[208:211], v[12:15]
	v_mfma_f32_16x16x32_bf16 v[8:11], v[136:139], v[208:211], v[8:11]
	v_mfma_f32_16x16x32_bf16 v[60:63], v[132:135], v[176:179], v[60:63]
	v_mfma_f32_16x16x32_bf16 v[56:59], v[140:143], v[176:179], v[56:59]
	v_mfma_f32_16x16x32_bf16 v[44:47], v[132:135], v[184:187], v[44:47]
	v_mfma_f32_16x16x32_bf16 v[40:43], v[140:143], v[184:187], v[40:43]
	v_mfma_f32_16x16x32_bf16 v[28:31], v[132:135], v[204:207], v[28:31]
	v_mfma_f32_16x16x32_bf16 v[24:27], v[140:143], v[204:207], v[24:27]
	v_mfma_f32_16x16x32_bf16 v[12:15], v[132:135], v[212:215], v[12:15]
	v_mfma_f32_16x16x32_bf16 v[8:11], v[140:143], v[212:215], v[8:11]
	s_setprio 0
	s_setprio 1
	v_mfma_f32_16x16x32_bf16 v[52:55], v[144:147], v[172:175], v[52:55]
	v_mfma_f32_16x16x32_bf16 v[48:51], v[164:167], v[172:175], v[48:51]
	v_mfma_f32_16x16x32_bf16 v[36:39], v[144:147], v[180:183], v[36:39]
	v_mfma_f32_16x16x32_bf16 v[32:35], v[164:167], v[180:183], v[32:35]
	v_mfma_f32_16x16x32_bf16 v[20:23], v[144:147], v[200:203], v[20:23]
	v_mfma_f32_16x16x32_bf16 v[16:19], v[164:167], v[200:203], v[16:19]
	v_mfma_f32_16x16x32_bf16 v[4:7], v[144:147], v[208:211], v[4:7]
	v_mfma_f32_16x16x32_bf16 v[0:3], v[164:167], v[208:211], v[0:3]
	v_mfma_f32_16x16x32_bf16 v[52:55], v[160:163], v[176:179], v[52:55]
	v_mfma_f32_16x16x32_bf16 v[48:51], v[168:171], v[176:179], v[48:51]
	v_mfma_f32_16x16x32_bf16 v[36:39], v[160:163], v[184:187], v[36:39]
	v_mfma_f32_16x16x32_bf16 v[32:35], v[168:171], v[184:187], v[32:35]
	v_mfma_f32_16x16x32_bf16 v[20:23], v[160:163], v[204:207], v[20:23]
	v_mfma_f32_16x16x32_bf16 v[16:19], v[168:171], v[204:207], v[16:19]
	v_mfma_f32_16x16x32_bf16 v[4:7], v[160:163], v[212:215], v[4:7]
	v_mfma_f32_16x16x32_bf16 v[0:3], v[168:171], v[212:215], v[0:3]
	s_setprio 0
	s_add_i32 s60, s60, 2
	s_add_u32 s58, s58, 0x100
	s_addc_u32 s59, s59, 0
	s_add_u32 s0, s0, 0x100
	s_addc_u32 s1, s1, 0
	s_cmp_gt_u32 s60, 13
	s_barrier
	s_cbranch_scc0 .LBB0_1307
	v_mbcnt_lo_u32_b32 v235, -1, 0
	v_mbcnt_hi_u32_b32 v235, -1, v235
	v_lshrrev_b32_e32 v236, 2, v235
	v_and_b32_e32 v237, 3, v235
	v_lshl_add_u32 v232, v237, 4, v236
	v_lshlrev_b32_e32 v232, 2, v232
	v_and_b32_e32 v233, -16, v191
	v_or_b32_e32 v233, v233, v236
	v_lshlrev_b32_e32 v237, 2, v237
	v_and_b32_e32 v234, -13, v193
	v_or_b32_e32 v234, v234, v237
	v_lshl_add_u32 v164, s30, 8, v233
	v_ashrrev_i32_e32 v165, 31, v164
	v_lshl_add_u64 v[162:163], v[164:165], 2, s[14:15]
	global_load_dword v181, v[162:163], off
	v_lshl_or_b32 v160, s34, 8, v234
	v_lshlrev_b64 v[128:129], 11, v[164:165]
	v_ashrrev_i32_e32 v161, 31, v160
	v_lshl_add_u64 v[128:129], s[8:9], 0, v[128:129]
	v_lshlrev_b64 v[130:131], 1, v[160:161]
	v_lshl_add_u64 v[172:173], v[128:129], 0, v[130:131]
	v_lshlrev_b64 v[128:129], 12, v[164:165]
	v_lshlrev_b64 v[132:133], 2, v[160:161]
	v_lshl_add_u64 v[128:129], s[6:7], 0, v[128:129]
	global_load_dwordx2 v[184:185], v[172:173], off
	global_load_dwordx2 v[188:189], v[172:173], off offset:32
	v_lshl_add_u64 v[176:177], v[128:129], 0, v[132:133]
	global_load_dwordx4 v[200:203], v[176:177], off
	global_load_dwordx4 v[204:207], v[176:177], off offset:64
	v_or_b32_e32 v166, 16, v164
	v_ashrrev_i32_e32 v167, 31, v166
	v_lshl_add_u64 v[136:137], v[166:167], 2, s[14:15]
	global_load_dword v180, v[136:137], off
	global_load_dwordx4 v[208:211], v[176:177], off offset:512
	global_load_dwordx4 v[144:147], v[176:177], off offset:576
	global_load_dwordx2 v[212:213], v[172:173], off offset:256
	global_load_dwordx2 v[214:215], v[172:173], off offset:288
	v_lshlrev_b64 v[128:129], 12, v[166:167]
	v_lshlrev_b64 v[134:135], 11, v[166:167]
	v_lshl_add_u64 v[128:129], s[6:7], 0, v[128:129]
	v_lshl_add_u64 v[134:135], s[8:9], 0, v[134:135]
	v_lshl_add_u64 v[170:171], v[128:129], 0, v[132:133]
	v_lshl_add_u64 v[168:169], v[134:135], 0, v[130:131]
	global_load_dwordx4 v[140:143], v[170:171], off
	global_load_dwordx4 v[136:139], v[170:171], off offset:64
	global_load_dwordx4 v[132:135], v[170:171], off offset:512
	global_load_dwordx4 v[128:131], v[170:171], off offset:576
	global_load_dwordx2 v[186:187], v[168:169], off
	global_load_dwordx2 v[182:183], v[168:169], off offset:32
	global_load_dwordx2 v[178:179], v[168:169], off offset:256
	global_load_dwordx2 v[174:175], v[168:169], off offset:288
	ds_bpermute_b32 v127, v232, v127
	ds_bpermute_b32 v126, v232, v126
	ds_bpermute_b32 v125, v232, v125
	ds_bpermute_b32 v124, v232, v124
	ds_bpermute_b32 v123, v232, v123
	ds_bpermute_b32 v122, v232, v122
	ds_bpermute_b32 v121, v232, v121
	ds_bpermute_b32 v120, v232, v120
	ds_bpermute_b32 v119, v232, v119
	ds_bpermute_b32 v118, v232, v118
	ds_bpermute_b32 v117, v232, v117
	ds_bpermute_b32 v116, v232, v116
	ds_bpermute_b32 v115, v232, v115
	ds_bpermute_b32 v114, v232, v114
	ds_bpermute_b32 v113, v232, v113
	ds_bpermute_b32 v112, v232, v112
	ds_bpermute_b32 v111, v232, v111
	ds_bpermute_b32 v110, v232, v110
	ds_bpermute_b32 v109, v232, v109
	ds_bpermute_b32 v108, v232, v108
	ds_bpermute_b32 v107, v232, v107
	ds_bpermute_b32 v106, v232, v106
	ds_bpermute_b32 v105, v232, v105
	ds_bpermute_b32 v104, v232, v104
	ds_bpermute_b32 v103, v232, v103
	ds_bpermute_b32 v102, v232, v102
	ds_bpermute_b32 v101, v232, v101
	ds_bpermute_b32 v100, v232, v100
	ds_bpermute_b32 v99, v232, v99
	ds_bpermute_b32 v98, v232, v98
	ds_bpermute_b32 v97, v232, v97
	ds_bpermute_b32 v96, v232, v96
	ds_bpermute_b32 v95, v232, v95
	ds_bpermute_b32 v94, v232, v94
	ds_bpermute_b32 v93, v232, v93
	ds_bpermute_b32 v92, v232, v92
	ds_bpermute_b32 v91, v232, v91
	ds_bpermute_b32 v90, v232, v90
	ds_bpermute_b32 v89, v232, v89
	ds_bpermute_b32 v88, v232, v88
	ds_bpermute_b32 v87, v232, v87
	ds_bpermute_b32 v86, v232, v86
	ds_bpermute_b32 v85, v232, v85
	ds_bpermute_b32 v84, v232, v84
	ds_bpermute_b32 v83, v232, v83
	ds_bpermute_b32 v82, v232, v82
	ds_bpermute_b32 v81, v232, v81
	ds_bpermute_b32 v80, v232, v80
	ds_bpermute_b32 v79, v232, v79
	ds_bpermute_b32 v78, v232, v78
	ds_bpermute_b32 v77, v232, v77
	ds_bpermute_b32 v76, v232, v76
	ds_bpermute_b32 v75, v232, v75
	ds_bpermute_b32 v74, v232, v74
	ds_bpermute_b32 v73, v232, v73
	ds_bpermute_b32 v72, v232, v72
	ds_bpermute_b32 v71, v232, v71
	ds_bpermute_b32 v70, v232, v70
	ds_bpermute_b32 v69, v232, v69
	ds_bpermute_b32 v68, v232, v68
	ds_bpermute_b32 v67, v232, v67
	ds_bpermute_b32 v66, v232, v66
	ds_bpermute_b32 v65, v232, v65
	ds_bpermute_b32 v64, v232, v64
	ds_bpermute_b32 v63, v232, v63
	ds_bpermute_b32 v62, v232, v62
	ds_bpermute_b32 v61, v232, v61
	ds_bpermute_b32 v60, v232, v60
	ds_bpermute_b32 v59, v232, v59
	ds_bpermute_b32 v58, v232, v58
	ds_bpermute_b32 v57, v232, v57
	ds_bpermute_b32 v56, v232, v56
	ds_bpermute_b32 v55, v232, v55
	ds_bpermute_b32 v54, v232, v54
	ds_bpermute_b32 v53, v232, v53
	ds_bpermute_b32 v52, v232, v52
	ds_bpermute_b32 v51, v232, v51
	ds_bpermute_b32 v50, v232, v50
	ds_bpermute_b32 v49, v232, v49
	ds_bpermute_b32 v48, v232, v48
	ds_bpermute_b32 v47, v232, v47
	ds_bpermute_b32 v46, v232, v46
	ds_bpermute_b32 v45, v232, v45
	ds_bpermute_b32 v44, v232, v44
	ds_bpermute_b32 v43, v232, v43
	ds_bpermute_b32 v42, v232, v42
	ds_bpermute_b32 v41, v232, v41
	ds_bpermute_b32 v40, v232, v40
	ds_bpermute_b32 v39, v232, v39
	ds_bpermute_b32 v38, v232, v38
	ds_bpermute_b32 v37, v232, v37
	ds_bpermute_b32 v36, v232, v36
	ds_bpermute_b32 v35, v232, v35
	ds_bpermute_b32 v34, v232, v34
	ds_bpermute_b32 v33, v232, v33
	ds_bpermute_b32 v32, v232, v32
	ds_bpermute_b32 v31, v232, v31
	ds_bpermute_b32 v30, v232, v30
	ds_bpermute_b32 v29, v232, v29
	ds_bpermute_b32 v28, v232, v28
	ds_bpermute_b32 v27, v232, v27
	ds_bpermute_b32 v26, v232, v26
	ds_bpermute_b32 v25, v232, v25
	ds_bpermute_b32 v24, v232, v24
	ds_bpermute_b32 v23, v232, v23
	ds_bpermute_b32 v22, v232, v22
	ds_bpermute_b32 v21, v232, v21
	ds_bpermute_b32 v20, v232, v20
	ds_bpermute_b32 v19, v232, v19
	ds_bpermute_b32 v18, v232, v18
	ds_bpermute_b32 v17, v232, v17
	ds_bpermute_b32 v16, v232, v16
	ds_bpermute_b32 v15, v232, v15
	ds_bpermute_b32 v14, v232, v14
	ds_bpermute_b32 v13, v232, v13
	ds_bpermute_b32 v12, v232, v12
	ds_bpermute_b32 v11, v232, v11
	ds_bpermute_b32 v10, v232, v10
	ds_bpermute_b32 v9, v232, v9
	ds_bpermute_b32 v8, v232, v8
	ds_bpermute_b32 v7, v232, v7
	ds_bpermute_b32 v6, v232, v6
	ds_bpermute_b32 v5, v232, v5
	ds_bpermute_b32 v4, v232, v4
	ds_bpermute_b32 v3, v232, v3
	ds_bpermute_b32 v2, v232, v2
	ds_bpermute_b32 v1, v232, v1
	ds_bpermute_b32 v0, v232, v0
	s_waitcnt lgkmcnt(0)
	s_waitcnt lgkmcnt(0)
	s_and_b64 vcc, exec, s[18:19]
	s_cbranch_vccz .LBB0_1310
	s_barrier

.LBB0_1394:
	ds_read_b128 v[150:153], v163
	ds_read_b128 v[154:157], v163 offset:1024
	ds_read_b128 v[158:161], v163 offset:2048
	ds_read_b128 v[168:171], v163 offset:3072
	ds_read_b128 v[172:175], v164
	ds_read_b128 v[176:179], v164 offset:1024
	ds_read_b128 v[180:183], v164 offset:2048
	ds_read_b128 v[184:187], v164 offset:3072
	s_add_u32 s34, s30, 0xfffc0080
	s_addc_u32 s35, s31, -1
	s_cmp_eq_u32 s63, 12
	s_cselect_b32 s37, s12, s35
	s_cselect_b32 s36, s21, s34
	s_cselect_b32 s35, s23, s62
	s_cselect_b32 s34, s25, s33
	v_lshl_add_u64 v[188:189], s[30:31], 0, v[142:143]
	s_add_i32 m0, s45, 0xc000
	ds_read_b128 v[192:195], v165
	ds_read_b128 v[196:199], v165 offset:1024
	ds_read_b128 v[200:203], v165 offset:2048
	ds_read_b128 v[204:207], v165 offset:3072
	ds_read_b128 v[208:211], v165 offset:4096
	ds_read_b128 v[212:215], v165 offset:5120
	ds_read_b128 v[216:219], v165 offset:6144
	ds_read_b128 v[220:223], v165 offset:7168
	global_load_lds_dwordx4 v[188:189], off
	v_lshl_add_u64 v[188:189], s[30:31], 0, v[140:141]
	s_add_i32 m0, s45, 0xe000
	s_nop 0
	global_load_lds_dwordx4 v[188:189], off
	s_waitcnt vmcnt(8)
	s_waitcnt lgkmcnt(0)
	s_barrier
	s_setprio 1
	s_waitcnt lgkmcnt(0)
	v_mfma_f32_16x16x32_bf16 v[124:127], v[150:153], v[192:195], v[124:127]
	v_mfma_f32_16x16x32_bf16 v[120:123], v[158:161], v[192:195], v[120:123]
	v_mfma_f32_16x16x32_bf16 v[108:111], v[150:153], v[200:203], v[108:111]
	v_mfma_f32_16x16x32_bf16 v[104:107], v[158:161], v[200:203], v[104:107]
	v_mfma_f32_16x16x32_bf16 v[92:95], v[150:153], v[208:211], v[92:95]
	v_mfma_f32_16x16x32_bf16 v[88:91], v[158:161], v[208:211], v[88:91]
	v_mfma_f32_16x16x32_bf16 v[76:79], v[150:153], v[216:219], v[76:79]
	v_mfma_f32_16x16x32_bf16 v[72:75], v[158:161], v[216:219], v[72:75]
	v_mfma_f32_16x16x32_bf16 v[124:127], v[154:157], v[196:199], v[124:127]
	v_mfma_f32_16x16x32_bf16 v[120:123], v[168:171], v[196:199], v[120:123]
	v_mfma_f32_16x16x32_bf16 v[108:111], v[154:157], v[204:207], v[108:111]
	v_mfma_f32_16x16x32_bf16 v[104:107], v[168:171], v[204:207], v[104:107]
	v_mfma_f32_16x16x32_bf16 v[92:95], v[154:157], v[212:215], v[92:95]
	v_mfma_f32_16x16x32_bf16 v[88:91], v[168:171], v[212:215], v[88:91]
	v_mfma_f32_16x16x32_bf16 v[76:79], v[154:157], v[220:223], v[76:79]
	v_mfma_f32_16x16x32_bf16 v[72:75], v[168:171], v[220:223], v[72:75]
	s_setprio 0
	s_setprio 1
	v_mfma_f32_16x16x32_bf16 v[116:119], v[172:175], v[192:195], v[116:119]
	v_mfma_f32_16x16x32_bf16 v[112:115], v[180:183], v[192:195], v[112:115]
	v_mfma_f32_16x16x32_bf16 v[100:103], v[172:175], v[200:203], v[100:103]
	v_mfma_f32_16x16x32_bf16 v[96:99], v[180:183], v[200:203], v[96:99]
	v_mfma_f32_16x16x32_bf16 v[84:87], v[172:175], v[208:211], v[84:87]
	v_mfma_f32_16x16x32_bf16 v[80:83], v[180:183], v[208:211], v[80:83]
	v_mfma_f32_16x16x32_bf16 v[68:71], v[172:175], v[216:219], v[68:71]
	v_mfma_f32_16x16x32_bf16 v[64:67], v[180:183], v[216:219], v[64:67]
	v_mfma_f32_16x16x32_bf16 v[116:119], v[176:179], v[196:199], v[116:119]
	v_mfma_f32_16x16x32_bf16 v[112:115], v[184:187], v[196:199], v[112:115]
	v_mfma_f32_16x16x32_bf16 v[100:103], v[176:179], v[204:207], v[100:103]
	v_mfma_f32_16x16x32_bf16 v[96:99], v[184:187], v[204:207], v[96:99]
	v_mfma_f32_16x16x32_bf16 v[84:87], v[176:179], v[212:215], v[84:87]
	v_mfma_f32_16x16x32_bf16 v[80:83], v[184:187], v[212:215], v[80:83]
	v_mfma_f32_16x16x32_bf16 v[68:71], v[176:179], v[220:223], v[68:71]
	v_mfma_f32_16x16x32_bf16 v[64:67], v[184:187], v[220:223], v[64:67]
	s_setprio 0
	s_barrier
	s_add_i32 s64, s53, s42
	v_lshl_add_u64 v[188:189], s[34:35], 0, v[132:133]
	s_mov_b32 m0, s64
	ds_read_b128 v[192:195], v165 offset:16384
	ds_read_b128 v[196:199], v165 offset:17408
	ds_read_b128 v[200:203], v165 offset:18432
	ds_read_b128 v[204:207], v165 offset:19456
	ds_read_b128 v[208:211], v165 offset:20480
	ds_read_b128 v[212:215], v165 offset:21504
	ds_read_b128 v[216:219], v165 offset:22528
	ds_read_b128 v[220:223], v165 offset:23552
	global_load_lds_dwordx4 v[188:189], off
	s_add_i32 m0, s64, 0x2000
	s_add_u32 s64, s34, 0x40000
	v_lshl_add_u64 v[224:225], s[34:35], 0, v[128:129]
	s_addc_u32 s65, s35, 0
	s_add_i32 s66, s54, s42
	global_load_lds_dwordx4 v[224:225], off
	v_lshl_add_u64 v[226:227], s[64:65], 0, v[132:133]
	s_mov_b32 m0, s66
	v_lshl_add_u64 v[228:229], s[36:37], 0, v[130:131]
	global_load_lds_dwordx4 v[226:227], off
	v_lshl_add_u64 v[226:227], s[64:65], 0, v[128:129]
	s_add_i32 m0, s66, 0x2000
	s_nop 0
	global_load_lds_dwordx4 v[226:227], off
	v_lshl_add_u64 v[226:227], s[36:37], 0, v[134:135]
	s_mov_b32 m0, s45
	s_nop 0
	global_load_lds_dwordx4 v[226:227], off
	s_mov_b32 m0, s46
	s_nop 0
	global_load_lds_dwordx4 v[228:229], off
	s_waitcnt vmcnt(8)
	s_waitcnt lgkmcnt(0)
	s_barrier
	s_setprio 1
	s_waitcnt lgkmcnt(0)
	v_mfma_f32_16x16x32_bf16 v[60:63], v[150:153], v[192:195], v[60:63]
	v_mfma_f32_16x16x32_bf16 v[56:59], v[158:161], v[192:195], v[56:59]
	v_mfma_f32_16x16x32_bf16 v[44:47], v[150:153], v[200:203], v[44:47]
	v_mfma_f32_16x16x32_bf16 v[40:43], v[158:161], v[200:203], v[40:43]
	v_mfma_f32_16x16x32_bf16 v[28:31], v[150:153], v[208:211], v[28:31]
	v_mfma_f32_16x16x32_bf16 v[24:27], v[158:161], v[208:211], v[24:27]
	v_mfma_f32_16x16x32_bf16 v[12:15], v[150:153], v[216:219], v[12:15]
	v_mfma_f32_16x16x32_bf16 v[8:11], v[158:161], v[216:219], v[8:11]
	v_mfma_f32_16x16x32_bf16 v[60:63], v[154:157], v[196:199], v[60:63]
	v_mfma_f32_16x16x32_bf16 v[56:59], v[168:171], v[196:199], v[56:59]
	v_mfma_f32_16x16x32_bf16 v[44:47], v[154:157], v[204:207], v[44:47]
	v_mfma_f32_16x16x32_bf16 v[40:43], v[168:171], v[204:207], v[40:43]
	v_mfma_f32_16x16x32_bf16 v[28:31], v[154:157], v[212:215], v[28:31]
	v_mfma_f32_16x16x32_bf16 v[24:27], v[168:171], v[212:215], v[24:27]
	v_mfma_f32_16x16x32_bf16 v[12:15], v[154:157], v[220:223], v[12:15]
	v_mfma_f32_16x16x32_bf16 v[8:11], v[168:171], v[220:223], v[8:11]
	s_setprio 0
	s_setprio 1
	v_mfma_f32_16x16x32_bf16 v[52:55], v[172:175], v[192:195], v[52:55]
	v_mfma_f32_16x16x32_bf16 v[48:51], v[180:183], v[192:195], v[48:51]
	v_mfma_f32_16x16x32_bf16 v[36:39], v[172:175], v[200:203], v[36:39]
	v_mfma_f32_16x16x32_bf16 v[32:35], v[180:183], v[200:203], v[32:35]
	v_mfma_f32_16x16x32_bf16 v[20:23], v[172:175], v[208:211], v[20:23]
	v_mfma_f32_16x16x32_bf16 v[16:19], v[180:183], v[208:211], v[16:19]
	v_mfma_f32_16x16x32_bf16 v[4:7], v[172:175], v[216:219], v[4:7]
	v_mfma_f32_16x16x32_bf16 v[0:3], v[180:183], v[216:219], v[0:3]
	v_mfma_f32_16x16x32_bf16 v[52:55], v[176:179], v[196:199], v[52:55]
	v_mfma_f32_16x16x32_bf16 v[48:51], v[184:187], v[196:199], v[48:51]
	v_mfma_f32_16x16x32_bf16 v[36:39], v[176:179], v[204:207], v[36:39]
	v_mfma_f32_16x16x32_bf16 v[32:35], v[184:187], v[204:207], v[32:35]
	v_mfma_f32_16x16x32_bf16 v[20:23], v[176:179], v[212:215], v[20:23]
	v_mfma_f32_16x16x32_bf16 v[16:19], v[184:187], v[212:215], v[16:19]
	v_mfma_f32_16x16x32_bf16 v[4:7], v[176:179], v[220:223], v[4:7]
	v_mfma_f32_16x16x32_bf16 v[0:3], v[184:187], v[220:223], v[0:3]
	s_setprio 0
	s_barrier
	s_add_i32 s64, 0, 0x18000
	v_add_u32_e32 v136, s64, v162
	s_add_i32 s65, 0, 0x1c000
	ds_read_b128 v[150:153], v136
	ds_read_b128 v[154:157], v136 offset:1024
	ds_read_b128 v[158:161], v136 offset:2048
	ds_read_b128 v[168:171], v136 offset:3072
	v_add_u32_e32 v136, s65, v162
	ds_read_b128 v[172:175], v136
	ds_read_b128 v[176:179], v136 offset:1024
	ds_read_b128 v[180:183], v136 offset:2048
	ds_read_b128 v[184:187], v136 offset:3072
	s_add_u32 s36, s36, 0x40000
	s_addc_u32 s37, s37, 0
	s_mov_b32 m0, s47
	v_lshl_add_u64 v[230:231], s[36:37], 0, v[134:135]
	ds_read_b128 v[192:195], v165 offset:32768
	ds_read_b128 v[196:199], v165 offset:33792
	ds_read_b128 v[200:203], v165 offset:34816
	ds_read_b128 v[204:207], v165 offset:35840
	ds_read_b128 v[208:211], v165 offset:36864
	ds_read_b128 v[212:215], v165 offset:37888
	ds_read_b128 v[216:219], v165 offset:38912
	ds_read_b128 v[220:223], v165 offset:39936
	global_load_lds_dwordx4 v[230:231], off
	v_lshl_add_u64 v[230:231], s[36:37], 0, v[130:131]
	s_mov_b32 m0, s48
	s_nop 0
	global_load_lds_dwordx4 v[230:231], off
	s_waitcnt vmcnt(8)
	s_waitcnt lgkmcnt(0)
	s_barrier
	s_setprio 1
	s_waitcnt lgkmcnt(0)
	v_mfma_f32_16x16x32_bf16 v[124:127], v[150:153], v[192:195], v[124:127]
	v_mfma_f32_16x16x32_bf16 v[120:123], v[158:161], v[192:195], v[120:123]
	v_mfma_f32_16x16x32_bf16 v[108:111], v[150:153], v[200:203], v[108:111]
	v_mfma_f32_16x16x32_bf16 v[104:107], v[158:161], v[200:203], v[104:107]
	v_mfma_f32_16x16x32_bf16 v[92:95], v[150:153], v[208:211], v[92:95]
	v_mfma_f32_16x16x32_bf16 v[88:91], v[158:161], v[208:211], v[88:91]
	v_mfma_f32_16x16x32_bf16 v[76:79], v[150:153], v[216:219], v[76:79]
	v_mfma_f32_16x16x32_bf16 v[72:75], v[158:161], v[216:219], v[72:75]
	v_mfma_f32_16x16x32_bf16 v[124:127], v[154:157], v[196:199], v[124:127]
	v_mfma_f32_16x16x32_bf16 v[120:123], v[168:171], v[196:199], v[120:123]
	v_mfma_f32_16x16x32_bf16 v[108:111], v[154:157], v[204:207], v[108:111]
	v_mfma_f32_16x16x32_bf16 v[104:107], v[168:171], v[204:207], v[104:107]
	v_mfma_f32_16x16x32_bf16 v[92:95], v[154:157], v[212:215], v[92:95]
	v_mfma_f32_16x16x32_bf16 v[88:91], v[168:171], v[212:215], v[88:91]
	v_mfma_f32_16x16x32_bf16 v[76:79], v[154:157], v[220:223], v[76:79]
	v_mfma_f32_16x16x32_bf16 v[72:75], v[168:171], v[220:223], v[72:75]
	s_setprio 0
	s_setprio 1
	v_mfma_f32_16x16x32_bf16 v[116:119], v[172:175], v[192:195], v[116:119]
	v_mfma_f32_16x16x32_bf16 v[112:115], v[180:183], v[192:195], v[112:115]
	v_mfma_f32_16x16x32_bf16 v[100:103], v[172:175], v[200:203], v[100:103]
	v_mfma_f32_16x16x32_bf16 v[96:99], v[180:183], v[200:203], v[96:99]
	v_mfma_f32_16x16x32_bf16 v[84:87], v[172:175], v[208:211], v[84:87]
	v_mfma_f32_16x16x32_bf16 v[80:83], v[180:183], v[208:211], v[80:83]
	v_mfma_f32_16x16x32_bf16 v[68:71], v[172:175], v[216:219], v[68:71]
	v_mfma_f32_16x16x32_bf16 v[64:67], v[180:183], v[216:219], v[64:67]
	v_mfma_f32_16x16x32_bf16 v[116:119], v[176:179], v[196:199], v[116:119]
	v_mfma_f32_16x16x32_bf16 v[112:115], v[184:187], v[196:199], v[112:115]
	v_mfma_f32_16x16x32_bf16 v[100:103], v[176:179], v[204:207], v[100:103]
	v_mfma_f32_16x16x32_bf16 v[96:99], v[184:187], v[204:207], v[96:99]
	v_mfma_f32_16x16x32_bf16 v[84:87], v[176:179], v[212:215], v[84:87]
	v_mfma_f32_16x16x32_bf16 v[80:83], v[184:187], v[212:215], v[80:83]
	v_mfma_f32_16x16x32_bf16 v[68:71], v[176:179], v[220:223], v[68:71]
	v_mfma_f32_16x16x32_bf16 v[64:67], v[184:187], v[220:223], v[64:67]
	s_setprio 0
	s_barrier
	s_add_i32 s36, s64, s42
	v_lshl_add_u64 v[188:189], v[188:189], 0, s[16:17]
	s_mov_b32 m0, s36
	ds_read_b128 v[192:195], v165 offset:49152
	ds_read_b128 v[196:199], v165 offset:50176
	ds_read_b128 v[200:203], v165 offset:51200
	ds_read_b128 v[204:207], v165 offset:52224
	ds_read_b128 v[208:211], v165 offset:53248
	ds_read_b128 v[212:215], v165 offset:54272
	ds_read_b128 v[216:219], v165 offset:55296
	ds_read_b128 v[220:223], v165 offset:56320
	global_load_lds_dwordx4 v[188:189], off
	s_add_i32 m0, s36, 0x2000
	s_add_u32 s34, s34, 0x40080
	v_lshl_add_u64 v[188:189], v[224:225], 0, s[16:17]
	s_addc_u32 s35, s35, 0
	s_add_i32 s36, s65, s42
	global_load_lds_dwordx4 v[188:189], off
	v_lshl_add_u64 v[188:189], s[34:35], 0, v[132:133]
	s_mov_b32 m0, s36
	s_nop 0
	global_load_lds_dwordx4 v[188:189], off
	v_lshl_add_u64 v[188:189], s[34:35], 0, v[128:129]
	s_add_i32 m0, s36, 0x2000
	s_nop 0
	global_load_lds_dwordx4 v[188:189], off
	v_lshl_add_u64 v[188:189], v[226:227], 0, s[16:17]
	s_mov_b32 m0, s49
	s_nop 0
	global_load_lds_dwordx4 v[188:189], off
	v_lshl_add_u64 v[188:189], v[228:229], 0, s[16:17]
	s_mov_b32 m0, s50
	s_nop 0
	global_load_lds_dwordx4 v[188:189], off
	s_waitcnt vmcnt(8)
	s_waitcnt lgkmcnt(0)
	s_barrier
	s_setprio 1
	s_waitcnt lgkmcnt(0)
	v_mfma_f32_16x16x32_bf16 v[60:63], v[150:153], v[192:195], v[60:63]
	v_mfma_f32_16x16x32_bf16 v[56:59], v[158:161], v[192:195], v[56:59]
	v_mfma_f32_16x16x32_bf16 v[44:47], v[150:153], v[200:203], v[44:47]
	v_mfma_f32_16x16x32_bf16 v[40:43], v[158:161], v[200:203], v[40:43]
	v_mfma_f32_16x16x32_bf16 v[28:31], v[150:153], v[208:211], v[28:31]
	v_mfma_f32_16x16x32_bf16 v[24:27], v[158:161], v[208:211], v[24:27]
	v_mfma_f32_16x16x32_bf16 v[12:15], v[150:153], v[216:219], v[12:15]
	v_mfma_f32_16x16x32_bf16 v[8:11], v[158:161], v[216:219], v[8:11]
	v_mfma_f32_16x16x32_bf16 v[60:63], v[154:157], v[196:199], v[60:63]
	v_mfma_f32_16x16x32_bf16 v[56:59], v[168:171], v[196:199], v[56:59]
	v_mfma_f32_16x16x32_bf16 v[44:47], v[154:157], v[204:207], v[44:47]
	v_mfma_f32_16x16x32_bf16 v[40:43], v[168:171], v[204:207], v[40:43]
	v_mfma_f32_16x16x32_bf16 v[28:31], v[154:157], v[212:215], v[28:31]
	v_mfma_f32_16x16x32_bf16 v[24:27], v[168:171], v[212:215], v[24:27]
	v_mfma_f32_16x16x32_bf16 v[12:15], v[154:157], v[220:223], v[12:15]
	v_mfma_f32_16x16x32_bf16 v[8:11], v[168:171], v[220:223], v[8:11]
	s_setprio 0
	s_setprio 1
	v_mfma_f32_16x16x32_bf16 v[52:55], v[172:175], v[192:195], v[52:55]
	v_mfma_f32_16x16x32_bf16 v[48:51], v[180:183], v[192:195], v[48:51]
	v_mfma_f32_16x16x32_bf16 v[36:39], v[172:175], v[200:203], v[36:39]
	v_mfma_f32_16x16x32_bf16 v[32:35], v[180:183], v[200:203], v[32:35]
	v_mfma_f32_16x16x32_bf16 v[20:23], v[172:175], v[208:211], v[20:23]
	v_mfma_f32_16x16x32_bf16 v[16:19], v[180:183], v[208:211], v[16:19]
	v_mfma_f32_16x16x32_bf16 v[4:7], v[172:175], v[216:219], v[4:7]
	v_mfma_f32_16x16x32_bf16 v[0:3], v[180:183], v[216:219], v[0:3]
	v_mfma_f32_16x16x32_bf16 v[52:55], v[176:179], v[196:199], v[52:55]
	v_mfma_f32_16x16x32_bf16 v[48:51], v[184:187], v[196:199], v[48:51]
	v_mfma_f32_16x16x32_bf16 v[36:39], v[176:179], v[204:207], v[36:39]
	v_mfma_f32_16x16x32_bf16 v[32:35], v[184:187], v[204:207], v[32:35]
	v_mfma_f32_16x16x32_bf16 v[20:23], v[176:179], v[212:215], v[20:23]
	v_mfma_f32_16x16x32_bf16 v[16:19], v[184:187], v[212:215], v[16:19]
	v_mfma_f32_16x16x32_bf16 v[4:7], v[176:179], v[220:223], v[4:7]
	v_mfma_f32_16x16x32_bf16 v[0:3], v[184:187], v[220:223], v[0:3]
	s_setprio 0
	s_add_i32 s63, s63, 2
	s_add_u32 s33, s33, 0x100
	s_addc_u32 s62, s62, 0
	s_add_u32 s30, s30, 0x100
	s_addc_u32 s31, s31, 0
	s_cmp_gt_u32 s63, 13
	s_barrier
	s_cbranch_scc0 .LBB0_1394
	s_and_b64 vcc, exec, s[18:19]
	s_cbranch_vccz .LBB0_1397
	s_barrier

.LBB0_1416:
	ds_read_b128 v[150:153], v163
	ds_read_b128 v[154:157], v163 offset:1024
	ds_read_b128 v[158:161], v163 offset:2048
	ds_read_b128 v[168:171], v163 offset:3072
	ds_read_b128 v[172:175], v164
	ds_read_b128 v[176:179], v164 offset:1024
	ds_read_b128 v[180:183], v164 offset:2048
	ds_read_b128 v[184:187], v164 offset:3072
	s_add_u32 s34, s30, 0xfffc0080
	s_addc_u32 s35, s31, -1
	s_cmp_eq_u32 s59, 12
	s_cselect_b32 s37, s21, s35
	s_cselect_b32 s36, s23, s34
	s_cselect_b32 s35, s25, s58
	s_cselect_b32 s34, s33, s57
	v_lshl_add_u64 v[188:189], s[30:31], 0, v[142:143]
	s_add_i32 m0, s45, 0xc000
	ds_read_b128 v[192:195], v165
	ds_read_b128 v[196:199], v165 offset:1024
	ds_read_b128 v[200:203], v165 offset:2048
	ds_read_b128 v[204:207], v165 offset:3072
	ds_read_b128 v[208:211], v165 offset:4096
	ds_read_b128 v[212:215], v165 offset:5120
	ds_read_b128 v[216:219], v165 offset:6144
	ds_read_b128 v[220:223], v165 offset:7168
	global_load_lds_dwordx4 v[188:189], off
	v_lshl_add_u64 v[188:189], s[30:31], 0, v[140:141]
	s_add_i32 m0, s45, 0xe000
	s_nop 0
	global_load_lds_dwordx4 v[188:189], off
	s_waitcnt vmcnt(8)
	s_waitcnt lgkmcnt(0)
	s_barrier
	s_setprio 1
	s_waitcnt lgkmcnt(0)
	v_mfma_f32_16x16x32_bf16 v[124:127], v[150:153], v[192:195], v[124:127]
	v_mfma_f32_16x16x32_bf16 v[120:123], v[158:161], v[192:195], v[120:123]
	v_mfma_f32_16x16x32_bf16 v[108:111], v[150:153], v[200:203], v[108:111]
	v_mfma_f32_16x16x32_bf16 v[104:107], v[158:161], v[200:203], v[104:107]
	v_mfma_f32_16x16x32_bf16 v[92:95], v[150:153], v[208:211], v[92:95]
	v_mfma_f32_16x16x32_bf16 v[88:91], v[158:161], v[208:211], v[88:91]
	v_mfma_f32_16x16x32_bf16 v[76:79], v[150:153], v[216:219], v[76:79]
	v_mfma_f32_16x16x32_bf16 v[72:75], v[158:161], v[216:219], v[72:75]
	v_mfma_f32_16x16x32_bf16 v[124:127], v[154:157], v[196:199], v[124:127]
	v_mfma_f32_16x16x32_bf16 v[120:123], v[168:171], v[196:199], v[120:123]
	v_mfma_f32_16x16x32_bf16 v[108:111], v[154:157], v[204:207], v[108:111]
	v_mfma_f32_16x16x32_bf16 v[104:107], v[168:171], v[204:207], v[104:107]
	v_mfma_f32_16x16x32_bf16 v[92:95], v[154:157], v[212:215], v[92:95]
	v_mfma_f32_16x16x32_bf16 v[88:91], v[168:171], v[212:215], v[88:91]
	v_mfma_f32_16x16x32_bf16 v[76:79], v[154:157], v[220:223], v[76:79]
	v_mfma_f32_16x16x32_bf16 v[72:75], v[168:171], v[220:223], v[72:75]
	s_setprio 0
	s_setprio 1
	v_mfma_f32_16x16x32_bf16 v[116:119], v[172:175], v[192:195], v[116:119]
	v_mfma_f32_16x16x32_bf16 v[112:115], v[180:183], v[192:195], v[112:115]
	v_mfma_f32_16x16x32_bf16 v[100:103], v[172:175], v[200:203], v[100:103]
	v_mfma_f32_16x16x32_bf16 v[96:99], v[180:183], v[200:203], v[96:99]
	v_mfma_f32_16x16x32_bf16 v[84:87], v[172:175], v[208:211], v[84:87]
	v_mfma_f32_16x16x32_bf16 v[80:83], v[180:183], v[208:211], v[80:83]
	v_mfma_f32_16x16x32_bf16 v[68:71], v[172:175], v[216:219], v[68:71]
	v_mfma_f32_16x16x32_bf16 v[64:67], v[180:183], v[216:219], v[64:67]
	v_mfma_f32_16x16x32_bf16 v[116:119], v[176:179], v[196:199], v[116:119]
	v_mfma_f32_16x16x32_bf16 v[112:115], v[184:187], v[196:199], v[112:115]
	v_mfma_f32_16x16x32_bf16 v[100:103], v[176:179], v[204:207], v[100:103]
	v_mfma_f32_16x16x32_bf16 v[96:99], v[184:187], v[204:207], v[96:99]
	v_mfma_f32_16x16x32_bf16 v[84:87], v[176:179], v[212:215], v[84:87]
	v_mfma_f32_16x16x32_bf16 v[80:83], v[184:187], v[212:215], v[80:83]
	v_mfma_f32_16x16x32_bf16 v[68:71], v[176:179], v[220:223], v[68:71]
	v_mfma_f32_16x16x32_bf16 v[64:67], v[184:187], v[220:223], v[64:67]
	s_setprio 0
	s_barrier
	s_add_i32 s60, s51, s42
	v_lshl_add_u64 v[188:189], s[34:35], 0, v[132:133]
	s_mov_b32 m0, s60
	ds_read_b128 v[192:195], v165 offset:16384
	ds_read_b128 v[196:199], v165 offset:17408
	ds_read_b128 v[200:203], v165 offset:18432
	ds_read_b128 v[204:207], v165 offset:19456
	ds_read_b128 v[208:211], v165 offset:20480
	ds_read_b128 v[212:215], v165 offset:21504
	ds_read_b128 v[216:219], v165 offset:22528
	ds_read_b128 v[220:223], v165 offset:23552
	global_load_lds_dwordx4 v[188:189], off
	s_add_i32 m0, s60, 0x2000
	s_add_u32 s60, s34, 0x40000
	v_lshl_add_u64 v[224:225], s[34:35], 0, v[128:129]
	s_addc_u32 s61, s35, 0
	s_add_i32 s62, s52, s42
	global_load_lds_dwordx4 v[224:225], off
	v_lshl_add_u64 v[226:227], s[60:61], 0, v[132:133]
	s_mov_b32 m0, s62
	v_lshl_add_u64 v[228:229], s[36:37], 0, v[130:131]
	global_load_lds_dwordx4 v[226:227], off
	v_lshl_add_u64 v[226:227], s[60:61], 0, v[128:129]
	s_add_i32 m0, s62, 0x2000
	s_nop 0
	global_load_lds_dwordx4 v[226:227], off
	v_lshl_add_u64 v[226:227], s[36:37], 0, v[134:135]
	s_mov_b32 m0, s45
	s_nop 0
	global_load_lds_dwordx4 v[226:227], off
	s_mov_b32 m0, s46
	s_nop 0
	global_load_lds_dwordx4 v[228:229], off
	s_waitcnt vmcnt(8)
	s_waitcnt lgkmcnt(0)
	s_barrier
	s_setprio 1
	s_waitcnt lgkmcnt(0)
	v_mfma_f32_16x16x32_bf16 v[60:63], v[150:153], v[192:195], v[60:63]
	v_mfma_f32_16x16x32_bf16 v[56:59], v[158:161], v[192:195], v[56:59]
	v_mfma_f32_16x16x32_bf16 v[44:47], v[150:153], v[200:203], v[44:47]
	v_mfma_f32_16x16x32_bf16 v[40:43], v[158:161], v[200:203], v[40:43]
	v_mfma_f32_16x16x32_bf16 v[28:31], v[150:153], v[208:211], v[28:31]
	v_mfma_f32_16x16x32_bf16 v[24:27], v[158:161], v[208:211], v[24:27]
	v_mfma_f32_16x16x32_bf16 v[12:15], v[150:153], v[216:219], v[12:15]
	v_mfma_f32_16x16x32_bf16 v[8:11], v[158:161], v[216:219], v[8:11]
	v_mfma_f32_16x16x32_bf16 v[60:63], v[154:157], v[196:199], v[60:63]
	v_mfma_f32_16x16x32_bf16 v[56:59], v[168:171], v[196:199], v[56:59]
	v_mfma_f32_16x16x32_bf16 v[44:47], v[154:157], v[204:207], v[44:47]
	v_mfma_f32_16x16x32_bf16 v[40:43], v[168:171], v[204:207], v[40:43]
	v_mfma_f32_16x16x32_bf16 v[28:31], v[154:157], v[212:215], v[28:31]
	v_mfma_f32_16x16x32_bf16 v[24:27], v[168:171], v[212:215], v[24:27]
	v_mfma_f32_16x16x32_bf16 v[12:15], v[154:157], v[220:223], v[12:15]
	v_mfma_f32_16x16x32_bf16 v[8:11], v[168:171], v[220:223], v[8:11]
	s_setprio 0
	s_setprio 1
	v_mfma_f32_16x16x32_bf16 v[52:55], v[172:175], v[192:195], v[52:55]
	v_mfma_f32_16x16x32_bf16 v[48:51], v[180:183], v[192:195], v[48:51]
	v_mfma_f32_16x16x32_bf16 v[36:39], v[172:175], v[200:203], v[36:39]
	v_mfma_f32_16x16x32_bf16 v[32:35], v[180:183], v[200:203], v[32:35]
	v_mfma_f32_16x16x32_bf16 v[20:23], v[172:175], v[208:211], v[20:23]
	v_mfma_f32_16x16x32_bf16 v[16:19], v[180:183], v[208:211], v[16:19]
	v_mfma_f32_16x16x32_bf16 v[4:7], v[172:175], v[216:219], v[4:7]
	v_mfma_f32_16x16x32_bf16 v[0:3], v[180:183], v[216:219], v[0:3]
	v_mfma_f32_16x16x32_bf16 v[52:55], v[176:179], v[196:199], v[52:55]
	v_mfma_f32_16x16x32_bf16 v[48:51], v[184:187], v[196:199], v[48:51]
	v_mfma_f32_16x16x32_bf16 v[36:39], v[176:179], v[204:207], v[36:39]
	v_mfma_f32_16x16x32_bf16 v[32:35], v[184:187], v[204:207], v[32:35]
	v_mfma_f32_16x16x32_bf16 v[20:23], v[176:179], v[212:215], v[20:23]
	v_mfma_f32_16x16x32_bf16 v[16:19], v[184:187], v[212:215], v[16:19]
	v_mfma_f32_16x16x32_bf16 v[4:7], v[176:179], v[220:223], v[4:7]
	v_mfma_f32_16x16x32_bf16 v[0:3], v[184:187], v[220:223], v[0:3]
	s_setprio 0
	s_barrier
	s_add_i32 s60, 0, 0x18000
	v_add_u32_e32 v136, s60, v162
	s_add_i32 s61, 0, 0x1c000
	ds_read_b128 v[150:153], v136
	ds_read_b128 v[154:157], v136 offset:1024
	ds_read_b128 v[158:161], v136 offset:2048
	ds_read_b128 v[168:171], v136 offset:3072
	v_add_u32_e32 v136, s61, v162
	ds_read_b128 v[172:175], v136
	ds_read_b128 v[176:179], v136 offset:1024
	ds_read_b128 v[180:183], v136 offset:2048
	ds_read_b128 v[184:187], v136 offset:3072
	s_add_u32 s36, s36, 0x40000
	s_addc_u32 s37, s37, 0
	s_mov_b32 m0, s47
	v_lshl_add_u64 v[230:231], s[36:37], 0, v[134:135]
	ds_read_b128 v[192:195], v165 offset:32768
	ds_read_b128 v[196:199], v165 offset:33792
	ds_read_b128 v[200:203], v165 offset:34816
	ds_read_b128 v[204:207], v165 offset:35840
	ds_read_b128 v[208:211], v165 offset:36864
	ds_read_b128 v[212:215], v165 offset:37888
	ds_read_b128 v[216:219], v165 offset:38912
	ds_read_b128 v[220:223], v165 offset:39936
	global_load_lds_dwordx4 v[230:231], off
	v_lshl_add_u64 v[230:231], s[36:37], 0, v[130:131]
	s_mov_b32 m0, s48
	s_nop 0
	global_load_lds_dwordx4 v[230:231], off
	s_waitcnt vmcnt(8)
	s_waitcnt lgkmcnt(0)
	s_barrier
	s_setprio 1
	s_waitcnt lgkmcnt(0)
	v_mfma_f32_16x16x32_bf16 v[124:127], v[150:153], v[192:195], v[124:127]
	v_mfma_f32_16x16x32_bf16 v[120:123], v[158:161], v[192:195], v[120:123]
	v_mfma_f32_16x16x32_bf16 v[108:111], v[150:153], v[200:203], v[108:111]
	v_mfma_f32_16x16x32_bf16 v[104:107], v[158:161], v[200:203], v[104:107]
	v_mfma_f32_16x16x32_bf16 v[92:95], v[150:153], v[208:211], v[92:95]
	v_mfma_f32_16x16x32_bf16 v[88:91], v[158:161], v[208:211], v[88:91]
	v_mfma_f32_16x16x32_bf16 v[76:79], v[150:153], v[216:219], v[76:79]
	v_mfma_f32_16x16x32_bf16 v[72:75], v[158:161], v[216:219], v[72:75]
	v_mfma_f32_16x16x32_bf16 v[124:127], v[154:157], v[196:199], v[124:127]
	v_mfma_f32_16x16x32_bf16 v[120:123], v[168:171], v[196:199], v[120:123]
	v_mfma_f32_16x16x32_bf16 v[108:111], v[154:157], v[204:207], v[108:111]
	v_mfma_f32_16x16x32_bf16 v[104:107], v[168:171], v[204:207], v[104:107]
	v_mfma_f32_16x16x32_bf16 v[92:95], v[154:157], v[212:215], v[92:95]
	v_mfma_f32_16x16x32_bf16 v[88:91], v[168:171], v[212:215], v[88:91]
	v_mfma_f32_16x16x32_bf16 v[76:79], v[154:157], v[220:223], v[76:79]
	v_mfma_f32_16x16x32_bf16 v[72:75], v[168:171], v[220:223], v[72:75]
	s_setprio 0
	s_setprio 1
	v_mfma_f32_16x16x32_bf16 v[116:119], v[172:175], v[192:195], v[116:119]
	v_mfma_f32_16x16x32_bf16 v[112:115], v[180:183], v[192:195], v[112:115]
	v_mfma_f32_16x16x32_bf16 v[100:103], v[172:175], v[200:203], v[100:103]
	v_mfma_f32_16x16x32_bf16 v[96:99], v[180:183], v[200:203], v[96:99]
	v_mfma_f32_16x16x32_bf16 v[84:87], v[172:175], v[208:211], v[84:87]
	v_mfma_f32_16x16x32_bf16 v[80:83], v[180:183], v[208:211], v[80:83]
	v_mfma_f32_16x16x32_bf16 v[68:71], v[172:175], v[216:219], v[68:71]
	v_mfma_f32_16x16x32_bf16 v[64:67], v[180:183], v[216:219], v[64:67]
	v_mfma_f32_16x16x32_bf16 v[116:119], v[176:179], v[196:199], v[116:119]
	v_mfma_f32_16x16x32_bf16 v[112:115], v[184:187], v[196:199], v[112:115]
	v_mfma_f32_16x16x32_bf16 v[100:103], v[176:179], v[204:207], v[100:103]
	v_mfma_f32_16x16x32_bf16 v[96:99], v[184:187], v[204:207], v[96:99]
	v_mfma_f32_16x16x32_bf16 v[84:87], v[176:179], v[212:215], v[84:87]
	v_mfma_f32_16x16x32_bf16 v[80:83], v[184:187], v[212:215], v[80:83]
	v_mfma_f32_16x16x32_bf16 v[68:71], v[176:179], v[220:223], v[68:71]
	v_mfma_f32_16x16x32_bf16 v[64:67], v[184:187], v[220:223], v[64:67]
	s_setprio 0
	s_barrier
	s_add_i32 s36, s60, s42
	v_lshl_add_u64 v[188:189], v[188:189], 0, s[16:17]
	s_mov_b32 m0, s36
	ds_read_b128 v[192:195], v165 offset:49152
	ds_read_b128 v[196:199], v165 offset:50176
	ds_read_b128 v[200:203], v165 offset:51200
	ds_read_b128 v[204:207], v165 offset:52224
	ds_read_b128 v[208:211], v165 offset:53248
	ds_read_b128 v[212:215], v165 offset:54272
	ds_read_b128 v[216:219], v165 offset:55296
	ds_read_b128 v[220:223], v165 offset:56320
	global_load_lds_dwordx4 v[188:189], off
	s_add_i32 m0, s36, 0x2000
	s_add_u32 s34, s34, 0x40080
	v_lshl_add_u64 v[188:189], v[224:225], 0, s[16:17]
	s_addc_u32 s35, s35, 0
	s_add_i32 s36, s61, s42
	global_load_lds_dwordx4 v[188:189], off
	v_lshl_add_u64 v[188:189], s[34:35], 0, v[132:133]
	s_mov_b32 m0, s36
	s_nop 0
	global_load_lds_dwordx4 v[188:189], off
	v_lshl_add_u64 v[188:189], s[34:35], 0, v[128:129]
	s_add_i32 m0, s36, 0x2000
	s_nop 0
	global_load_lds_dwordx4 v[188:189], off
	v_lshl_add_u64 v[188:189], v[226:227], 0, s[16:17]
	s_mov_b32 m0, s49
	s_nop 0
	global_load_lds_dwordx4 v[188:189], off
	v_lshl_add_u64 v[188:189], v[228:229], 0, s[16:17]
	s_mov_b32 m0, s50
	s_nop 0
	global_load_lds_dwordx4 v[188:189], off
	s_waitcnt vmcnt(8)
	s_waitcnt lgkmcnt(0)
	s_barrier
	s_setprio 1
	s_waitcnt lgkmcnt(0)
	v_mfma_f32_16x16x32_bf16 v[60:63], v[150:153], v[192:195], v[60:63]
	v_mfma_f32_16x16x32_bf16 v[56:59], v[158:161], v[192:195], v[56:59]
	v_mfma_f32_16x16x32_bf16 v[44:47], v[150:153], v[200:203], v[44:47]
	v_mfma_f32_16x16x32_bf16 v[40:43], v[158:161], v[200:203], v[40:43]
	v_mfma_f32_16x16x32_bf16 v[28:31], v[150:153], v[208:211], v[28:31]
	v_mfma_f32_16x16x32_bf16 v[24:27], v[158:161], v[208:211], v[24:27]
	v_mfma_f32_16x16x32_bf16 v[12:15], v[150:153], v[216:219], v[12:15]
	v_mfma_f32_16x16x32_bf16 v[8:11], v[158:161], v[216:219], v[8:11]
	v_mfma_f32_16x16x32_bf16 v[60:63], v[154:157], v[196:199], v[60:63]
	v_mfma_f32_16x16x32_bf16 v[56:59], v[168:171], v[196:199], v[56:59]
	v_mfma_f32_16x16x32_bf16 v[44:47], v[154:157], v[204:207], v[44:47]
	v_mfma_f32_16x16x32_bf16 v[40:43], v[168:171], v[204:207], v[40:43]
	v_mfma_f32_16x16x32_bf16 v[28:31], v[154:157], v[212:215], v[28:31]
	v_mfma_f32_16x16x32_bf16 v[24:27], v[168:171], v[212:215], v[24:27]
	v_mfma_f32_16x16x32_bf16 v[12:15], v[154:157], v[220:223], v[12:15]
	v_mfma_f32_16x16x32_bf16 v[8:11], v[168:171], v[220:223], v[8:11]
	s_setprio 0
	s_setprio 1
	v_mfma_f32_16x16x32_bf16 v[52:55], v[172:175], v[192:195], v[52:55]
	v_mfma_f32_16x16x32_bf16 v[48:51], v[180:183], v[192:195], v[48:51]
	v_mfma_f32_16x16x32_bf16 v[36:39], v[172:175], v[200:203], v[36:39]
	v_mfma_f32_16x16x32_bf16 v[32:35], v[180:183], v[200:203], v[32:35]
	v_mfma_f32_16x16x32_bf16 v[20:23], v[172:175], v[208:211], v[20:23]
	v_mfma_f32_16x16x32_bf16 v[16:19], v[180:183], v[208:211], v[16:19]
	v_mfma_f32_16x16x32_bf16 v[4:7], v[172:175], v[216:219], v[4:7]
	v_mfma_f32_16x16x32_bf16 v[0:3], v[180:183], v[216:219], v[0:3]
	v_mfma_f32_16x16x32_bf16 v[52:55], v[176:179], v[196:199], v[52:55]
	v_mfma_f32_16x16x32_bf16 v[48:51], v[184:187], v[196:199], v[48:51]
	v_mfma_f32_16x16x32_bf16 v[36:39], v[176:179], v[204:207], v[36:39]
	v_mfma_f32_16x16x32_bf16 v[32:35], v[184:187], v[204:207], v[32:35]
	v_mfma_f32_16x16x32_bf16 v[20:23], v[176:179], v[212:215], v[20:23]
	v_mfma_f32_16x16x32_bf16 v[16:19], v[184:187], v[212:215], v[16:19]
	v_mfma_f32_16x16x32_bf16 v[4:7], v[176:179], v[220:223], v[4:7]
	v_mfma_f32_16x16x32_bf16 v[0:3], v[184:187], v[220:223], v[0:3]
	s_setprio 0
	s_add_i32 s59, s59, 2
	s_add_u32 s57, s57, 0x100
	s_addc_u32 s58, s58, 0
	s_add_u32 s30, s30, 0x100
	s_addc_u32 s31, s31, 0
	s_cmp_gt_u32 s59, 13
	s_barrier
	s_cbranch_scc0 .LBB0_1416
	v_lshl_add_u32 v214, s0, 8, v139
	v_ashrrev_i32_e32 v215, 31, v214
	v_lshl_add_u64 v[212:213], v[214:215], 2, s[10:11]
	global_load_dword v204, v[212:213], off
	global_load_dword v205, v[212:213], off offset:64
	global_load_dword v206, v[212:213], off offset:128
	global_load_dword v207, v[212:213], off offset:192
	global_load_dword v208, v[212:213], off offset:512
	global_load_dword v209, v[212:213], off offset:576
	global_load_dword v210, v[212:213], off offset:640
	global_load_dword v211, v[212:213], off offset:704
	s_and_b64 vcc, exec, s[18:19]
	s_cbranch_vccz .LBB0_1419
	s_barrier

.LBB0_1497:
	ds_read_b128 v[128:131], v171
	ds_read_b128 v[132:135], v171 offset:1024
	ds_read_b128 v[136:139], v171 offset:2048
	ds_read_b128 v[140:143], v171 offset:3072
	ds_read_b128 v[156:159], v172
	ds_read_b128 v[160:163], v172 offset:1024
	ds_read_b128 v[164:167], v172 offset:2048
	ds_read_b128 v[176:179], v172 offset:3072
	s_add_u32 s26, s24, 0x100
	s_addc_u32 s27, s25, 0
	s_cmp_eq_u32 s55, 40
	s_cselect_b32 s31, s7, s27
	s_cselect_b32 s30, s6, s26
	s_cselect_b32 s29, s23, s54
	s_cselect_b32 s28, s22, s53
	v_lshl_add_u64 v[188:189], s[24:25], 0, v[150:151]
	s_add_i32 m0, s36, 0xc000
	ds_read_b128 v[180:183], v173
	ds_read_b128 v[184:187], v173 offset:1024
	ds_read_b128 v[192:195], v173 offset:2048
	ds_read_b128 v[196:199], v173 offset:3072
	ds_read_b128 v[200:203], v173 offset:4096
	ds_read_b128 v[204:207], v173 offset:5120
	ds_read_b128 v[208:211], v173 offset:6144
	ds_read_b128 v[212:215], v173 offset:7168
	global_load_lds_dwordx4 v[188:189], off
	v_lshl_add_u64 v[188:189], s[24:25], 0, v[148:149]
	s_add_i32 m0, s36, 0xe000
	s_nop 0
	global_load_lds_dwordx4 v[188:189], off
	s_waitcnt vmcnt(8)
	s_waitcnt lgkmcnt(0)
	s_barrier
	s_setprio 1
	s_waitcnt lgkmcnt(0)
	v_mfma_f32_16x16x32_bf16 v[124:127], v[128:131], v[180:183], v[124:127]
	v_mfma_f32_16x16x32_bf16 v[120:123], v[136:139], v[180:183], v[120:123]
	v_mfma_f32_16x16x32_bf16 v[108:111], v[128:131], v[192:195], v[108:111]
	v_mfma_f32_16x16x32_bf16 v[104:107], v[136:139], v[192:195], v[104:107]
	v_mfma_f32_16x16x32_bf16 v[92:95], v[128:131], v[200:203], v[92:95]
	v_mfma_f32_16x16x32_bf16 v[88:91], v[136:139], v[200:203], v[88:91]
	v_mfma_f32_16x16x32_bf16 v[76:79], v[128:131], v[208:211], v[76:79]
	v_mfma_f32_16x16x32_bf16 v[72:75], v[136:139], v[208:211], v[72:75]
	v_mfma_f32_16x16x32_bf16 v[124:127], v[132:135], v[184:187], v[124:127]
	v_mfma_f32_16x16x32_bf16 v[120:123], v[140:143], v[184:187], v[120:123]
	v_mfma_f32_16x16x32_bf16 v[108:111], v[132:135], v[196:199], v[108:111]
	v_mfma_f32_16x16x32_bf16 v[104:107], v[140:143], v[196:199], v[104:107]
	v_mfma_f32_16x16x32_bf16 v[92:95], v[132:135], v[204:207], v[92:95]
	v_mfma_f32_16x16x32_bf16 v[88:91], v[140:143], v[204:207], v[88:91]
	v_mfma_f32_16x16x32_bf16 v[76:79], v[132:135], v[212:215], v[76:79]
	v_mfma_f32_16x16x32_bf16 v[72:75], v[140:143], v[212:215], v[72:75]
	s_setprio 0
	s_setprio 1
	v_mfma_f32_16x16x32_bf16 v[116:119], v[156:159], v[180:183], v[116:119]
	v_mfma_f32_16x16x32_bf16 v[112:115], v[164:167], v[180:183], v[112:115]
	v_mfma_f32_16x16x32_bf16 v[100:103], v[156:159], v[192:195], v[100:103]
	v_mfma_f32_16x16x32_bf16 v[96:99], v[164:167], v[192:195], v[96:99]
	v_mfma_f32_16x16x32_bf16 v[84:87], v[156:159], v[200:203], v[84:87]
	v_mfma_f32_16x16x32_bf16 v[80:83], v[164:167], v[200:203], v[80:83]
	v_mfma_f32_16x16x32_bf16 v[68:71], v[156:159], v[208:211], v[68:71]
	v_mfma_f32_16x16x32_bf16 v[64:67], v[164:167], v[208:211], v[64:67]
	v_mfma_f32_16x16x32_bf16 v[116:119], v[160:163], v[184:187], v[116:119]
	v_mfma_f32_16x16x32_bf16 v[112:115], v[176:179], v[184:187], v[112:115]
	v_mfma_f32_16x16x32_bf16 v[100:103], v[160:163], v[196:199], v[100:103]
	v_mfma_f32_16x16x32_bf16 v[96:99], v[176:179], v[196:199], v[96:99]
	v_mfma_f32_16x16x32_bf16 v[84:87], v[160:163], v[204:207], v[84:87]
	v_mfma_f32_16x16x32_bf16 v[80:83], v[176:179], v[204:207], v[80:83]
	v_mfma_f32_16x16x32_bf16 v[68:71], v[160:163], v[212:215], v[68:71]
	v_mfma_f32_16x16x32_bf16 v[64:67], v[176:179], v[212:215], v[64:67]
	s_setprio 0
	s_barrier
	s_add_i32 s24, s47, s35
	v_lshl_add_u64 v[188:189], s[28:29], 0, v[144:145]
	s_mov_b32 m0, s24
	ds_read_b128 v[180:183], v173 offset:16384
	ds_read_b128 v[184:187], v173 offset:17408
	ds_read_b128 v[192:195], v173 offset:18432
	ds_read_b128 v[196:199], v173 offset:19456
	ds_read_b128 v[200:203], v173 offset:20480
	ds_read_b128 v[204:207], v173 offset:21504
	ds_read_b128 v[208:211], v173 offset:22528
	ds_read_b128 v[212:215], v173 offset:23552
	global_load_lds_dwordx4 v[188:189], off
	s_add_i32 m0, s24, 0x2000
	s_add_u32 s24, s28, 0xb0000
	v_lshl_add_u64 v[216:217], s[28:29], 0, v[146:147]
	s_addc_u32 s25, s29, 0
	s_add_i32 s56, s48, s35
	global_load_lds_dwordx4 v[216:217], off
	v_lshl_add_u64 v[218:219], s[24:25], 0, v[144:145]
	s_mov_b32 m0, s56
	v_lshl_add_u64 v[220:221], s[30:31], 0, v[146:147]
	global_load_lds_dwordx4 v[218:219], off
	v_lshl_add_u64 v[218:219], s[24:25], 0, v[146:147]
	s_add_i32 m0, s56, 0x2000
	s_nop 0
	global_load_lds_dwordx4 v[218:219], off
	v_lshl_add_u64 v[218:219], s[30:31], 0, v[144:145]
	s_mov_b32 m0, s36
	s_nop 0
	global_load_lds_dwordx4 v[218:219], off
	s_mov_b32 m0, s37
	s_nop 0
	global_load_lds_dwordx4 v[220:221], off
	s_waitcnt vmcnt(8)
	s_waitcnt lgkmcnt(0)
	s_barrier
	s_setprio 1
	s_waitcnt lgkmcnt(0)
	v_mfma_f32_16x16x32_bf16 v[60:63], v[128:131], v[180:183], v[60:63]
	v_mfma_f32_16x16x32_bf16 v[56:59], v[136:139], v[180:183], v[56:59]
	v_mfma_f32_16x16x32_bf16 v[44:47], v[128:131], v[192:195], v[44:47]
	v_mfma_f32_16x16x32_bf16 v[40:43], v[136:139], v[192:195], v[40:43]
	v_mfma_f32_16x16x32_bf16 v[28:31], v[128:131], v[200:203], v[28:31]
	v_mfma_f32_16x16x32_bf16 v[24:27], v[136:139], v[200:203], v[24:27]
	v_mfma_f32_16x16x32_bf16 v[12:15], v[128:131], v[208:211], v[12:15]
	v_mfma_f32_16x16x32_bf16 v[8:11], v[136:139], v[208:211], v[8:11]
	v_mfma_f32_16x16x32_bf16 v[60:63], v[132:135], v[184:187], v[60:63]
	v_mfma_f32_16x16x32_bf16 v[56:59], v[140:143], v[184:187], v[56:59]
	v_mfma_f32_16x16x32_bf16 v[44:47], v[132:135], v[196:199], v[44:47]
	v_mfma_f32_16x16x32_bf16 v[40:43], v[140:143], v[196:199], v[40:43]
	v_mfma_f32_16x16x32_bf16 v[28:31], v[132:135], v[204:207], v[28:31]
	v_mfma_f32_16x16x32_bf16 v[24:27], v[140:143], v[204:207], v[24:27]
	v_mfma_f32_16x16x32_bf16 v[12:15], v[132:135], v[212:215], v[12:15]
	v_mfma_f32_16x16x32_bf16 v[8:11], v[140:143], v[212:215], v[8:11]
	s_setprio 0
	s_setprio 1
	v_mfma_f32_16x16x32_bf16 v[52:55], v[156:159], v[180:183], v[52:55]
	v_mfma_f32_16x16x32_bf16 v[48:51], v[164:167], v[180:183], v[48:51]
	v_mfma_f32_16x16x32_bf16 v[36:39], v[156:159], v[192:195], v[36:39]
	v_mfma_f32_16x16x32_bf16 v[32:35], v[164:167], v[192:195], v[32:35]
	v_mfma_f32_16x16x32_bf16 v[20:23], v[156:159], v[200:203], v[20:23]
	v_mfma_f32_16x16x32_bf16 v[16:19], v[164:167], v[200:203], v[16:19]
	v_mfma_f32_16x16x32_bf16 v[4:7], v[156:159], v[208:211], v[4:7]
	v_mfma_f32_16x16x32_bf16 v[0:3], v[164:167], v[208:211], v[0:3]
	v_mfma_f32_16x16x32_bf16 v[52:55], v[160:163], v[184:187], v[52:55]
	v_mfma_f32_16x16x32_bf16 v[48:51], v[176:179], v[184:187], v[48:51]
	v_mfma_f32_16x16x32_bf16 v[36:39], v[160:163], v[196:199], v[36:39]
	v_mfma_f32_16x16x32_bf16 v[32:35], v[176:179], v[196:199], v[32:35]
	v_mfma_f32_16x16x32_bf16 v[20:23], v[160:163], v[204:207], v[20:23]
	v_mfma_f32_16x16x32_bf16 v[16:19], v[176:179], v[204:207], v[16:19]
	v_mfma_f32_16x16x32_bf16 v[4:7], v[160:163], v[212:215], v[4:7]
	v_mfma_f32_16x16x32_bf16 v[0:3], v[176:179], v[212:215], v[0:3]
	s_setprio 0
	s_barrier
	s_add_i32 s56, 0, 0x18000
	s_add_i32 s57, 0, 0x1c000
	v_add_u32_e32 v140, s56, v169
	v_add_u32_e32 v175, s57, v169
	ds_read_b128 v[128:131], v140
	ds_read_b128 v[132:135], v140 offset:1024
	ds_read_b128 v[136:139], v140 offset:2048
	ds_read_b128 v[140:143], v140 offset:3072
	ds_read_b128 v[156:159], v175
	ds_read_b128 v[160:163], v175 offset:1024
	ds_read_b128 v[164:167], v175 offset:2048
	ds_read_b128 v[176:179], v175 offset:3072
	s_add_u32 s24, s30, 0xb0000
	s_addc_u32 s25, s31, 0
	s_mov_b32 m0, s38
	v_lshl_add_u64 v[222:223], s[24:25], 0, v[144:145]
	ds_read_b128 v[180:183], v173 offset:32768
	ds_read_b128 v[184:187], v173 offset:33792
	ds_read_b128 v[192:195], v173 offset:34816
	ds_read_b128 v[196:199], v173 offset:35840
	ds_read_b128 v[200:203], v173 offset:36864
	ds_read_b128 v[204:207], v173 offset:37888
	ds_read_b128 v[208:211], v173 offset:38912
	ds_read_b128 v[212:215], v173 offset:39936
	global_load_lds_dwordx4 v[222:223], off
	v_lshl_add_u64 v[222:223], s[24:25], 0, v[146:147]
	s_mov_b32 m0, s39
	s_nop 0
	global_load_lds_dwordx4 v[222:223], off
	s_waitcnt vmcnt(8)
	s_waitcnt lgkmcnt(0)
	s_barrier
	s_setprio 1
	s_waitcnt lgkmcnt(0)
	v_mfma_f32_16x16x32_bf16 v[124:127], v[128:131], v[180:183], v[124:127]
	v_mfma_f32_16x16x32_bf16 v[120:123], v[136:139], v[180:183], v[120:123]
	v_mfma_f32_16x16x32_bf16 v[108:111], v[128:131], v[192:195], v[108:111]
	v_mfma_f32_16x16x32_bf16 v[104:107], v[136:139], v[192:195], v[104:107]
	v_mfma_f32_16x16x32_bf16 v[92:95], v[128:131], v[200:203], v[92:95]
	v_mfma_f32_16x16x32_bf16 v[88:91], v[136:139], v[200:203], v[88:91]
	v_mfma_f32_16x16x32_bf16 v[76:79], v[128:131], v[208:211], v[76:79]
	v_mfma_f32_16x16x32_bf16 v[72:75], v[136:139], v[208:211], v[72:75]
	v_mfma_f32_16x16x32_bf16 v[124:127], v[132:135], v[184:187], v[124:127]
	v_mfma_f32_16x16x32_bf16 v[120:123], v[140:143], v[184:187], v[120:123]
	v_mfma_f32_16x16x32_bf16 v[108:111], v[132:135], v[196:199], v[108:111]
	v_mfma_f32_16x16x32_bf16 v[104:107], v[140:143], v[196:199], v[104:107]
	v_mfma_f32_16x16x32_bf16 v[92:95], v[132:135], v[204:207], v[92:95]
	v_mfma_f32_16x16x32_bf16 v[88:91], v[140:143], v[204:207], v[88:91]
	v_mfma_f32_16x16x32_bf16 v[76:79], v[132:135], v[212:215], v[76:79]
	v_mfma_f32_16x16x32_bf16 v[72:75], v[140:143], v[212:215], v[72:75]
	s_setprio 0
	s_setprio 1
	v_mfma_f32_16x16x32_bf16 v[116:119], v[156:159], v[180:183], v[116:119]
	v_mfma_f32_16x16x32_bf16 v[112:115], v[164:167], v[180:183], v[112:115]
	v_mfma_f32_16x16x32_bf16 v[100:103], v[156:159], v[192:195], v[100:103]
	v_mfma_f32_16x16x32_bf16 v[96:99], v[164:167], v[192:195], v[96:99]
	v_mfma_f32_16x16x32_bf16 v[84:87], v[156:159], v[200:203], v[84:87]
	v_mfma_f32_16x16x32_bf16 v[80:83], v[164:167], v[200:203], v[80:83]
	v_mfma_f32_16x16x32_bf16 v[68:71], v[156:159], v[208:211], v[68:71]
	v_mfma_f32_16x16x32_bf16 v[64:67], v[164:167], v[208:211], v[64:67]
	v_mfma_f32_16x16x32_bf16 v[116:119], v[160:163], v[184:187], v[116:119]
	v_mfma_f32_16x16x32_bf16 v[112:115], v[176:179], v[184:187], v[112:115]
	v_mfma_f32_16x16x32_bf16 v[100:103], v[160:163], v[196:199], v[100:103]
	v_mfma_f32_16x16x32_bf16 v[96:99], v[176:179], v[196:199], v[96:99]
	v_mfma_f32_16x16x32_bf16 v[84:87], v[160:163], v[204:207], v[84:87]
	v_mfma_f32_16x16x32_bf16 v[80:83], v[176:179], v[204:207], v[80:83]
	v_mfma_f32_16x16x32_bf16 v[68:71], v[160:163], v[212:215], v[68:71]
	v_mfma_f32_16x16x32_bf16 v[64:67], v[176:179], v[212:215], v[64:67]
	s_setprio 0
	s_barrier
	s_add_i32 s24, s56, s35
	v_lshl_add_u64 v[188:189], v[188:189], 0, s[18:19]
	s_mov_b32 m0, s24
	ds_read_b128 v[180:183], v173 offset:49152
	ds_read_b128 v[184:187], v173 offset:50176
	ds_read_b128 v[192:195], v173 offset:51200
	ds_read_b128 v[196:199], v173 offset:52224
	ds_read_b128 v[200:203], v173 offset:53248
	ds_read_b128 v[204:207], v173 offset:54272
	ds_read_b128 v[208:211], v173 offset:55296
	ds_read_b128 v[212:215], v173 offset:56320
	global_load_lds_dwordx4 v[188:189], off
	s_add_i32 m0, s24, 0x2000
	s_add_u32 s24, s28, 0xb0080
	v_lshl_add_u64 v[188:189], v[216:217], 0, s[18:19]
	s_addc_u32 s25, s29, 0
	s_add_i32 s28, s57, s35
	global_load_lds_dwordx4 v[188:189], off
	v_lshl_add_u64 v[188:189], s[24:25], 0, v[144:145]
	s_mov_b32 m0, s28
	s_nop 0
	global_load_lds_dwordx4 v[188:189], off
	v_lshl_add_u64 v[188:189], s[24:25], 0, v[146:147]
	s_add_i32 m0, s28, 0x2000
	s_nop 0
	global_load_lds_dwordx4 v[188:189], off
	v_lshl_add_u64 v[188:189], v[218:219], 0, s[18:19]
	s_mov_b32 m0, s41
	s_nop 0
	global_load_lds_dwordx4 v[188:189], off
	v_lshl_add_u64 v[188:189], v[220:221], 0, s[18:19]
	s_mov_b32 m0, s42
	s_nop 0
	global_load_lds_dwordx4 v[188:189], off
	s_waitcnt vmcnt(8)
	s_waitcnt lgkmcnt(0)
	s_barrier
	s_setprio 1
	s_waitcnt lgkmcnt(0)
	v_mfma_f32_16x16x32_bf16 v[60:63], v[128:131], v[180:183], v[60:63]
	v_mfma_f32_16x16x32_bf16 v[56:59], v[136:139], v[180:183], v[56:59]
	v_mfma_f32_16x16x32_bf16 v[44:47], v[128:131], v[192:195], v[44:47]
	v_mfma_f32_16x16x32_bf16 v[40:43], v[136:139], v[192:195], v[40:43]
	v_mfma_f32_16x16x32_bf16 v[28:31], v[128:131], v[200:203], v[28:31]
	v_mfma_f32_16x16x32_bf16 v[24:27], v[136:139], v[200:203], v[24:27]
	v_mfma_f32_16x16x32_bf16 v[12:15], v[128:131], v[208:211], v[12:15]
	v_mfma_f32_16x16x32_bf16 v[8:11], v[136:139], v[208:211], v[8:11]
	v_mfma_f32_16x16x32_bf16 v[60:63], v[132:135], v[184:187], v[60:63]
	v_mfma_f32_16x16x32_bf16 v[56:59], v[140:143], v[184:187], v[56:59]
	v_mfma_f32_16x16x32_bf16 v[44:47], v[132:135], v[196:199], v[44:47]
	v_mfma_f32_16x16x32_bf16 v[40:43], v[140:143], v[196:199], v[40:43]
	v_mfma_f32_16x16x32_bf16 v[28:31], v[132:135], v[204:207], v[28:31]
	v_mfma_f32_16x16x32_bf16 v[24:27], v[140:143], v[204:207], v[24:27]
	v_mfma_f32_16x16x32_bf16 v[12:15], v[132:135], v[212:215], v[12:15]
	v_mfma_f32_16x16x32_bf16 v[8:11], v[140:143], v[212:215], v[8:11]
	s_setprio 0
	s_setprio 1
	v_mfma_f32_16x16x32_bf16 v[52:55], v[156:159], v[180:183], v[52:55]
	v_mfma_f32_16x16x32_bf16 v[48:51], v[164:167], v[180:183], v[48:51]
	v_mfma_f32_16x16x32_bf16 v[36:39], v[156:159], v[192:195], v[36:39]
	v_mfma_f32_16x16x32_bf16 v[32:35], v[164:167], v[192:195], v[32:35]
	v_mfma_f32_16x16x32_bf16 v[20:23], v[156:159], v[200:203], v[20:23]
	v_mfma_f32_16x16x32_bf16 v[16:19], v[164:167], v[200:203], v[16:19]
	v_mfma_f32_16x16x32_bf16 v[4:7], v[156:159], v[208:211], v[4:7]
	v_mfma_f32_16x16x32_bf16 v[0:3], v[164:167], v[208:211], v[0:3]
	v_mfma_f32_16x16x32_bf16 v[52:55], v[160:163], v[184:187], v[52:55]
	v_mfma_f32_16x16x32_bf16 v[48:51], v[176:179], v[184:187], v[48:51]
	v_mfma_f32_16x16x32_bf16 v[36:39], v[160:163], v[196:199], v[36:39]
	v_mfma_f32_16x16x32_bf16 v[32:35], v[176:179], v[196:199], v[32:35]
	v_mfma_f32_16x16x32_bf16 v[20:23], v[160:163], v[204:207], v[20:23]
	v_mfma_f32_16x16x32_bf16 v[16:19], v[176:179], v[204:207], v[16:19]
	v_mfma_f32_16x16x32_bf16 v[4:7], v[160:163], v[212:215], v[4:7]
	v_mfma_f32_16x16x32_bf16 v[0:3], v[176:179], v[212:215], v[0:3]
	s_setprio 0
	s_add_i32 s55, s55, 2
	s_add_u32 s53, s53, 0x100
	s_addc_u32 s54, s54, 0
	s_cmp_gt_u32 s55, 41
	s_mov_b64 s[24:25], s[26:27]
	s_barrier
	s_cbranch_scc0 .LBB0_1497
	v_mbcnt_lo_u32_b32 v235, -1, 0
	v_mbcnt_hi_u32_b32 v235, -1, v235
	v_lshrrev_b32_e32 v236, 2, v235
	v_and_b32_e32 v237, 3, v235
	v_lshl_add_u32 v232, v237, 4, v236
	v_lshlrev_b32_e32 v232, 2, v232
	v_and_b32_e32 v233, -16, v168
	v_or_b32_e32 v233, v233, v236
	v_lshlrev_b32_e32 v237, 2, v237
	v_and_b32_e32 v234, -13, v170
	v_or_b32_e32 v234, v234, v237
	v_lshl_add_u32 v158, s52, 8, v233
	v_lshl_or_b32 v156, s51, 8, v234
	v_ashrrev_i32_e32 v159, 31, v158
	v_lshlrev_b64 v[128:129], 12, v[158:159]
	v_ashrrev_i32_e32 v157, 31, v156
	v_lshl_add_u64 v[128:129], s[10:11], 0, v[128:129]
	v_lshlrev_b64 v[130:131], 2, v[156:157]
	v_lshl_add_u64 v[188:189], v[128:129], 0, v[130:131]
	global_load_dwordx4 v[164:167], v[188:189], off
	global_load_dwordx4 v[176:179], v[188:189], off offset:64
	global_load_dwordx4 v[180:183], v[188:189], off offset:512
	global_load_dwordx4 v[184:187], v[188:189], off offset:576
	v_or_b32_e32 v160, 16, v158
	v_ashrrev_i32_e32 v161, 31, v160
	v_lshlrev_b64 v[128:129], 12, v[160:161]
	v_lshl_add_u64 v[128:129], s[10:11], 0, v[128:129]
	v_lshl_add_u64 v[162:163], v[128:129], 0, v[130:131]
	global_load_dwordx4 v[140:143], v[162:163], off
	global_load_dwordx4 v[136:139], v[162:163], off offset:64
	global_load_dwordx4 v[132:135], v[162:163], off offset:512
	global_load_dwordx4 v[128:131], v[162:163], off offset:576
	v_lshlrev_b64 v[192:193], 11, v[158:159]
	v_lshl_add_u64 v[192:193], s[14:15], 0, v[192:193]
	v_and_b32_e32 v191, 64, v174
	v_lshl_add_u64 v[192:193], v[156:157], 1, v[192:193]
	v_xor_b32_e32 v175, 1, v174
	v_add_u32_e32 v191, 64, v191
	v_cmp_lt_i32_e32 vcc, v175, v191
	v_xor_b32_e32 v194, 2, v174
	ds_bpermute_b32 v127, v232, v127
	ds_bpermute_b32 v126, v232, v126
	ds_bpermute_b32 v125, v232, v125
	ds_bpermute_b32 v124, v232, v124
	ds_bpermute_b32 v123, v232, v123
	ds_bpermute_b32 v122, v232, v122
	ds_bpermute_b32 v121, v232, v121
	ds_bpermute_b32 v120, v232, v120
	ds_bpermute_b32 v119, v232, v119
	ds_bpermute_b32 v118, v232, v118
	ds_bpermute_b32 v117, v232, v117
	ds_bpermute_b32 v116, v232, v116
	ds_bpermute_b32 v115, v232, v115
	ds_bpermute_b32 v114, v232, v114
	ds_bpermute_b32 v113, v232, v113
	ds_bpermute_b32 v112, v232, v112
	ds_bpermute_b32 v111, v232, v111
	ds_bpermute_b32 v110, v232, v110
	ds_bpermute_b32 v109, v232, v109
	ds_bpermute_b32 v108, v232, v108
	ds_bpermute_b32 v107, v232, v107
	ds_bpermute_b32 v106, v232, v106
	ds_bpermute_b32 v105, v232, v105
	ds_bpermute_b32 v104, v232, v104
	ds_bpermute_b32 v103, v232, v103
	ds_bpermute_b32 v102, v232, v102
	ds_bpermute_b32 v101, v232, v101
	ds_bpermute_b32 v100, v232, v100
	ds_bpermute_b32 v99, v232, v99
	ds_bpermute_b32 v98, v232, v98
	ds_bpermute_b32 v97, v232, v97
	ds_bpermute_b32 v96, v232, v96
	ds_bpermute_b32 v95, v232, v95
	ds_bpermute_b32 v94, v232, v94
	ds_bpermute_b32 v93, v232, v93
	ds_bpermute_b32 v92, v232, v92
	ds_bpermute_b32 v91, v232, v91
	ds_bpermute_b32 v90, v232, v90
	ds_bpermute_b32 v89, v232, v89
	ds_bpermute_b32 v88, v232, v88
	ds_bpermute_b32 v87, v232, v87
	ds_bpermute_b32 v86, v232, v86
	ds_bpermute_b32 v85, v232, v85
	ds_bpermute_b32 v84, v232, v84
	ds_bpermute_b32 v83, v232, v83
	ds_bpermute_b32 v82, v232, v82
	ds_bpermute_b32 v81, v232, v81
	ds_bpermute_b32 v80, v232, v80
	ds_bpermute_b32 v79, v232, v79
	ds_bpermute_b32 v78, v232, v78
	ds_bpermute_b32 v77, v232, v77
	ds_bpermute_b32 v76, v232, v76
	ds_bpermute_b32 v75, v232, v75
	ds_bpermute_b32 v74, v232, v74
	ds_bpermute_b32 v73, v232, v73
	ds_bpermute_b32 v72, v232, v72
	ds_bpermute_b32 v71, v232, v71
	ds_bpermute_b32 v70, v232, v70
	ds_bpermute_b32 v69, v232, v69
	ds_bpermute_b32 v68, v232, v68
	ds_bpermute_b32 v67, v232, v67
	ds_bpermute_b32 v66, v232, v66
	ds_bpermute_b32 v65, v232, v65
	ds_bpermute_b32 v64, v232, v64
	ds_bpermute_b32 v63, v232, v63
	ds_bpermute_b32 v62, v232, v62
	ds_bpermute_b32 v61, v232, v61
	ds_bpermute_b32 v60, v232, v60
	ds_bpermute_b32 v59, v232, v59
	ds_bpermute_b32 v58, v232, v58
	ds_bpermute_b32 v57, v232, v57
	ds_bpermute_b32 v56, v232, v56
	ds_bpermute_b32 v55, v232, v55
	ds_bpermute_b32 v54, v232, v54
	ds_bpermute_b32 v53, v232, v53
	ds_bpermute_b32 v52, v232, v52
	ds_bpermute_b32 v51, v232, v51
	ds_bpermute_b32 v50, v232, v50
	ds_bpermute_b32 v49, v232, v49
	ds_bpermute_b32 v48, v232, v48
	ds_bpermute_b32 v47, v232, v47
	ds_bpermute_b32 v46, v232, v46
	ds_bpermute_b32 v45, v232, v45
	ds_bpermute_b32 v44, v232, v44
	ds_bpermute_b32 v43, v232, v43
	ds_bpermute_b32 v42, v232, v42
	ds_bpermute_b32 v41, v232, v41
	ds_bpermute_b32 v40, v232, v40
	ds_bpermute_b32 v39, v232, v39
	ds_bpermute_b32 v38, v232, v38
	ds_bpermute_b32 v37, v232, v37
	ds_bpermute_b32 v36, v232, v36
	ds_bpermute_b32 v35, v232, v35
	ds_bpermute_b32 v34, v232, v34
	ds_bpermute_b32 v33, v232, v33
	ds_bpermute_b32 v32, v232, v32
	ds_bpermute_b32 v31, v232, v31
	ds_bpermute_b32 v30, v232, v30
	ds_bpermute_b32 v29, v232, v29
	ds_bpermute_b32 v28, v232, v28
	ds_bpermute_b32 v27, v232, v27
	ds_bpermute_b32 v26, v232, v26
	ds_bpermute_b32 v25, v232, v25
	ds_bpermute_b32 v24, v232, v24
	ds_bpermute_b32 v23, v232, v23
	ds_bpermute_b32 v22, v232, v22
	ds_bpermute_b32 v21, v232, v21
	ds_bpermute_b32 v20, v232, v20
	ds_bpermute_b32 v19, v232, v19
	ds_bpermute_b32 v18, v232, v18
	ds_bpermute_b32 v17, v232, v17
	ds_bpermute_b32 v16, v232, v16
	ds_bpermute_b32 v15, v232, v15
	ds_bpermute_b32 v14, v232, v14
	ds_bpermute_b32 v13, v232, v13
	ds_bpermute_b32 v12, v232, v12
	ds_bpermute_b32 v11, v232, v11
	ds_bpermute_b32 v10, v232, v10
	ds_bpermute_b32 v9, v232, v9
	ds_bpermute_b32 v8, v232, v8
	ds_bpermute_b32 v7, v232, v7
	ds_bpermute_b32 v6, v232, v6
	ds_bpermute_b32 v5, v232, v5
	ds_bpermute_b32 v4, v232, v4
	ds_bpermute_b32 v3, v232, v3
	ds_bpermute_b32 v2, v232, v2
	ds_bpermute_b32 v1, v232, v1
	ds_bpermute_b32 v0, v232, v0
	s_waitcnt lgkmcnt(0)
	s_waitcnt lgkmcnt(0)
	s_cmp_eq_u64 s[20:21], 0
	s_cbranch_scc1 .LBB0_1500
	s_barrier

.LBB0_1530:
	ds_read_b128 v[150:153], v163
	ds_read_b128 v[154:157], v163 offset:1024
	ds_read_b128 v[158:161], v163 offset:2048
	ds_read_b128 v[168:171], v163 offset:3072
	ds_read_b128 v[172:175], v164
	ds_read_b128 v[176:179], v164 offset:1024
	ds_read_b128 v[180:183], v164 offset:2048
	ds_read_b128 v[184:187], v164 offset:3072
	s_add_u32 s30, s0, 0xfffc0080
	s_addc_u32 s31, s1, -1
	s_cmp_eq_u32 s60, 12
	s_cselect_b32 s35, s4, s31
	s_cselect_b32 s34, s21, s30
	s_cselect_b32 s31, s23, s59
	s_cselect_b32 s30, s25, s58
	v_lshl_add_u64 v[188:189], s[0:1], 0, v[142:143]
	s_add_i32 m0, s42, 0xc000
	ds_read_b128 v[192:195], v165
	ds_read_b128 v[196:199], v165 offset:1024
	ds_read_b128 v[200:203], v165 offset:2048
	ds_read_b128 v[204:207], v165 offset:3072
	ds_read_b128 v[208:211], v165 offset:4096
	ds_read_b128 v[212:215], v165 offset:5120
	ds_read_b128 v[216:219], v165 offset:6144
	ds_read_b128 v[220:223], v165 offset:7168
	global_load_lds_dwordx4 v[188:189], off
	v_lshl_add_u64 v[188:189], s[0:1], 0, v[140:141]
	s_add_i32 m0, s42, 0xe000
	s_nop 0
	global_load_lds_dwordx4 v[188:189], off
	s_waitcnt vmcnt(8)
	s_waitcnt lgkmcnt(0)
	s_barrier
	s_setprio 1
	s_waitcnt lgkmcnt(0)
	v_mfma_f32_16x16x32_bf16 v[124:127], v[150:153], v[192:195], v[124:127]
	v_mfma_f32_16x16x32_bf16 v[120:123], v[158:161], v[192:195], v[120:123]
	v_mfma_f32_16x16x32_bf16 v[108:111], v[150:153], v[200:203], v[108:111]
	v_mfma_f32_16x16x32_bf16 v[104:107], v[158:161], v[200:203], v[104:107]
	v_mfma_f32_16x16x32_bf16 v[92:95], v[150:153], v[208:211], v[92:95]
	v_mfma_f32_16x16x32_bf16 v[88:91], v[158:161], v[208:211], v[88:91]
	v_mfma_f32_16x16x32_bf16 v[76:79], v[150:153], v[216:219], v[76:79]
	v_mfma_f32_16x16x32_bf16 v[72:75], v[158:161], v[216:219], v[72:75]
	v_mfma_f32_16x16x32_bf16 v[124:127], v[154:157], v[196:199], v[124:127]
	v_mfma_f32_16x16x32_bf16 v[120:123], v[168:171], v[196:199], v[120:123]
	v_mfma_f32_16x16x32_bf16 v[108:111], v[154:157], v[204:207], v[108:111]
	v_mfma_f32_16x16x32_bf16 v[104:107], v[168:171], v[204:207], v[104:107]
	v_mfma_f32_16x16x32_bf16 v[92:95], v[154:157], v[212:215], v[92:95]
	v_mfma_f32_16x16x32_bf16 v[88:91], v[168:171], v[212:215], v[88:91]
	v_mfma_f32_16x16x32_bf16 v[76:79], v[154:157], v[220:223], v[76:79]
	v_mfma_f32_16x16x32_bf16 v[72:75], v[168:171], v[220:223], v[72:75]
	s_setprio 0
	s_setprio 1
	v_mfma_f32_16x16x32_bf16 v[116:119], v[172:175], v[192:195], v[116:119]
	v_mfma_f32_16x16x32_bf16 v[112:115], v[180:183], v[192:195], v[112:115]
	v_mfma_f32_16x16x32_bf16 v[100:103], v[172:175], v[200:203], v[100:103]
	v_mfma_f32_16x16x32_bf16 v[96:99], v[180:183], v[200:203], v[96:99]
	v_mfma_f32_16x16x32_bf16 v[84:87], v[172:175], v[208:211], v[84:87]
	v_mfma_f32_16x16x32_bf16 v[80:83], v[180:183], v[208:211], v[80:83]
	v_mfma_f32_16x16x32_bf16 v[68:71], v[172:175], v[216:219], v[68:71]
	v_mfma_f32_16x16x32_bf16 v[64:67], v[180:183], v[216:219], v[64:67]
	v_mfma_f32_16x16x32_bf16 v[116:119], v[176:179], v[196:199], v[116:119]
	v_mfma_f32_16x16x32_bf16 v[112:115], v[184:187], v[196:199], v[112:115]
	v_mfma_f32_16x16x32_bf16 v[100:103], v[176:179], v[204:207], v[100:103]
	v_mfma_f32_16x16x32_bf16 v[96:99], v[184:187], v[204:207], v[96:99]
	v_mfma_f32_16x16x32_bf16 v[84:87], v[176:179], v[212:215], v[84:87]
	v_mfma_f32_16x16x32_bf16 v[80:83], v[184:187], v[212:215], v[80:83]
	v_mfma_f32_16x16x32_bf16 v[68:71], v[176:179], v[220:223], v[68:71]
	v_mfma_f32_16x16x32_bf16 v[64:67], v[184:187], v[220:223], v[64:67]
	s_setprio 0
	s_barrier
	s_add_i32 s61, s48, s41
	v_lshl_add_u64 v[188:189], s[30:31], 0, v[132:133]
	s_mov_b32 m0, s61
	ds_read_b128 v[192:195], v165 offset:16384
	ds_read_b128 v[196:199], v165 offset:17408
	ds_read_b128 v[200:203], v165 offset:18432
	ds_read_b128 v[204:207], v165 offset:19456
	ds_read_b128 v[208:211], v165 offset:20480
	ds_read_b128 v[212:215], v165 offset:21504
	ds_read_b128 v[216:219], v165 offset:22528
	ds_read_b128 v[220:223], v165 offset:23552
	global_load_lds_dwordx4 v[188:189], off
	s_add_i32 m0, s61, 0x2000
	s_add_u32 s62, s30, 0x40000
	v_lshl_add_u64 v[224:225], s[30:31], 0, v[128:129]
	s_addc_u32 s63, s31, 0
	s_add_i32 s61, s49, s41
	global_load_lds_dwordx4 v[224:225], off
	v_lshl_add_u64 v[226:227], s[62:63], 0, v[132:133]
	s_mov_b32 m0, s61
	v_lshl_add_u64 v[228:229], s[34:35], 0, v[130:131]
	global_load_lds_dwordx4 v[226:227], off
	v_lshl_add_u64 v[226:227], s[62:63], 0, v[128:129]
	s_add_i32 m0, s61, 0x2000
	s_nop 0
	global_load_lds_dwordx4 v[226:227], off
	v_lshl_add_u64 v[226:227], s[34:35], 0, v[134:135]
	s_mov_b32 m0, s42
	s_nop 0
	global_load_lds_dwordx4 v[226:227], off
	s_mov_b32 m0, s43
	s_nop 0
	global_load_lds_dwordx4 v[228:229], off
	s_waitcnt vmcnt(8)
	s_waitcnt lgkmcnt(0)
	s_barrier
	s_setprio 1
	s_waitcnt lgkmcnt(0)
	v_mfma_f32_16x16x32_bf16 v[60:63], v[150:153], v[192:195], v[60:63]
	v_mfma_f32_16x16x32_bf16 v[56:59], v[158:161], v[192:195], v[56:59]
	v_mfma_f32_16x16x32_bf16 v[44:47], v[150:153], v[200:203], v[44:47]
	v_mfma_f32_16x16x32_bf16 v[40:43], v[158:161], v[200:203], v[40:43]
	v_mfma_f32_16x16x32_bf16 v[28:31], v[150:153], v[208:211], v[28:31]
	v_mfma_f32_16x16x32_bf16 v[24:27], v[158:161], v[208:211], v[24:27]
	v_mfma_f32_16x16x32_bf16 v[12:15], v[150:153], v[216:219], v[12:15]
	v_mfma_f32_16x16x32_bf16 v[8:11], v[158:161], v[216:219], v[8:11]
	v_mfma_f32_16x16x32_bf16 v[60:63], v[154:157], v[196:199], v[60:63]
	v_mfma_f32_16x16x32_bf16 v[56:59], v[168:171], v[196:199], v[56:59]
	v_mfma_f32_16x16x32_bf16 v[44:47], v[154:157], v[204:207], v[44:47]
	v_mfma_f32_16x16x32_bf16 v[40:43], v[168:171], v[204:207], v[40:43]
	v_mfma_f32_16x16x32_bf16 v[28:31], v[154:157], v[212:215], v[28:31]
	v_mfma_f32_16x16x32_bf16 v[24:27], v[168:171], v[212:215], v[24:27]
	v_mfma_f32_16x16x32_bf16 v[12:15], v[154:157], v[220:223], v[12:15]
	v_mfma_f32_16x16x32_bf16 v[8:11], v[168:171], v[220:223], v[8:11]
	s_setprio 0
	s_setprio 1
	v_mfma_f32_16x16x32_bf16 v[52:55], v[172:175], v[192:195], v[52:55]
	v_mfma_f32_16x16x32_bf16 v[48:51], v[180:183], v[192:195], v[48:51]
	v_mfma_f32_16x16x32_bf16 v[36:39], v[172:175], v[200:203], v[36:39]
	v_mfma_f32_16x16x32_bf16 v[32:35], v[180:183], v[200:203], v[32:35]
	v_mfma_f32_16x16x32_bf16 v[20:23], v[172:175], v[208:211], v[20:23]
	v_mfma_f32_16x16x32_bf16 v[16:19], v[180:183], v[208:211], v[16:19]
	v_mfma_f32_16x16x32_bf16 v[4:7], v[172:175], v[216:219], v[4:7]
	v_mfma_f32_16x16x32_bf16 v[0:3], v[180:183], v[216:219], v[0:3]
	v_mfma_f32_16x16x32_bf16 v[52:55], v[176:179], v[196:199], v[52:55]
	v_mfma_f32_16x16x32_bf16 v[48:51], v[184:187], v[196:199], v[48:51]
	v_mfma_f32_16x16x32_bf16 v[36:39], v[176:179], v[204:207], v[36:39]
	v_mfma_f32_16x16x32_bf16 v[32:35], v[184:187], v[204:207], v[32:35]
	v_mfma_f32_16x16x32_bf16 v[20:23], v[176:179], v[212:215], v[20:23]
	v_mfma_f32_16x16x32_bf16 v[16:19], v[184:187], v[212:215], v[16:19]
	v_mfma_f32_16x16x32_bf16 v[4:7], v[176:179], v[220:223], v[4:7]
	v_mfma_f32_16x16x32_bf16 v[0:3], v[184:187], v[220:223], v[0:3]
	s_setprio 0
	s_barrier
	s_add_i32 s61, 0, 0x18000
	v_add_u32_e32 v136, s61, v162
	s_add_i32 s62, 0, 0x1c000
	ds_read_b128 v[150:153], v136
	ds_read_b128 v[154:157], v136 offset:1024
	ds_read_b128 v[158:161], v136 offset:2048
	ds_read_b128 v[168:171], v136 offset:3072
	v_add_u32_e32 v136, s62, v162
	ds_read_b128 v[172:175], v136
	ds_read_b128 v[176:179], v136 offset:1024
	ds_read_b128 v[180:183], v136 offset:2048
	ds_read_b128 v[184:187], v136 offset:3072
	s_add_u32 s34, s34, 0x40000
	s_addc_u32 s35, s35, 0
	s_mov_b32 m0, s44
	v_lshl_add_u64 v[230:231], s[34:35], 0, v[134:135]
	ds_read_b128 v[192:195], v165 offset:32768
	ds_read_b128 v[196:199], v165 offset:33792
	ds_read_b128 v[200:203], v165 offset:34816
	ds_read_b128 v[204:207], v165 offset:35840
	ds_read_b128 v[208:211], v165 offset:36864
	ds_read_b128 v[212:215], v165 offset:37888
	ds_read_b128 v[216:219], v165 offset:38912
	ds_read_b128 v[220:223], v165 offset:39936
	global_load_lds_dwordx4 v[230:231], off
	v_lshl_add_u64 v[230:231], s[34:35], 0, v[130:131]
	s_mov_b32 m0, s45
	s_nop 0
	global_load_lds_dwordx4 v[230:231], off
	s_waitcnt vmcnt(8)
	s_waitcnt lgkmcnt(0)
	s_barrier
	s_setprio 1
	s_waitcnt lgkmcnt(0)
	v_mfma_f32_16x16x32_bf16 v[124:127], v[150:153], v[192:195], v[124:127]
	v_mfma_f32_16x16x32_bf16 v[120:123], v[158:161], v[192:195], v[120:123]
	v_mfma_f32_16x16x32_bf16 v[108:111], v[150:153], v[200:203], v[108:111]
	v_mfma_f32_16x16x32_bf16 v[104:107], v[158:161], v[200:203], v[104:107]
	v_mfma_f32_16x16x32_bf16 v[92:95], v[150:153], v[208:211], v[92:95]
	v_mfma_f32_16x16x32_bf16 v[88:91], v[158:161], v[208:211], v[88:91]
	v_mfma_f32_16x16x32_bf16 v[76:79], v[150:153], v[216:219], v[76:79]
	v_mfma_f32_16x16x32_bf16 v[72:75], v[158:161], v[216:219], v[72:75]
	v_mfma_f32_16x16x32_bf16 v[124:127], v[154:157], v[196:199], v[124:127]
	v_mfma_f32_16x16x32_bf16 v[120:123], v[168:171], v[196:199], v[120:123]
	v_mfma_f32_16x16x32_bf16 v[108:111], v[154:157], v[204:207], v[108:111]
	v_mfma_f32_16x16x32_bf16 v[104:107], v[168:171], v[204:207], v[104:107]
	v_mfma_f32_16x16x32_bf16 v[92:95], v[154:157], v[212:215], v[92:95]
	v_mfma_f32_16x16x32_bf16 v[88:91], v[168:171], v[212:215], v[88:91]
	v_mfma_f32_16x16x32_bf16 v[76:79], v[154:157], v[220:223], v[76:79]
	v_mfma_f32_16x16x32_bf16 v[72:75], v[168:171], v[220:223], v[72:75]
	s_setprio 0
	s_setprio 1
	v_mfma_f32_16x16x32_bf16 v[116:119], v[172:175], v[192:195], v[116:119]
	v_mfma_f32_16x16x32_bf16 v[112:115], v[180:183], v[192:195], v[112:115]
	v_mfma_f32_16x16x32_bf16 v[100:103], v[172:175], v[200:203], v[100:103]
	v_mfma_f32_16x16x32_bf16 v[96:99], v[180:183], v[200:203], v[96:99]
	v_mfma_f32_16x16x32_bf16 v[84:87], v[172:175], v[208:211], v[84:87]
	v_mfma_f32_16x16x32_bf16 v[80:83], v[180:183], v[208:211], v[80:83]
	v_mfma_f32_16x16x32_bf16 v[68:71], v[172:175], v[216:219], v[68:71]
	v_mfma_f32_16x16x32_bf16 v[64:67], v[180:183], v[216:219], v[64:67]
	v_mfma_f32_16x16x32_bf16 v[116:119], v[176:179], v[196:199], v[116:119]
	v_mfma_f32_16x16x32_bf16 v[112:115], v[184:187], v[196:199], v[112:115]
	v_mfma_f32_16x16x32_bf16 v[100:103], v[176:179], v[204:207], v[100:103]
	v_mfma_f32_16x16x32_bf16 v[96:99], v[184:187], v[204:207], v[96:99]
	v_mfma_f32_16x16x32_bf16 v[84:87], v[176:179], v[212:215], v[84:87]
	v_mfma_f32_16x16x32_bf16 v[80:83], v[184:187], v[212:215], v[80:83]
	v_mfma_f32_16x16x32_bf16 v[68:71], v[176:179], v[220:223], v[68:71]
	v_mfma_f32_16x16x32_bf16 v[64:67], v[184:187], v[220:223], v[64:67]
	s_setprio 0
	s_barrier
	s_add_i32 s34, s61, s41
	v_lshl_add_u64 v[188:189], v[188:189], 0, s[16:17]
	s_mov_b32 m0, s34
	ds_read_b128 v[192:195], v165 offset:49152
	ds_read_b128 v[196:199], v165 offset:50176
	ds_read_b128 v[200:203], v165 offset:51200
	ds_read_b128 v[204:207], v165 offset:52224
	ds_read_b128 v[208:211], v165 offset:53248
	ds_read_b128 v[212:215], v165 offset:54272
	ds_read_b128 v[216:219], v165 offset:55296
	ds_read_b128 v[220:223], v165 offset:56320
	global_load_lds_dwordx4 v[188:189], off
	s_add_i32 m0, s34, 0x2000
	s_add_u32 s30, s30, 0x40080
	v_lshl_add_u64 v[188:189], v[224:225], 0, s[16:17]
	s_addc_u32 s31, s31, 0
	s_add_i32 s34, s62, s41
	global_load_lds_dwordx4 v[188:189], off
	v_lshl_add_u64 v[188:189], s[30:31], 0, v[132:133]
	s_mov_b32 m0, s34
	s_nop 0
	global_load_lds_dwordx4 v[188:189], off
	v_lshl_add_u64 v[188:189], s[30:31], 0, v[128:129]
	s_add_i32 m0, s34, 0x2000
	s_nop 0
	global_load_lds_dwordx4 v[188:189], off
	v_lshl_add_u64 v[188:189], v[226:227], 0, s[16:17]
	s_mov_b32 m0, s46
	s_nop 0
	global_load_lds_dwordx4 v[188:189], off
	v_lshl_add_u64 v[188:189], v[228:229], 0, s[16:17]
	s_mov_b32 m0, s47
	s_nop 0
	global_load_lds_dwordx4 v[188:189], off
	s_waitcnt vmcnt(8)
	s_waitcnt lgkmcnt(0)
	s_barrier
	s_setprio 1
	s_waitcnt lgkmcnt(0)
	v_mfma_f32_16x16x32_bf16 v[60:63], v[150:153], v[192:195], v[60:63]
	v_mfma_f32_16x16x32_bf16 v[56:59], v[158:161], v[192:195], v[56:59]
	v_mfma_f32_16x16x32_bf16 v[44:47], v[150:153], v[200:203], v[44:47]
	v_mfma_f32_16x16x32_bf16 v[40:43], v[158:161], v[200:203], v[40:43]
	v_mfma_f32_16x16x32_bf16 v[28:31], v[150:153], v[208:211], v[28:31]
	v_mfma_f32_16x16x32_bf16 v[24:27], v[158:161], v[208:211], v[24:27]
	v_mfma_f32_16x16x32_bf16 v[12:15], v[150:153], v[216:219], v[12:15]
	v_mfma_f32_16x16x32_bf16 v[8:11], v[158:161], v[216:219], v[8:11]
	v_mfma_f32_16x16x32_bf16 v[60:63], v[154:157], v[196:199], v[60:63]
	v_mfma_f32_16x16x32_bf16 v[56:59], v[168:171], v[196:199], v[56:59]
	v_mfma_f32_16x16x32_bf16 v[44:47], v[154:157], v[204:207], v[44:47]
	v_mfma_f32_16x16x32_bf16 v[40:43], v[168:171], v[204:207], v[40:43]
	v_mfma_f32_16x16x32_bf16 v[28:31], v[154:157], v[212:215], v[28:31]
	v_mfma_f32_16x16x32_bf16 v[24:27], v[168:171], v[212:215], v[24:27]
	v_mfma_f32_16x16x32_bf16 v[12:15], v[154:157], v[220:223], v[12:15]
	v_mfma_f32_16x16x32_bf16 v[8:11], v[168:171], v[220:223], v[8:11]
	s_setprio 0
	s_setprio 1
	v_mfma_f32_16x16x32_bf16 v[52:55], v[172:175], v[192:195], v[52:55]
	v_mfma_f32_16x16x32_bf16 v[48:51], v[180:183], v[192:195], v[48:51]
	v_mfma_f32_16x16x32_bf16 v[36:39], v[172:175], v[200:203], v[36:39]
	v_mfma_f32_16x16x32_bf16 v[32:35], v[180:183], v[200:203], v[32:35]
	v_mfma_f32_16x16x32_bf16 v[20:23], v[172:175], v[208:211], v[20:23]
	v_mfma_f32_16x16x32_bf16 v[16:19], v[180:183], v[208:211], v[16:19]
	v_mfma_f32_16x16x32_bf16 v[4:7], v[172:175], v[216:219], v[4:7]
	v_mfma_f32_16x16x32_bf16 v[0:3], v[180:183], v[216:219], v[0:3]
	v_mfma_f32_16x16x32_bf16 v[52:55], v[176:179], v[196:199], v[52:55]
	v_mfma_f32_16x16x32_bf16 v[48:51], v[184:187], v[196:199], v[48:51]
	v_mfma_f32_16x16x32_bf16 v[36:39], v[176:179], v[204:207], v[36:39]
	v_mfma_f32_16x16x32_bf16 v[32:35], v[184:187], v[204:207], v[32:35]
	v_mfma_f32_16x16x32_bf16 v[20:23], v[176:179], v[212:215], v[20:23]
	v_mfma_f32_16x16x32_bf16 v[16:19], v[184:187], v[212:215], v[16:19]
	v_mfma_f32_16x16x32_bf16 v[4:7], v[176:179], v[220:223], v[4:7]
	v_mfma_f32_16x16x32_bf16 v[0:3], v[184:187], v[220:223], v[0:3]
	s_setprio 0
	s_add_i32 s60, s60, 2
	s_add_u32 s58, s58, 0x100
	s_addc_u32 s59, s59, 0
	s_add_u32 s0, s0, 0x100
	s_addc_u32 s1, s1, 0
	s_cmp_gt_u32 s60, 13
	s_barrier
	s_cbranch_scc0 .LBB0_1530
	s_and_b64 vcc, exec, s[18:19]
	s_cbranch_vccz .LBB0_1533
	s_barrier

.LBB0_1605:
	ds_read_b128 v[146:149], v152
	ds_read_b128 v[156:159], v152 offset:1024
	ds_read_b128 v[160:163], v152 offset:2048
	ds_read_b128 v[164:167], v152 offset:3072
	ds_read_b128 v[168:171], v153
	ds_read_b128 v[172:175], v153 offset:1024
	ds_read_b128 v[176:179], v153 offset:2048
	ds_read_b128 v[180:183], v153 offset:3072
	s_add_u32 s36, s34, 0xfffc0080
	s_addc_u32 s37, s35, -1
	s_cmp_eq_u32 s66, 12
	s_cselect_b32 s39, s27, s37
	s_cselect_b32 s38, s62, s36
	s_cselect_b32 s37, s25, s65
	s_cselect_b32 s36, s63, s64
	v_lshl_add_u64 v[188:189], s[34:35], 0, v[140:141]
	s_add_i32 m0, s46, 0xc000
	ds_read_b128 v[184:187], v154
	ds_read_b128 v[192:195], v154 offset:1024
	ds_read_b128 v[196:199], v154 offset:2048
	ds_read_b128 v[200:203], v154 offset:3072
	ds_read_b128 v[204:207], v154 offset:4096
	ds_read_b128 v[208:211], v154 offset:5120
	ds_read_b128 v[212:215], v154 offset:6144
	ds_read_b128 v[216:219], v154 offset:7168
	global_load_lds_dwordx4 v[188:189], off
	v_lshl_add_u64 v[188:189], s[34:35], 0, v[138:139]
	s_add_i32 m0, s46, 0xe000
	s_nop 0
	global_load_lds_dwordx4 v[188:189], off
	s_waitcnt vmcnt(8)
	s_waitcnt lgkmcnt(0)
	s_barrier
	s_setprio 1
	s_waitcnt lgkmcnt(0)
	v_mfma_f32_16x16x32_bf16 v[124:127], v[146:149], v[184:187], v[124:127]
	v_mfma_f32_16x16x32_bf16 v[120:123], v[160:163], v[184:187], v[120:123]
	v_mfma_f32_16x16x32_bf16 v[108:111], v[146:149], v[196:199], v[108:111]
	v_mfma_f32_16x16x32_bf16 v[104:107], v[160:163], v[196:199], v[104:107]
	v_mfma_f32_16x16x32_bf16 v[92:95], v[146:149], v[204:207], v[92:95]
	v_mfma_f32_16x16x32_bf16 v[88:91], v[160:163], v[204:207], v[88:91]
	v_mfma_f32_16x16x32_bf16 v[76:79], v[146:149], v[212:215], v[76:79]
	v_mfma_f32_16x16x32_bf16 v[72:75], v[160:163], v[212:215], v[72:75]
	v_mfma_f32_16x16x32_bf16 v[124:127], v[156:159], v[192:195], v[124:127]
	v_mfma_f32_16x16x32_bf16 v[120:123], v[164:167], v[192:195], v[120:123]
	v_mfma_f32_16x16x32_bf16 v[108:111], v[156:159], v[200:203], v[108:111]
	v_mfma_f32_16x16x32_bf16 v[104:107], v[164:167], v[200:203], v[104:107]
	v_mfma_f32_16x16x32_bf16 v[92:95], v[156:159], v[208:211], v[92:95]
	v_mfma_f32_16x16x32_bf16 v[88:91], v[164:167], v[208:211], v[88:91]
	v_mfma_f32_16x16x32_bf16 v[76:79], v[156:159], v[216:219], v[76:79]
	v_mfma_f32_16x16x32_bf16 v[72:75], v[164:167], v[216:219], v[72:75]
	s_setprio 0
	s_setprio 1
	v_mfma_f32_16x16x32_bf16 v[116:119], v[168:171], v[184:187], v[116:119]
	v_mfma_f32_16x16x32_bf16 v[112:115], v[176:179], v[184:187], v[112:115]
	v_mfma_f32_16x16x32_bf16 v[100:103], v[168:171], v[196:199], v[100:103]
	v_mfma_f32_16x16x32_bf16 v[96:99], v[176:179], v[196:199], v[96:99]
	v_mfma_f32_16x16x32_bf16 v[84:87], v[168:171], v[204:207], v[84:87]
	v_mfma_f32_16x16x32_bf16 v[80:83], v[176:179], v[204:207], v[80:83]
	v_mfma_f32_16x16x32_bf16 v[68:71], v[168:171], v[212:215], v[68:71]
	v_mfma_f32_16x16x32_bf16 v[64:67], v[176:179], v[212:215], v[64:67]
	v_mfma_f32_16x16x32_bf16 v[116:119], v[172:175], v[192:195], v[116:119]
	v_mfma_f32_16x16x32_bf16 v[112:115], v[180:183], v[192:195], v[112:115]
	v_mfma_f32_16x16x32_bf16 v[100:103], v[172:175], v[200:203], v[100:103]
	v_mfma_f32_16x16x32_bf16 v[96:99], v[180:183], v[200:203], v[96:99]
	v_mfma_f32_16x16x32_bf16 v[84:87], v[172:175], v[208:211], v[84:87]
	v_mfma_f32_16x16x32_bf16 v[80:83], v[180:183], v[208:211], v[80:83]
	v_mfma_f32_16x16x32_bf16 v[68:71], v[172:175], v[216:219], v[68:71]
	v_mfma_f32_16x16x32_bf16 v[64:67], v[180:183], v[216:219], v[64:67]
	s_setprio 0
	s_barrier
	s_add_i32 s67, s54, s43
	v_lshl_add_u64 v[188:189], s[36:37], 0, v[132:133]
	s_mov_b32 m0, s67
	ds_read_b128 v[184:187], v154 offset:16384
	ds_read_b128 v[192:195], v154 offset:17408
	ds_read_b128 v[196:199], v154 offset:18432
	ds_read_b128 v[200:203], v154 offset:19456
	ds_read_b128 v[204:207], v154 offset:20480
	ds_read_b128 v[208:211], v154 offset:21504
	ds_read_b128 v[212:215], v154 offset:22528
	ds_read_b128 v[216:219], v154 offset:23552
	global_load_lds_dwordx4 v[188:189], off
	s_add_i32 m0, s67, 0x2000
	s_add_u32 s68, s36, 0x40000
	v_lshl_add_u64 v[220:221], s[36:37], 0, v[128:129]
	s_addc_u32 s69, s37, 0
	s_add_i32 s67, s55, s43
	global_load_lds_dwordx4 v[220:221], off
	v_lshl_add_u64 v[222:223], s[68:69], 0, v[132:133]
	s_mov_b32 m0, s67
	v_lshl_add_u64 v[224:225], s[38:39], 0, v[130:131]
	global_load_lds_dwordx4 v[222:223], off
	v_lshl_add_u64 v[222:223], s[68:69], 0, v[128:129]
	s_add_i32 m0, s67, 0x2000
	s_nop 0
	global_load_lds_dwordx4 v[222:223], off
	v_lshl_add_u64 v[222:223], s[38:39], 0, v[134:135]
	s_mov_b32 m0, s46
	s_nop 0
	global_load_lds_dwordx4 v[222:223], off
	s_mov_b32 m0, s47
	s_nop 0
	global_load_lds_dwordx4 v[224:225], off
	s_waitcnt vmcnt(8)
	s_waitcnt lgkmcnt(0)
	s_barrier
	s_setprio 1
	s_waitcnt lgkmcnt(0)
	v_mfma_f32_16x16x32_bf16 v[60:63], v[146:149], v[184:187], v[60:63]
	v_mfma_f32_16x16x32_bf16 v[56:59], v[160:163], v[184:187], v[56:59]
	v_mfma_f32_16x16x32_bf16 v[44:47], v[146:149], v[196:199], v[44:47]
	v_mfma_f32_16x16x32_bf16 v[40:43], v[160:163], v[196:199], v[40:43]
	v_mfma_f32_16x16x32_bf16 v[28:31], v[146:149], v[204:207], v[28:31]
	v_mfma_f32_16x16x32_bf16 v[24:27], v[160:163], v[204:207], v[24:27]
	v_mfma_f32_16x16x32_bf16 v[12:15], v[146:149], v[212:215], v[12:15]
	v_mfma_f32_16x16x32_bf16 v[8:11], v[160:163], v[212:215], v[8:11]
	v_mfma_f32_16x16x32_bf16 v[60:63], v[156:159], v[192:195], v[60:63]
	v_mfma_f32_16x16x32_bf16 v[56:59], v[164:167], v[192:195], v[56:59]
	v_mfma_f32_16x16x32_bf16 v[44:47], v[156:159], v[200:203], v[44:47]
	v_mfma_f32_16x16x32_bf16 v[40:43], v[164:167], v[200:203], v[40:43]
	v_mfma_f32_16x16x32_bf16 v[28:31], v[156:159], v[208:211], v[28:31]
	v_mfma_f32_16x16x32_bf16 v[24:27], v[164:167], v[208:211], v[24:27]
	v_mfma_f32_16x16x32_bf16 v[12:15], v[156:159], v[216:219], v[12:15]
	v_mfma_f32_16x16x32_bf16 v[8:11], v[164:167], v[216:219], v[8:11]
	s_setprio 0
	s_setprio 1
	v_mfma_f32_16x16x32_bf16 v[52:55], v[168:171], v[184:187], v[52:55]
	v_mfma_f32_16x16x32_bf16 v[48:51], v[176:179], v[184:187], v[48:51]
	v_mfma_f32_16x16x32_bf16 v[36:39], v[168:171], v[196:199], v[36:39]
	v_mfma_f32_16x16x32_bf16 v[32:35], v[176:179], v[196:199], v[32:35]
	v_mfma_f32_16x16x32_bf16 v[20:23], v[168:171], v[204:207], v[20:23]
	v_mfma_f32_16x16x32_bf16 v[16:19], v[176:179], v[204:207], v[16:19]
	v_mfma_f32_16x16x32_bf16 v[4:7], v[168:171], v[212:215], v[4:7]
	v_mfma_f32_16x16x32_bf16 v[0:3], v[176:179], v[212:215], v[0:3]
	v_mfma_f32_16x16x32_bf16 v[52:55], v[172:175], v[192:195], v[52:55]
	v_mfma_f32_16x16x32_bf16 v[48:51], v[180:183], v[192:195], v[48:51]
	v_mfma_f32_16x16x32_bf16 v[36:39], v[172:175], v[200:203], v[36:39]
	v_mfma_f32_16x16x32_bf16 v[32:35], v[180:183], v[200:203], v[32:35]
	v_mfma_f32_16x16x32_bf16 v[20:23], v[172:175], v[208:211], v[20:23]
	v_mfma_f32_16x16x32_bf16 v[16:19], v[180:183], v[208:211], v[16:19]
	v_mfma_f32_16x16x32_bf16 v[4:7], v[172:175], v[216:219], v[4:7]
	v_mfma_f32_16x16x32_bf16 v[0:3], v[180:183], v[216:219], v[0:3]
	s_setprio 0
	s_barrier
	s_add_i32 s67, 0, 0x18000
	s_add_i32 s68, 0, 0x1c000
	v_add_u32_e32 v164, s67, v151
	v_add_u32_e32 v180, s68, v151
	ds_read_b128 v[146:149], v164
	ds_read_b128 v[156:159], v164 offset:1024
	ds_read_b128 v[160:163], v164 offset:2048
	ds_read_b128 v[164:167], v164 offset:3072
	ds_read_b128 v[168:171], v180
	ds_read_b128 v[172:175], v180 offset:1024
	ds_read_b128 v[176:179], v180 offset:2048
	ds_read_b128 v[180:183], v180 offset:3072
	s_add_u32 s38, s38, 0x40000
	s_addc_u32 s39, s39, 0
	s_mov_b32 m0, s48
	v_lshl_add_u64 v[226:227], s[38:39], 0, v[134:135]
	ds_read_b128 v[184:187], v154 offset:32768
	ds_read_b128 v[192:195], v154 offset:33792
	ds_read_b128 v[196:199], v154 offset:34816
	ds_read_b128 v[200:203], v154 offset:35840
	ds_read_b128 v[204:207], v154 offset:36864
	ds_read_b128 v[208:211], v154 offset:37888
	ds_read_b128 v[212:215], v154 offset:38912
	ds_read_b128 v[216:219], v154 offset:39936
	global_load_lds_dwordx4 v[226:227], off
	v_lshl_add_u64 v[226:227], s[38:39], 0, v[130:131]
	s_mov_b32 m0, s49
	s_nop 0
	global_load_lds_dwordx4 v[226:227], off
	s_waitcnt vmcnt(8)
	s_waitcnt lgkmcnt(0)
	s_barrier
	s_setprio 1
	s_waitcnt lgkmcnt(0)
	v_mfma_f32_16x16x32_bf16 v[124:127], v[146:149], v[184:187], v[124:127]
	v_mfma_f32_16x16x32_bf16 v[120:123], v[160:163], v[184:187], v[120:123]
	v_mfma_f32_16x16x32_bf16 v[108:111], v[146:149], v[196:199], v[108:111]
	v_mfma_f32_16x16x32_bf16 v[104:107], v[160:163], v[196:199], v[104:107]
	v_mfma_f32_16x16x32_bf16 v[92:95], v[146:149], v[204:207], v[92:95]
	v_mfma_f32_16x16x32_bf16 v[88:91], v[160:163], v[204:207], v[88:91]
	v_mfma_f32_16x16x32_bf16 v[76:79], v[146:149], v[212:215], v[76:79]
	v_mfma_f32_16x16x32_bf16 v[72:75], v[160:163], v[212:215], v[72:75]
	v_mfma_f32_16x16x32_bf16 v[124:127], v[156:159], v[192:195], v[124:127]
	v_mfma_f32_16x16x32_bf16 v[120:123], v[164:167], v[192:195], v[120:123]
	v_mfma_f32_16x16x32_bf16 v[108:111], v[156:159], v[200:203], v[108:111]
	v_mfma_f32_16x16x32_bf16 v[104:107], v[164:167], v[200:203], v[104:107]
	v_mfma_f32_16x16x32_bf16 v[92:95], v[156:159], v[208:211], v[92:95]
	v_mfma_f32_16x16x32_bf16 v[88:91], v[164:167], v[208:211], v[88:91]
	v_mfma_f32_16x16x32_bf16 v[76:79], v[156:159], v[216:219], v[76:79]
	v_mfma_f32_16x16x32_bf16 v[72:75], v[164:167], v[216:219], v[72:75]
	s_setprio 0
	s_setprio 1
	v_mfma_f32_16x16x32_bf16 v[116:119], v[168:171], v[184:187], v[116:119]
	v_mfma_f32_16x16x32_bf16 v[112:115], v[176:179], v[184:187], v[112:115]
	v_mfma_f32_16x16x32_bf16 v[100:103], v[168:171], v[196:199], v[100:103]
	v_mfma_f32_16x16x32_bf16 v[96:99], v[176:179], v[196:199], v[96:99]
	v_mfma_f32_16x16x32_bf16 v[84:87], v[168:171], v[204:207], v[84:87]
	v_mfma_f32_16x16x32_bf16 v[80:83], v[176:179], v[204:207], v[80:83]
	v_mfma_f32_16x16x32_bf16 v[68:71], v[168:171], v[212:215], v[68:71]
	v_mfma_f32_16x16x32_bf16 v[64:67], v[176:179], v[212:215], v[64:67]
	v_mfma_f32_16x16x32_bf16 v[116:119], v[172:175], v[192:195], v[116:119]
	v_mfma_f32_16x16x32_bf16 v[112:115], v[180:183], v[192:195], v[112:115]
	v_mfma_f32_16x16x32_bf16 v[100:103], v[172:175], v[200:203], v[100:103]
	v_mfma_f32_16x16x32_bf16 v[96:99], v[180:183], v[200:203], v[96:99]
	v_mfma_f32_16x16x32_bf16 v[84:87], v[172:175], v[208:211], v[84:87]
	v_mfma_f32_16x16x32_bf16 v[80:83], v[180:183], v[208:211], v[80:83]
	v_mfma_f32_16x16x32_bf16 v[68:71], v[172:175], v[216:219], v[68:71]
	v_mfma_f32_16x16x32_bf16 v[64:67], v[180:183], v[216:219], v[64:67]
	s_setprio 0
	s_barrier
	s_add_i32 s38, s67, s43
	v_lshl_add_u64 v[188:189], v[188:189], 0, s[14:15]
	s_mov_b32 m0, s38
	ds_read_b128 v[184:187], v154 offset:49152
	ds_read_b128 v[192:195], v154 offset:50176
	ds_read_b128 v[196:199], v154 offset:51200
	ds_read_b128 v[200:203], v154 offset:52224
	ds_read_b128 v[204:207], v154 offset:53248
	ds_read_b128 v[208:211], v154 offset:54272
	ds_read_b128 v[212:215], v154 offset:55296
	ds_read_b128 v[216:219], v154 offset:56320
	global_load_lds_dwordx4 v[188:189], off
	s_add_i32 m0, s38, 0x2000
	s_add_u32 s36, s36, 0x40080
	v_lshl_add_u64 v[188:189], v[220:221], 0, s[14:15]
	s_addc_u32 s37, s37, 0
	s_add_i32 s38, s68, s43
	global_load_lds_dwordx4 v[188:189], off
	v_lshl_add_u64 v[188:189], s[36:37], 0, v[132:133]
	s_mov_b32 m0, s38
	s_nop 0
	global_load_lds_dwordx4 v[188:189], off
	v_lshl_add_u64 v[188:189], s[36:37], 0, v[128:129]
	s_add_i32 m0, s38, 0x2000
	s_nop 0
	global_load_lds_dwordx4 v[188:189], off
	v_lshl_add_u64 v[188:189], v[222:223], 0, s[14:15]
	s_mov_b32 m0, s50
	s_nop 0
	global_load_lds_dwordx4 v[188:189], off
	v_lshl_add_u64 v[188:189], v[224:225], 0, s[14:15]
	s_mov_b32 m0, s51
	s_nop 0
	global_load_lds_dwordx4 v[188:189], off
	s_waitcnt vmcnt(8)
	s_waitcnt lgkmcnt(0)
	s_barrier
	s_setprio 1
	s_waitcnt lgkmcnt(0)
	v_mfma_f32_16x16x32_bf16 v[60:63], v[146:149], v[184:187], v[60:63]
	v_mfma_f32_16x16x32_bf16 v[56:59], v[160:163], v[184:187], v[56:59]
	v_mfma_f32_16x16x32_bf16 v[44:47], v[146:149], v[196:199], v[44:47]
	v_mfma_f32_16x16x32_bf16 v[40:43], v[160:163], v[196:199], v[40:43]
	v_mfma_f32_16x16x32_bf16 v[28:31], v[146:149], v[204:207], v[28:31]
	v_mfma_f32_16x16x32_bf16 v[24:27], v[160:163], v[204:207], v[24:27]
	v_mfma_f32_16x16x32_bf16 v[12:15], v[146:149], v[212:215], v[12:15]
	v_mfma_f32_16x16x32_bf16 v[8:11], v[160:163], v[212:215], v[8:11]
	v_mfma_f32_16x16x32_bf16 v[60:63], v[156:159], v[192:195], v[60:63]
	v_mfma_f32_16x16x32_bf16 v[56:59], v[164:167], v[192:195], v[56:59]
	v_mfma_f32_16x16x32_bf16 v[44:47], v[156:159], v[200:203], v[44:47]
	v_mfma_f32_16x16x32_bf16 v[40:43], v[164:167], v[200:203], v[40:43]
	v_mfma_f32_16x16x32_bf16 v[28:31], v[156:159], v[208:211], v[28:31]
	v_mfma_f32_16x16x32_bf16 v[24:27], v[164:167], v[208:211], v[24:27]
	v_mfma_f32_16x16x32_bf16 v[12:15], v[156:159], v[216:219], v[12:15]
	v_mfma_f32_16x16x32_bf16 v[8:11], v[164:167], v[216:219], v[8:11]
	s_setprio 0
	s_setprio 1
	v_mfma_f32_16x16x32_bf16 v[52:55], v[168:171], v[184:187], v[52:55]
	v_mfma_f32_16x16x32_bf16 v[48:51], v[176:179], v[184:187], v[48:51]
	v_mfma_f32_16x16x32_bf16 v[36:39], v[168:171], v[196:199], v[36:39]
	v_mfma_f32_16x16x32_bf16 v[32:35], v[176:179], v[196:199], v[32:35]
	v_mfma_f32_16x16x32_bf16 v[20:23], v[168:171], v[204:207], v[20:23]
	v_mfma_f32_16x16x32_bf16 v[16:19], v[176:179], v[204:207], v[16:19]
	v_mfma_f32_16x16x32_bf16 v[4:7], v[168:171], v[212:215], v[4:7]
	v_mfma_f32_16x16x32_bf16 v[0:3], v[176:179], v[212:215], v[0:3]
	v_mfma_f32_16x16x32_bf16 v[52:55], v[172:175], v[192:195], v[52:55]
	v_mfma_f32_16x16x32_bf16 v[48:51], v[180:183], v[192:195], v[48:51]
	v_mfma_f32_16x16x32_bf16 v[36:39], v[172:175], v[200:203], v[36:39]
	v_mfma_f32_16x16x32_bf16 v[32:35], v[180:183], v[200:203], v[32:35]
	v_mfma_f32_16x16x32_bf16 v[20:23], v[172:175], v[208:211], v[20:23]
	v_mfma_f32_16x16x32_bf16 v[16:19], v[180:183], v[208:211], v[16:19]
	v_mfma_f32_16x16x32_bf16 v[4:7], v[172:175], v[216:219], v[4:7]
	v_mfma_f32_16x16x32_bf16 v[0:3], v[180:183], v[216:219], v[0:3]
	s_setprio 0
	s_add_i32 s66, s66, 2
	s_add_u32 s64, s64, 0x100
	s_addc_u32 s65, s65, 0
	s_add_u32 s34, s34, 0x100
	s_addc_u32 s35, s35, 0
	s_cmp_gt_u32 s66, 13
	s_barrier
	s_cbranch_scc0 .LBB0_1605
	v_lshl_add_u32 v210, s4, 8, v150
	v_ashrrev_i32_e32 v211, 31, v210
	v_lshl_add_u64 v[208:209], v[210:211], 2, s[12:13]
	global_load_dword v200, v[208:209], off
	global_load_dword v201, v[208:209], off offset:64
	global_load_dword v202, v[208:209], off offset:128
	global_load_dword v203, v[208:209], off offset:192
	global_load_dword v204, v[208:209], off offset:512
	global_load_dword v205, v[208:209], off offset:576
	global_load_dword v206, v[208:209], off offset:640
	global_load_dword v207, v[208:209], off offset:704
	s_and_b64 vcc, exec, s[16:17]
	s_cbranch_vccz .LBB0_1608
	s_barrier

.LBB0_1810:
	ds_read_b128 v[128:131], v171
	ds_read_b128 v[132:135], v171 offset:1024
	ds_read_b128 v[136:139], v171 offset:2048
	ds_read_b128 v[140:143], v171 offset:3072
	ds_read_b128 v[156:159], v172
	ds_read_b128 v[160:163], v172 offset:1024
	ds_read_b128 v[164:167], v172 offset:2048
	ds_read_b128 v[176:179], v172 offset:3072
	s_add_u32 s30, s28, 0x100
	s_addc_u32 s31, s29, 0
	s_cmp_eq_u32 s57, 12
	s_cselect_b32 s37, s19, s31
	s_cselect_b32 s36, s25, s30
	s_cselect_b32 s35, s17, s56
	s_cselect_b32 s34, s54, s55
	v_lshl_add_u64 v[188:189], s[28:29], 0, v[150:151]
	s_add_i32 m0, s27, 0xc000
	ds_read_b128 v[180:183], v173
	ds_read_b128 v[184:187], v173 offset:1024
	ds_read_b128 v[192:195], v173 offset:2048
	ds_read_b128 v[196:199], v173 offset:3072
	ds_read_b128 v[200:203], v173 offset:4096
	ds_read_b128 v[204:207], v173 offset:5120
	ds_read_b128 v[208:211], v173 offset:6144
	ds_read_b128 v[212:215], v173 offset:7168
	global_load_lds_dwordx4 v[188:189], off
	v_lshl_add_u64 v[188:189], s[28:29], 0, v[148:149]
	s_add_i32 m0, s27, 0xe000
	s_nop 0
	global_load_lds_dwordx4 v[188:189], off
	s_waitcnt vmcnt(8)
	s_waitcnt lgkmcnt(0)
	s_barrier
	s_setprio 1
	s_waitcnt lgkmcnt(0)
	v_mfma_f32_16x16x32_bf16 v[124:127], v[128:131], v[180:183], v[124:127]
	v_mfma_f32_16x16x32_bf16 v[120:123], v[136:139], v[180:183], v[120:123]
	v_mfma_f32_16x16x32_bf16 v[108:111], v[128:131], v[192:195], v[108:111]
	v_mfma_f32_16x16x32_bf16 v[104:107], v[136:139], v[192:195], v[104:107]
	v_mfma_f32_16x16x32_bf16 v[92:95], v[128:131], v[200:203], v[92:95]
	v_mfma_f32_16x16x32_bf16 v[88:91], v[136:139], v[200:203], v[88:91]
	v_mfma_f32_16x16x32_bf16 v[76:79], v[128:131], v[208:211], v[76:79]
	v_mfma_f32_16x16x32_bf16 v[72:75], v[136:139], v[208:211], v[72:75]
	v_mfma_f32_16x16x32_bf16 v[124:127], v[132:135], v[184:187], v[124:127]
	v_mfma_f32_16x16x32_bf16 v[120:123], v[140:143], v[184:187], v[120:123]
	v_mfma_f32_16x16x32_bf16 v[108:111], v[132:135], v[196:199], v[108:111]
	v_mfma_f32_16x16x32_bf16 v[104:107], v[140:143], v[196:199], v[104:107]
	v_mfma_f32_16x16x32_bf16 v[92:95], v[132:135], v[204:207], v[92:95]
	v_mfma_f32_16x16x32_bf16 v[88:91], v[140:143], v[204:207], v[88:91]
	v_mfma_f32_16x16x32_bf16 v[76:79], v[132:135], v[212:215], v[76:79]
	v_mfma_f32_16x16x32_bf16 v[72:75], v[140:143], v[212:215], v[72:75]
	s_setprio 0
	s_setprio 1
	v_mfma_f32_16x16x32_bf16 v[116:119], v[156:159], v[180:183], v[116:119]
	v_mfma_f32_16x16x32_bf16 v[112:115], v[164:167], v[180:183], v[112:115]
	v_mfma_f32_16x16x32_bf16 v[100:103], v[156:159], v[192:195], v[100:103]
	v_mfma_f32_16x16x32_bf16 v[96:99], v[164:167], v[192:195], v[96:99]
	v_mfma_f32_16x16x32_bf16 v[84:87], v[156:159], v[200:203], v[84:87]
	v_mfma_f32_16x16x32_bf16 v[80:83], v[164:167], v[200:203], v[80:83]
	v_mfma_f32_16x16x32_bf16 v[68:71], v[156:159], v[208:211], v[68:71]
	v_mfma_f32_16x16x32_bf16 v[64:67], v[164:167], v[208:211], v[64:67]
	v_mfma_f32_16x16x32_bf16 v[116:119], v[160:163], v[184:187], v[116:119]
	v_mfma_f32_16x16x32_bf16 v[112:115], v[176:179], v[184:187], v[112:115]
	v_mfma_f32_16x16x32_bf16 v[100:103], v[160:163], v[196:199], v[100:103]
	v_mfma_f32_16x16x32_bf16 v[96:99], v[176:179], v[196:199], v[96:99]
	v_mfma_f32_16x16x32_bf16 v[84:87], v[160:163], v[204:207], v[84:87]
	v_mfma_f32_16x16x32_bf16 v[80:83], v[176:179], v[204:207], v[80:83]
	v_mfma_f32_16x16x32_bf16 v[68:71], v[160:163], v[212:215], v[68:71]
	v_mfma_f32_16x16x32_bf16 v[64:67], v[176:179], v[212:215], v[64:67]
	s_setprio 0
	s_barrier
	s_add_i32 s28, s52, s41
	v_lshl_add_u64 v[188:189], s[34:35], 0, v[144:145]
	s_mov_b32 m0, s28
	ds_read_b128 v[180:183], v173 offset:16384
	ds_read_b128 v[184:187], v173 offset:17408
	ds_read_b128 v[192:195], v173 offset:18432
	ds_read_b128 v[196:199], v173 offset:19456
	ds_read_b128 v[200:203], v173 offset:20480
	ds_read_b128 v[204:207], v173 offset:21504
	ds_read_b128 v[208:211], v173 offset:22528
	ds_read_b128 v[212:215], v173 offset:23552
	global_load_lds_dwordx4 v[188:189], off
	s_add_i32 m0, s28, 0x2000
	s_add_u32 s28, s34, 0x40000
	v_lshl_add_u64 v[216:217], s[34:35], 0, v[146:147]
	s_addc_u32 s29, s35, 0
	s_add_i32 s58, s53, s41
	global_load_lds_dwordx4 v[216:217], off
	v_lshl_add_u64 v[218:219], s[28:29], 0, v[144:145]
	s_mov_b32 m0, s58
	v_lshl_add_u64 v[220:221], s[36:37], 0, v[146:147]
	global_load_lds_dwordx4 v[218:219], off
	v_lshl_add_u64 v[218:219], s[28:29], 0, v[146:147]
	s_add_i32 m0, s58, 0x2000
	s_nop 0
	global_load_lds_dwordx4 v[218:219], off
	v_lshl_add_u64 v[218:219], s[36:37], 0, v[144:145]
	s_mov_b32 m0, s27
	s_nop 0
	global_load_lds_dwordx4 v[218:219], off
	s_mov_b32 m0, s42
	s_nop 0
	global_load_lds_dwordx4 v[220:221], off
	s_waitcnt vmcnt(8)
	s_waitcnt lgkmcnt(0)
	s_barrier
	s_setprio 1
	s_waitcnt lgkmcnt(0)
	v_mfma_f32_16x16x32_bf16 v[60:63], v[128:131], v[180:183], v[60:63]
	v_mfma_f32_16x16x32_bf16 v[56:59], v[136:139], v[180:183], v[56:59]
	v_mfma_f32_16x16x32_bf16 v[44:47], v[128:131], v[192:195], v[44:47]
	v_mfma_f32_16x16x32_bf16 v[40:43], v[136:139], v[192:195], v[40:43]
	v_mfma_f32_16x16x32_bf16 v[28:31], v[128:131], v[200:203], v[28:31]
	v_mfma_f32_16x16x32_bf16 v[24:27], v[136:139], v[200:203], v[24:27]
	v_mfma_f32_16x16x32_bf16 v[12:15], v[128:131], v[208:211], v[12:15]
	v_mfma_f32_16x16x32_bf16 v[8:11], v[136:139], v[208:211], v[8:11]
	v_mfma_f32_16x16x32_bf16 v[60:63], v[132:135], v[184:187], v[60:63]
	v_mfma_f32_16x16x32_bf16 v[56:59], v[140:143], v[184:187], v[56:59]
	v_mfma_f32_16x16x32_bf16 v[44:47], v[132:135], v[196:199], v[44:47]
	v_mfma_f32_16x16x32_bf16 v[40:43], v[140:143], v[196:199], v[40:43]
	v_mfma_f32_16x16x32_bf16 v[28:31], v[132:135], v[204:207], v[28:31]
	v_mfma_f32_16x16x32_bf16 v[24:27], v[140:143], v[204:207], v[24:27]
	v_mfma_f32_16x16x32_bf16 v[12:15], v[132:135], v[212:215], v[12:15]
	v_mfma_f32_16x16x32_bf16 v[8:11], v[140:143], v[212:215], v[8:11]
	s_setprio 0
	s_setprio 1
	v_mfma_f32_16x16x32_bf16 v[52:55], v[156:159], v[180:183], v[52:55]
	v_mfma_f32_16x16x32_bf16 v[48:51], v[164:167], v[180:183], v[48:51]
	v_mfma_f32_16x16x32_bf16 v[36:39], v[156:159], v[192:195], v[36:39]
	v_mfma_f32_16x16x32_bf16 v[32:35], v[164:167], v[192:195], v[32:35]
	v_mfma_f32_16x16x32_bf16 v[20:23], v[156:159], v[200:203], v[20:23]
	v_mfma_f32_16x16x32_bf16 v[16:19], v[164:167], v[200:203], v[16:19]
	v_mfma_f32_16x16x32_bf16 v[4:7], v[156:159], v[208:211], v[4:7]
	v_mfma_f32_16x16x32_bf16 v[0:3], v[164:167], v[208:211], v[0:3]
	v_mfma_f32_16x16x32_bf16 v[52:55], v[160:163], v[184:187], v[52:55]
	v_mfma_f32_16x16x32_bf16 v[48:51], v[176:179], v[184:187], v[48:51]
	v_mfma_f32_16x16x32_bf16 v[36:39], v[160:163], v[196:199], v[36:39]
	v_mfma_f32_16x16x32_bf16 v[32:35], v[176:179], v[196:199], v[32:35]
	v_mfma_f32_16x16x32_bf16 v[20:23], v[160:163], v[204:207], v[20:23]
	v_mfma_f32_16x16x32_bf16 v[16:19], v[176:179], v[204:207], v[16:19]
	v_mfma_f32_16x16x32_bf16 v[4:7], v[160:163], v[212:215], v[4:7]
	v_mfma_f32_16x16x32_bf16 v[0:3], v[176:179], v[212:215], v[0:3]
	s_setprio 0
	s_barrier
	s_add_i32 s58, 0, 0x18000
	s_add_i32 s59, 0, 0x1c000
	v_add_u32_e32 v140, s58, v169
	v_add_u32_e32 v175, s59, v169
	ds_read_b128 v[128:131], v140
	ds_read_b128 v[132:135], v140 offset:1024
	ds_read_b128 v[136:139], v140 offset:2048
	ds_read_b128 v[140:143], v140 offset:3072
	ds_read_b128 v[156:159], v175
	ds_read_b128 v[160:163], v175 offset:1024
	ds_read_b128 v[164:167], v175 offset:2048
	ds_read_b128 v[176:179], v175 offset:3072
	s_add_u32 s28, s36, 0x40000
	s_addc_u32 s29, s37, 0
	s_mov_b32 m0, s43
	v_lshl_add_u64 v[222:223], s[28:29], 0, v[144:145]
	ds_read_b128 v[180:183], v173 offset:32768
	ds_read_b128 v[184:187], v173 offset:33792
	ds_read_b128 v[192:195], v173 offset:34816
	ds_read_b128 v[196:199], v173 offset:35840
	ds_read_b128 v[200:203], v173 offset:36864
	ds_read_b128 v[204:207], v173 offset:37888
	ds_read_b128 v[208:211], v173 offset:38912
	ds_read_b128 v[212:215], v173 offset:39936
	global_load_lds_dwordx4 v[222:223], off
	v_lshl_add_u64 v[222:223], s[28:29], 0, v[146:147]
	s_mov_b32 m0, s44
	s_nop 0
	global_load_lds_dwordx4 v[222:223], off
	s_waitcnt vmcnt(8)
	s_waitcnt lgkmcnt(0)
	s_barrier
	s_setprio 1
	s_waitcnt lgkmcnt(0)
	v_mfma_f32_16x16x32_bf16 v[124:127], v[128:131], v[180:183], v[124:127]
	v_mfma_f32_16x16x32_bf16 v[120:123], v[136:139], v[180:183], v[120:123]
	v_mfma_f32_16x16x32_bf16 v[108:111], v[128:131], v[192:195], v[108:111]
	v_mfma_f32_16x16x32_bf16 v[104:107], v[136:139], v[192:195], v[104:107]
	v_mfma_f32_16x16x32_bf16 v[92:95], v[128:131], v[200:203], v[92:95]
	v_mfma_f32_16x16x32_bf16 v[88:91], v[136:139], v[200:203], v[88:91]
	v_mfma_f32_16x16x32_bf16 v[76:79], v[128:131], v[208:211], v[76:79]
	v_mfma_f32_16x16x32_bf16 v[72:75], v[136:139], v[208:211], v[72:75]
	v_mfma_f32_16x16x32_bf16 v[124:127], v[132:135], v[184:187], v[124:127]
	v_mfma_f32_16x16x32_bf16 v[120:123], v[140:143], v[184:187], v[120:123]
	v_mfma_f32_16x16x32_bf16 v[108:111], v[132:135], v[196:199], v[108:111]
	v_mfma_f32_16x16x32_bf16 v[104:107], v[140:143], v[196:199], v[104:107]
	v_mfma_f32_16x16x32_bf16 v[92:95], v[132:135], v[204:207], v[92:95]
	v_mfma_f32_16x16x32_bf16 v[88:91], v[140:143], v[204:207], v[88:91]
	v_mfma_f32_16x16x32_bf16 v[76:79], v[132:135], v[212:215], v[76:79]
	v_mfma_f32_16x16x32_bf16 v[72:75], v[140:143], v[212:215], v[72:75]
	s_setprio 0
	s_setprio 1
	v_mfma_f32_16x16x32_bf16 v[116:119], v[156:159], v[180:183], v[116:119]
	v_mfma_f32_16x16x32_bf16 v[112:115], v[164:167], v[180:183], v[112:115]
	v_mfma_f32_16x16x32_bf16 v[100:103], v[156:159], v[192:195], v[100:103]
	v_mfma_f32_16x16x32_bf16 v[96:99], v[164:167], v[192:195], v[96:99]
	v_mfma_f32_16x16x32_bf16 v[84:87], v[156:159], v[200:203], v[84:87]
	v_mfma_f32_16x16x32_bf16 v[80:83], v[164:167], v[200:203], v[80:83]
	v_mfma_f32_16x16x32_bf16 v[68:71], v[156:159], v[208:211], v[68:71]
	v_mfma_f32_16x16x32_bf16 v[64:67], v[164:167], v[208:211], v[64:67]
	v_mfma_f32_16x16x32_bf16 v[116:119], v[160:163], v[184:187], v[116:119]
	v_mfma_f32_16x16x32_bf16 v[112:115], v[176:179], v[184:187], v[112:115]
	v_mfma_f32_16x16x32_bf16 v[100:103], v[160:163], v[196:199], v[100:103]
	v_mfma_f32_16x16x32_bf16 v[96:99], v[176:179], v[196:199], v[96:99]
	v_mfma_f32_16x16x32_bf16 v[84:87], v[160:163], v[204:207], v[84:87]
	v_mfma_f32_16x16x32_bf16 v[80:83], v[176:179], v[204:207], v[80:83]
	v_mfma_f32_16x16x32_bf16 v[68:71], v[160:163], v[212:215], v[68:71]
	v_mfma_f32_16x16x32_bf16 v[64:67], v[176:179], v[212:215], v[64:67]
	s_setprio 0
	s_barrier
	s_add_i32 s28, s58, s41
	v_lshl_add_u64 v[188:189], v[188:189], 0, s[12:13]
	s_mov_b32 m0, s28
	ds_read_b128 v[180:183], v173 offset:49152
	ds_read_b128 v[184:187], v173 offset:50176
	ds_read_b128 v[192:195], v173 offset:51200
	ds_read_b128 v[196:199], v173 offset:52224
	ds_read_b128 v[200:203], v173 offset:53248
	ds_read_b128 v[204:207], v173 offset:54272
	ds_read_b128 v[208:211], v173 offset:55296
	ds_read_b128 v[212:215], v173 offset:56320
	global_load_lds_dwordx4 v[188:189], off
	s_add_i32 m0, s28, 0x2000
	s_add_u32 s28, s34, 0x40080
	v_lshl_add_u64 v[188:189], v[216:217], 0, s[12:13]
	s_addc_u32 s29, s35, 0
	s_add_i32 s34, s59, s41
	global_load_lds_dwordx4 v[188:189], off
	v_lshl_add_u64 v[188:189], s[28:29], 0, v[144:145]
	s_mov_b32 m0, s34
	s_nop 0
	global_load_lds_dwordx4 v[188:189], off
	v_lshl_add_u64 v[188:189], s[28:29], 0, v[146:147]
	s_add_i32 m0, s34, 0x2000
	s_nop 0
	global_load_lds_dwordx4 v[188:189], off
	v_lshl_add_u64 v[188:189], v[218:219], 0, s[12:13]
	s_mov_b32 m0, s46
	s_nop 0
	global_load_lds_dwordx4 v[188:189], off
	v_lshl_add_u64 v[188:189], v[220:221], 0, s[12:13]
	s_mov_b32 m0, s47
	s_nop 0
	global_load_lds_dwordx4 v[188:189], off
	s_waitcnt vmcnt(8)
	s_waitcnt lgkmcnt(0)
	s_barrier
	s_setprio 1
	s_waitcnt lgkmcnt(0)
	v_mfma_f32_16x16x32_bf16 v[60:63], v[128:131], v[180:183], v[60:63]
	v_mfma_f32_16x16x32_bf16 v[56:59], v[136:139], v[180:183], v[56:59]
	v_mfma_f32_16x16x32_bf16 v[44:47], v[128:131], v[192:195], v[44:47]
	v_mfma_f32_16x16x32_bf16 v[40:43], v[136:139], v[192:195], v[40:43]
	v_mfma_f32_16x16x32_bf16 v[28:31], v[128:131], v[200:203], v[28:31]
	v_mfma_f32_16x16x32_bf16 v[24:27], v[136:139], v[200:203], v[24:27]
	v_mfma_f32_16x16x32_bf16 v[12:15], v[128:131], v[208:211], v[12:15]
	v_mfma_f32_16x16x32_bf16 v[8:11], v[136:139], v[208:211], v[8:11]
	v_mfma_f32_16x16x32_bf16 v[60:63], v[132:135], v[184:187], v[60:63]
	v_mfma_f32_16x16x32_bf16 v[56:59], v[140:143], v[184:187], v[56:59]
	v_mfma_f32_16x16x32_bf16 v[44:47], v[132:135], v[196:199], v[44:47]
	v_mfma_f32_16x16x32_bf16 v[40:43], v[140:143], v[196:199], v[40:43]
	v_mfma_f32_16x16x32_bf16 v[28:31], v[132:135], v[204:207], v[28:31]
	v_mfma_f32_16x16x32_bf16 v[24:27], v[140:143], v[204:207], v[24:27]
	v_mfma_f32_16x16x32_bf16 v[12:15], v[132:135], v[212:215], v[12:15]
	v_mfma_f32_16x16x32_bf16 v[8:11], v[140:143], v[212:215], v[8:11]
	s_setprio 0
	s_setprio 1
	v_mfma_f32_16x16x32_bf16 v[52:55], v[156:159], v[180:183], v[52:55]
	v_mfma_f32_16x16x32_bf16 v[48:51], v[164:167], v[180:183], v[48:51]
	v_mfma_f32_16x16x32_bf16 v[36:39], v[156:159], v[192:195], v[36:39]
	v_mfma_f32_16x16x32_bf16 v[32:35], v[164:167], v[192:195], v[32:35]
	v_mfma_f32_16x16x32_bf16 v[20:23], v[156:159], v[200:203], v[20:23]
	v_mfma_f32_16x16x32_bf16 v[16:19], v[164:167], v[200:203], v[16:19]
	v_mfma_f32_16x16x32_bf16 v[4:7], v[156:159], v[208:211], v[4:7]
	v_mfma_f32_16x16x32_bf16 v[0:3], v[164:167], v[208:211], v[0:3]
	v_mfma_f32_16x16x32_bf16 v[52:55], v[160:163], v[184:187], v[52:55]
	v_mfma_f32_16x16x32_bf16 v[48:51], v[176:179], v[184:187], v[48:51]
	v_mfma_f32_16x16x32_bf16 v[36:39], v[160:163], v[196:199], v[36:39]
	v_mfma_f32_16x16x32_bf16 v[32:35], v[176:179], v[196:199], v[32:35]
	v_mfma_f32_16x16x32_bf16 v[20:23], v[160:163], v[204:207], v[20:23]
	v_mfma_f32_16x16x32_bf16 v[16:19], v[176:179], v[204:207], v[16:19]
	v_mfma_f32_16x16x32_bf16 v[4:7], v[160:163], v[212:215], v[4:7]
	v_mfma_f32_16x16x32_bf16 v[0:3], v[176:179], v[212:215], v[0:3]
	s_setprio 0
	s_add_i32 s57, s57, 2
	s_add_u32 s55, s55, 0x100
	s_addc_u32 s56, s56, 0
	s_cmp_gt_u32 s57, 13
	s_mov_b64 s[28:29], s[30:31]
	s_barrier
	s_cbranch_scc0 .LBB0_1810
	v_mbcnt_lo_u32_b32 v235, -1, 0
	v_mbcnt_hi_u32_b32 v235, -1, v235
	v_lshrrev_b32_e32 v236, 2, v235
	v_and_b32_e32 v237, 3, v235
	v_lshl_add_u32 v232, v237, 4, v236
	v_lshlrev_b32_e32 v232, 2, v232
	v_and_b32_e32 v233, -16, v168
	v_or_b32_e32 v233, v233, v236
	v_lshlrev_b32_e32 v237, 2, v237
	v_and_b32_e32 v234, -13, v170
	v_or_b32_e32 v234, v234, v237
	v_lshl_add_u32 v158, s24, 8, v233
	v_lshl_or_b32 v156, s26, 8, v234
	v_ashrrev_i32_e32 v159, 31, v158
	v_lshlrev_b64 v[128:129], 12, v[158:159]
	v_ashrrev_i32_e32 v157, 31, v156
	v_lshl_add_u64 v[128:129], s[0:1], 0, v[128:129]
	v_lshlrev_b64 v[130:131], 2, v[156:157]
	v_lshl_add_u64 v[188:189], v[128:129], 0, v[130:131]
	global_load_dwordx4 v[164:167], v[188:189], off
	global_load_dwordx4 v[176:179], v[188:189], off offset:64
	global_load_dwordx4 v[180:183], v[188:189], off offset:512
	global_load_dwordx4 v[184:187], v[188:189], off offset:576
	v_or_b32_e32 v160, 16, v158
	v_ashrrev_i32_e32 v161, 31, v160
	v_lshlrev_b64 v[128:129], 12, v[160:161]
	v_lshl_add_u64 v[128:129], s[0:1], 0, v[128:129]
	v_lshl_add_u64 v[162:163], v[128:129], 0, v[130:131]
	global_load_dwordx4 v[140:143], v[162:163], off
	global_load_dwordx4 v[136:139], v[162:163], off offset:64
	global_load_dwordx4 v[132:135], v[162:163], off offset:512
	global_load_dwordx4 v[128:131], v[162:163], off offset:576
	v_lshlrev_b64 v[192:193], 11, v[158:159]
	v_lshl_add_u64 v[192:193], s[8:9], 0, v[192:193]
	v_and_b32_e32 v191, 64, v174
	v_lshl_add_u64 v[192:193], v[156:157], 1, v[192:193]
	v_xor_b32_e32 v175, 1, v174
	v_add_u32_e32 v191, 64, v191
	v_cmp_lt_i32_e32 vcc, v175, v191
	v_xor_b32_e32 v194, 2, v174
	ds_bpermute_b32 v127, v232, v127
	ds_bpermute_b32 v126, v232, v126
	ds_bpermute_b32 v125, v232, v125
	ds_bpermute_b32 v124, v232, v124
	ds_bpermute_b32 v123, v232, v123
	ds_bpermute_b32 v122, v232, v122
	ds_bpermute_b32 v121, v232, v121
	ds_bpermute_b32 v120, v232, v120
	ds_bpermute_b32 v119, v232, v119
	ds_bpermute_b32 v118, v232, v118
	ds_bpermute_b32 v117, v232, v117
	ds_bpermute_b32 v116, v232, v116
	ds_bpermute_b32 v115, v232, v115
	ds_bpermute_b32 v114, v232, v114
	ds_bpermute_b32 v113, v232, v113
	ds_bpermute_b32 v112, v232, v112
	ds_bpermute_b32 v111, v232, v111
	ds_bpermute_b32 v110, v232, v110
	ds_bpermute_b32 v109, v232, v109
	ds_bpermute_b32 v108, v232, v108
	ds_bpermute_b32 v107, v232, v107
	ds_bpermute_b32 v106, v232, v106
	ds_bpermute_b32 v105, v232, v105
	ds_bpermute_b32 v104, v232, v104
	ds_bpermute_b32 v103, v232, v103
	ds_bpermute_b32 v102, v232, v102
	ds_bpermute_b32 v101, v232, v101
	ds_bpermute_b32 v100, v232, v100
	ds_bpermute_b32 v99, v232, v99
	ds_bpermute_b32 v98, v232, v98
	ds_bpermute_b32 v97, v232, v97
	ds_bpermute_b32 v96, v232, v96
	ds_bpermute_b32 v95, v232, v95
	ds_bpermute_b32 v94, v232, v94
	ds_bpermute_b32 v93, v232, v93
	ds_bpermute_b32 v92, v232, v92
	ds_bpermute_b32 v91, v232, v91
	ds_bpermute_b32 v90, v232, v90
	ds_bpermute_b32 v89, v232, v89
	ds_bpermute_b32 v88, v232, v88
	ds_bpermute_b32 v87, v232, v87
	ds_bpermute_b32 v86, v232, v86
	ds_bpermute_b32 v85, v232, v85
	ds_bpermute_b32 v84, v232, v84
	ds_bpermute_b32 v83, v232, v83
	ds_bpermute_b32 v82, v232, v82
	ds_bpermute_b32 v81, v232, v81
	ds_bpermute_b32 v80, v232, v80
	ds_bpermute_b32 v79, v232, v79
	ds_bpermute_b32 v78, v232, v78
	ds_bpermute_b32 v77, v232, v77
	ds_bpermute_b32 v76, v232, v76
	ds_bpermute_b32 v75, v232, v75
	ds_bpermute_b32 v74, v232, v74
	ds_bpermute_b32 v73, v232, v73
	ds_bpermute_b32 v72, v232, v72
	ds_bpermute_b32 v71, v232, v71
	ds_bpermute_b32 v70, v232, v70
	ds_bpermute_b32 v69, v232, v69
	ds_bpermute_b32 v68, v232, v68
	ds_bpermute_b32 v67, v232, v67
	ds_bpermute_b32 v66, v232, v66
	ds_bpermute_b32 v65, v232, v65
	ds_bpermute_b32 v64, v232, v64
	ds_bpermute_b32 v63, v232, v63
	ds_bpermute_b32 v62, v232, v62
	ds_bpermute_b32 v61, v232, v61
	ds_bpermute_b32 v60, v232, v60
	ds_bpermute_b32 v59, v232, v59
	ds_bpermute_b32 v58, v232, v58
	ds_bpermute_b32 v57, v232, v57
	ds_bpermute_b32 v56, v232, v56
	ds_bpermute_b32 v55, v232, v55
	ds_bpermute_b32 v54, v232, v54
	ds_bpermute_b32 v53, v232, v53
	ds_bpermute_b32 v52, v232, v52
	ds_bpermute_b32 v51, v232, v51
	ds_bpermute_b32 v50, v232, v50
	ds_bpermute_b32 v49, v232, v49
	ds_bpermute_b32 v48, v232, v48
	ds_bpermute_b32 v47, v232, v47
	ds_bpermute_b32 v46, v232, v46
	ds_bpermute_b32 v45, v232, v45
	ds_bpermute_b32 v44, v232, v44
	ds_bpermute_b32 v43, v232, v43
	ds_bpermute_b32 v42, v232, v42
	ds_bpermute_b32 v41, v232, v41
	ds_bpermute_b32 v40, v232, v40
	ds_bpermute_b32 v39, v232, v39
	ds_bpermute_b32 v38, v232, v38
	ds_bpermute_b32 v37, v232, v37
	ds_bpermute_b32 v36, v232, v36
	ds_bpermute_b32 v35, v232, v35
	ds_bpermute_b32 v34, v232, v34
	ds_bpermute_b32 v33, v232, v33
	ds_bpermute_b32 v32, v232, v32
	ds_bpermute_b32 v31, v232, v31
	ds_bpermute_b32 v30, v232, v30
	ds_bpermute_b32 v29, v232, v29
	ds_bpermute_b32 v28, v232, v28
	ds_bpermute_b32 v27, v232, v27
	ds_bpermute_b32 v26, v232, v26
	ds_bpermute_b32 v25, v232, v25
	ds_bpermute_b32 v24, v232, v24
	ds_bpermute_b32 v23, v232, v23
	ds_bpermute_b32 v22, v232, v22
	ds_bpermute_b32 v21, v232, v21
	ds_bpermute_b32 v20, v232, v20
	ds_bpermute_b32 v19, v232, v19
	ds_bpermute_b32 v18, v232, v18
	ds_bpermute_b32 v17, v232, v17
	ds_bpermute_b32 v16, v232, v16
	ds_bpermute_b32 v15, v232, v15
	ds_bpermute_b32 v14, v232, v14
	ds_bpermute_b32 v13, v232, v13
	ds_bpermute_b32 v12, v232, v12
	ds_bpermute_b32 v11, v232, v11
	ds_bpermute_b32 v10, v232, v10
	ds_bpermute_b32 v9, v232, v9
	ds_bpermute_b32 v8, v232, v8
	ds_bpermute_b32 v7, v232, v7
	ds_bpermute_b32 v6, v232, v6
	ds_bpermute_b32 v5, v232, v5
	ds_bpermute_b32 v4, v232, v4
	ds_bpermute_b32 v3, v232, v3
	ds_bpermute_b32 v2, v232, v2
	ds_bpermute_b32 v1, v232, v1
	ds_bpermute_b32 v0, v232, v0
	s_waitcnt lgkmcnt(0)
	s_waitcnt lgkmcnt(0)
	s_cmp_eq_u64 s[14:15], 0
	s_cbranch_scc1 .LBB0_1813
	s_barrier

.LBB0_1917:
	ds_read_b128 v[150:153], v163
	ds_read_b128 v[154:157], v163 offset:1024
	ds_read_b128 v[158:161], v163 offset:2048
	ds_read_b128 v[168:171], v163 offset:3072
	ds_read_b128 v[172:175], v164
	ds_read_b128 v[176:179], v164 offset:1024
	ds_read_b128 v[180:183], v164 offset:2048
	ds_read_b128 v[184:187], v164 offset:3072
	s_add_u32 s34, s30, 0xfffc0080
	s_addc_u32 s35, s31, -1
	s_cmp_eq_u32 s61, 12
	s_cselect_b32 s37, s8, s35
	s_cselect_b32 s36, s21, s34
	s_cselect_b32 s35, s23, s60
	s_cselect_b32 s34, s25, s33
	v_lshl_add_u64 v[188:189], s[30:31], 0, v[142:143]
	s_add_i32 m0, s45, 0xc000
	ds_read_b128 v[192:195], v165
	ds_read_b128 v[196:199], v165 offset:1024
	ds_read_b128 v[200:203], v165 offset:2048
	ds_read_b128 v[204:207], v165 offset:3072
	ds_read_b128 v[208:211], v165 offset:4096
	ds_read_b128 v[212:215], v165 offset:5120
	ds_read_b128 v[216:219], v165 offset:6144
	ds_read_b128 v[220:223], v165 offset:7168
	global_load_lds_dwordx4 v[188:189], off
	v_lshl_add_u64 v[188:189], s[30:31], 0, v[140:141]
	s_add_i32 m0, s45, 0xe000
	s_nop 0
	global_load_lds_dwordx4 v[188:189], off
	s_waitcnt vmcnt(8)
	s_waitcnt lgkmcnt(0)
	s_barrier
	s_setprio 1
	s_waitcnt lgkmcnt(0)
	v_mfma_f32_16x16x32_bf16 v[124:127], v[150:153], v[192:195], v[124:127]
	v_mfma_f32_16x16x32_bf16 v[120:123], v[158:161], v[192:195], v[120:123]
	v_mfma_f32_16x16x32_bf16 v[108:111], v[150:153], v[200:203], v[108:111]
	v_mfma_f32_16x16x32_bf16 v[104:107], v[158:161], v[200:203], v[104:107]
	v_mfma_f32_16x16x32_bf16 v[92:95], v[150:153], v[208:211], v[92:95]
	v_mfma_f32_16x16x32_bf16 v[88:91], v[158:161], v[208:211], v[88:91]
	v_mfma_f32_16x16x32_bf16 v[76:79], v[150:153], v[216:219], v[76:79]
	v_mfma_f32_16x16x32_bf16 v[72:75], v[158:161], v[216:219], v[72:75]
	v_mfma_f32_16x16x32_bf16 v[124:127], v[154:157], v[196:199], v[124:127]
	v_mfma_f32_16x16x32_bf16 v[120:123], v[168:171], v[196:199], v[120:123]
	v_mfma_f32_16x16x32_bf16 v[108:111], v[154:157], v[204:207], v[108:111]
	v_mfma_f32_16x16x32_bf16 v[104:107], v[168:171], v[204:207], v[104:107]
	v_mfma_f32_16x16x32_bf16 v[92:95], v[154:157], v[212:215], v[92:95]
	v_mfma_f32_16x16x32_bf16 v[88:91], v[168:171], v[212:215], v[88:91]
	v_mfma_f32_16x16x32_bf16 v[76:79], v[154:157], v[220:223], v[76:79]
	v_mfma_f32_16x16x32_bf16 v[72:75], v[168:171], v[220:223], v[72:75]
	s_setprio 0
	s_setprio 1
	v_mfma_f32_16x16x32_bf16 v[116:119], v[172:175], v[192:195], v[116:119]
	v_mfma_f32_16x16x32_bf16 v[112:115], v[180:183], v[192:195], v[112:115]
	v_mfma_f32_16x16x32_bf16 v[100:103], v[172:175], v[200:203], v[100:103]
	v_mfma_f32_16x16x32_bf16 v[96:99], v[180:183], v[200:203], v[96:99]
	v_mfma_f32_16x16x32_bf16 v[84:87], v[172:175], v[208:211], v[84:87]
	v_mfma_f32_16x16x32_bf16 v[80:83], v[180:183], v[208:211], v[80:83]
	v_mfma_f32_16x16x32_bf16 v[68:71], v[172:175], v[216:219], v[68:71]
	v_mfma_f32_16x16x32_bf16 v[64:67], v[180:183], v[216:219], v[64:67]
	v_mfma_f32_16x16x32_bf16 v[116:119], v[176:179], v[196:199], v[116:119]
	v_mfma_f32_16x16x32_bf16 v[112:115], v[184:187], v[196:199], v[112:115]
	v_mfma_f32_16x16x32_bf16 v[100:103], v[176:179], v[204:207], v[100:103]
	v_mfma_f32_16x16x32_bf16 v[96:99], v[184:187], v[204:207], v[96:99]
	v_mfma_f32_16x16x32_bf16 v[84:87], v[176:179], v[212:215], v[84:87]
	v_mfma_f32_16x16x32_bf16 v[80:83], v[184:187], v[212:215], v[80:83]
	v_mfma_f32_16x16x32_bf16 v[68:71], v[176:179], v[220:223], v[68:71]
	v_mfma_f32_16x16x32_bf16 v[64:67], v[184:187], v[220:223], v[64:67]
	s_setprio 0
	s_barrier
	s_add_i32 s62, s53, s42
	v_lshl_add_u64 v[188:189], s[34:35], 0, v[132:133]
	s_mov_b32 m0, s62
	ds_read_b128 v[192:195], v165 offset:16384
	ds_read_b128 v[196:199], v165 offset:17408
	ds_read_b128 v[200:203], v165 offset:18432
	ds_read_b128 v[204:207], v165 offset:19456
	ds_read_b128 v[208:211], v165 offset:20480
	ds_read_b128 v[212:215], v165 offset:21504
	ds_read_b128 v[216:219], v165 offset:22528
	ds_read_b128 v[220:223], v165 offset:23552
	global_load_lds_dwordx4 v[188:189], off
	s_add_i32 m0, s62, 0x2000
	s_add_u32 s62, s34, 0x40000
	v_lshl_add_u64 v[224:225], s[34:35], 0, v[128:129]
	s_addc_u32 s63, s35, 0
	s_add_i32 s64, s54, s42
	global_load_lds_dwordx4 v[224:225], off
	v_lshl_add_u64 v[226:227], s[62:63], 0, v[132:133]
	s_mov_b32 m0, s64
	v_lshl_add_u64 v[228:229], s[36:37], 0, v[130:131]
	global_load_lds_dwordx4 v[226:227], off
	v_lshl_add_u64 v[226:227], s[62:63], 0, v[128:129]
	s_add_i32 m0, s64, 0x2000
	s_nop 0
	global_load_lds_dwordx4 v[226:227], off
	v_lshl_add_u64 v[226:227], s[36:37], 0, v[134:135]
	s_mov_b32 m0, s45
	s_nop 0
	global_load_lds_dwordx4 v[226:227], off
	s_mov_b32 m0, s46
	s_nop 0
	global_load_lds_dwordx4 v[228:229], off
	s_waitcnt vmcnt(8)
	s_waitcnt lgkmcnt(0)
	s_barrier
	s_setprio 1
	s_waitcnt lgkmcnt(0)
	v_mfma_f32_16x16x32_bf16 v[60:63], v[150:153], v[192:195], v[60:63]
	v_mfma_f32_16x16x32_bf16 v[56:59], v[158:161], v[192:195], v[56:59]
	v_mfma_f32_16x16x32_bf16 v[44:47], v[150:153], v[200:203], v[44:47]
	v_mfma_f32_16x16x32_bf16 v[40:43], v[158:161], v[200:203], v[40:43]
	v_mfma_f32_16x16x32_bf16 v[28:31], v[150:153], v[208:211], v[28:31]
	v_mfma_f32_16x16x32_bf16 v[24:27], v[158:161], v[208:211], v[24:27]
	v_mfma_f32_16x16x32_bf16 v[12:15], v[150:153], v[216:219], v[12:15]
	v_mfma_f32_16x16x32_bf16 v[8:11], v[158:161], v[216:219], v[8:11]
	v_mfma_f32_16x16x32_bf16 v[60:63], v[154:157], v[196:199], v[60:63]
	v_mfma_f32_16x16x32_bf16 v[56:59], v[168:171], v[196:199], v[56:59]
	v_mfma_f32_16x16x32_bf16 v[44:47], v[154:157], v[204:207], v[44:47]
	v_mfma_f32_16x16x32_bf16 v[40:43], v[168:171], v[204:207], v[40:43]
	v_mfma_f32_16x16x32_bf16 v[28:31], v[154:157], v[212:215], v[28:31]
	v_mfma_f32_16x16x32_bf16 v[24:27], v[168:171], v[212:215], v[24:27]
	v_mfma_f32_16x16x32_bf16 v[12:15], v[154:157], v[220:223], v[12:15]
	v_mfma_f32_16x16x32_bf16 v[8:11], v[168:171], v[220:223], v[8:11]
	s_setprio 0
	s_setprio 1
	v_mfma_f32_16x16x32_bf16 v[52:55], v[172:175], v[192:195], v[52:55]
	v_mfma_f32_16x16x32_bf16 v[48:51], v[180:183], v[192:195], v[48:51]
	v_mfma_f32_16x16x32_bf16 v[36:39], v[172:175], v[200:203], v[36:39]
	v_mfma_f32_16x16x32_bf16 v[32:35], v[180:183], v[200:203], v[32:35]
	v_mfma_f32_16x16x32_bf16 v[20:23], v[172:175], v[208:211], v[20:23]
	v_mfma_f32_16x16x32_bf16 v[16:19], v[180:183], v[208:211], v[16:19]
	v_mfma_f32_16x16x32_bf16 v[4:7], v[172:175], v[216:219], v[4:7]
	v_mfma_f32_16x16x32_bf16 v[0:3], v[180:183], v[216:219], v[0:3]
	v_mfma_f32_16x16x32_bf16 v[52:55], v[176:179], v[196:199], v[52:55]
	v_mfma_f32_16x16x32_bf16 v[48:51], v[184:187], v[196:199], v[48:51]
	v_mfma_f32_16x16x32_bf16 v[36:39], v[176:179], v[204:207], v[36:39]
	v_mfma_f32_16x16x32_bf16 v[32:35], v[184:187], v[204:207], v[32:35]
	v_mfma_f32_16x16x32_bf16 v[20:23], v[176:179], v[212:215], v[20:23]
	v_mfma_f32_16x16x32_bf16 v[16:19], v[184:187], v[212:215], v[16:19]
	v_mfma_f32_16x16x32_bf16 v[4:7], v[176:179], v[220:223], v[4:7]
	v_mfma_f32_16x16x32_bf16 v[0:3], v[184:187], v[220:223], v[0:3]
	s_setprio 0
	s_barrier
	s_add_i32 s62, 0, 0x18000
	v_add_u32_e32 v136, s62, v162
	s_add_i32 s63, 0, 0x1c000
	ds_read_b128 v[150:153], v136
	ds_read_b128 v[154:157], v136 offset:1024
	ds_read_b128 v[158:161], v136 offset:2048
	ds_read_b128 v[168:171], v136 offset:3072
	v_add_u32_e32 v136, s63, v162
	ds_read_b128 v[172:175], v136
	ds_read_b128 v[176:179], v136 offset:1024
	ds_read_b128 v[180:183], v136 offset:2048
	ds_read_b128 v[184:187], v136 offset:3072
	s_add_u32 s36, s36, 0x40000
	s_addc_u32 s37, s37, 0
	s_mov_b32 m0, s47
	v_lshl_add_u64 v[230:231], s[36:37], 0, v[134:135]
	ds_read_b128 v[192:195], v165 offset:32768
	ds_read_b128 v[196:199], v165 offset:33792
	ds_read_b128 v[200:203], v165 offset:34816
	ds_read_b128 v[204:207], v165 offset:35840
	ds_read_b128 v[208:211], v165 offset:36864
	ds_read_b128 v[212:215], v165 offset:37888
	ds_read_b128 v[216:219], v165 offset:38912
	ds_read_b128 v[220:223], v165 offset:39936
	global_load_lds_dwordx4 v[230:231], off
	v_lshl_add_u64 v[230:231], s[36:37], 0, v[130:131]
	s_mov_b32 m0, s48
	s_nop 0
	global_load_lds_dwordx4 v[230:231], off
	s_waitcnt vmcnt(8)
	s_waitcnt lgkmcnt(0)
	s_barrier
	s_setprio 1
	s_waitcnt lgkmcnt(0)
	v_mfma_f32_16x16x32_bf16 v[124:127], v[150:153], v[192:195], v[124:127]
	v_mfma_f32_16x16x32_bf16 v[120:123], v[158:161], v[192:195], v[120:123]
	v_mfma_f32_16x16x32_bf16 v[108:111], v[150:153], v[200:203], v[108:111]
	v_mfma_f32_16x16x32_bf16 v[104:107], v[158:161], v[200:203], v[104:107]
	v_mfma_f32_16x16x32_bf16 v[92:95], v[150:153], v[208:211], v[92:95]
	v_mfma_f32_16x16x32_bf16 v[88:91], v[158:161], v[208:211], v[88:91]
	v_mfma_f32_16x16x32_bf16 v[76:79], v[150:153], v[216:219], v[76:79]
	v_mfma_f32_16x16x32_bf16 v[72:75], v[158:161], v[216:219], v[72:75]
	v_mfma_f32_16x16x32_bf16 v[124:127], v[154:157], v[196:199], v[124:127]
	v_mfma_f32_16x16x32_bf16 v[120:123], v[168:171], v[196:199], v[120:123]
	v_mfma_f32_16x16x32_bf16 v[108:111], v[154:157], v[204:207], v[108:111]
	v_mfma_f32_16x16x32_bf16 v[104:107], v[168:171], v[204:207], v[104:107]
	v_mfma_f32_16x16x32_bf16 v[92:95], v[154:157], v[212:215], v[92:95]
	v_mfma_f32_16x16x32_bf16 v[88:91], v[168:171], v[212:215], v[88:91]
	v_mfma_f32_16x16x32_bf16 v[76:79], v[154:157], v[220:223], v[76:79]
	v_mfma_f32_16x16x32_bf16 v[72:75], v[168:171], v[220:223], v[72:75]
	s_setprio 0
	s_setprio 1
	v_mfma_f32_16x16x32_bf16 v[116:119], v[172:175], v[192:195], v[116:119]
	v_mfma_f32_16x16x32_bf16 v[112:115], v[180:183], v[192:195], v[112:115]
	v_mfma_f32_16x16x32_bf16 v[100:103], v[172:175], v[200:203], v[100:103]
	v_mfma_f32_16x16x32_bf16 v[96:99], v[180:183], v[200:203], v[96:99]
	v_mfma_f32_16x16x32_bf16 v[84:87], v[172:175], v[208:211], v[84:87]
	v_mfma_f32_16x16x32_bf16 v[80:83], v[180:183], v[208:211], v[80:83]
	v_mfma_f32_16x16x32_bf16 v[68:71], v[172:175], v[216:219], v[68:71]
	v_mfma_f32_16x16x32_bf16 v[64:67], v[180:183], v[216:219], v[64:67]
	v_mfma_f32_16x16x32_bf16 v[116:119], v[176:179], v[196:199], v[116:119]
	v_mfma_f32_16x16x32_bf16 v[112:115], v[184:187], v[196:199], v[112:115]
	v_mfma_f32_16x16x32_bf16 v[100:103], v[176:179], v[204:207], v[100:103]
	v_mfma_f32_16x16x32_bf16 v[96:99], v[184:187], v[204:207], v[96:99]
	v_mfma_f32_16x16x32_bf16 v[84:87], v[176:179], v[212:215], v[84:87]
	v_mfma_f32_16x16x32_bf16 v[80:83], v[184:187], v[212:215], v[80:83]
	v_mfma_f32_16x16x32_bf16 v[68:71], v[176:179], v[220:223], v[68:71]
	v_mfma_f32_16x16x32_bf16 v[64:67], v[184:187], v[220:223], v[64:67]
	s_setprio 0
	s_barrier
	s_add_i32 s36, s62, s42
	v_lshl_add_u64 v[188:189], v[188:189], 0, s[16:17]
	s_mov_b32 m0, s36
	ds_read_b128 v[192:195], v165 offset:49152
	ds_read_b128 v[196:199], v165 offset:50176
	ds_read_b128 v[200:203], v165 offset:51200
	ds_read_b128 v[204:207], v165 offset:52224
	ds_read_b128 v[208:211], v165 offset:53248
	ds_read_b128 v[212:215], v165 offset:54272
	ds_read_b128 v[216:219], v165 offset:55296
	ds_read_b128 v[220:223], v165 offset:56320
	global_load_lds_dwordx4 v[188:189], off
	s_add_i32 m0, s36, 0x2000
	s_add_u32 s34, s34, 0x40080
	v_lshl_add_u64 v[188:189], v[224:225], 0, s[16:17]
	s_addc_u32 s35, s35, 0
	s_add_i32 s36, s63, s42
	global_load_lds_dwordx4 v[188:189], off
	v_lshl_add_u64 v[188:189], s[34:35], 0, v[132:133]
	s_mov_b32 m0, s36
	s_nop 0
	global_load_lds_dwordx4 v[188:189], off
	v_lshl_add_u64 v[188:189], s[34:35], 0, v[128:129]
	s_add_i32 m0, s36, 0x2000
	s_nop 0
	global_load_lds_dwordx4 v[188:189], off
	v_lshl_add_u64 v[188:189], v[226:227], 0, s[16:17]
	s_mov_b32 m0, s49
	s_nop 0
	global_load_lds_dwordx4 v[188:189], off
	v_lshl_add_u64 v[188:189], v[228:229], 0, s[16:17]
	s_mov_b32 m0, s50
	s_nop 0
	global_load_lds_dwordx4 v[188:189], off
	s_waitcnt vmcnt(8)
	s_waitcnt lgkmcnt(0)
	s_barrier
	s_setprio 1
	s_waitcnt lgkmcnt(0)
	v_mfma_f32_16x16x32_bf16 v[60:63], v[150:153], v[192:195], v[60:63]
	v_mfma_f32_16x16x32_bf16 v[56:59], v[158:161], v[192:195], v[56:59]
	v_mfma_f32_16x16x32_bf16 v[44:47], v[150:153], v[200:203], v[44:47]
	v_mfma_f32_16x16x32_bf16 v[40:43], v[158:161], v[200:203], v[40:43]
	v_mfma_f32_16x16x32_bf16 v[28:31], v[150:153], v[208:211], v[28:31]
	v_mfma_f32_16x16x32_bf16 v[24:27], v[158:161], v[208:211], v[24:27]
	v_mfma_f32_16x16x32_bf16 v[12:15], v[150:153], v[216:219], v[12:15]
	v_mfma_f32_16x16x32_bf16 v[8:11], v[158:161], v[216:219], v[8:11]
	v_mfma_f32_16x16x32_bf16 v[60:63], v[154:157], v[196:199], v[60:63]
	v_mfma_f32_16x16x32_bf16 v[56:59], v[168:171], v[196:199], v[56:59]
	v_mfma_f32_16x16x32_bf16 v[44:47], v[154:157], v[204:207], v[44:47]
	v_mfma_f32_16x16x32_bf16 v[40:43], v[168:171], v[204:207], v[40:43]
	v_mfma_f32_16x16x32_bf16 v[28:31], v[154:157], v[212:215], v[28:31]
	v_mfma_f32_16x16x32_bf16 v[24:27], v[168:171], v[212:215], v[24:27]
	v_mfma_f32_16x16x32_bf16 v[12:15], v[154:157], v[220:223], v[12:15]
	v_mfma_f32_16x16x32_bf16 v[8:11], v[168:171], v[220:223], v[8:11]
	s_setprio 0
	s_setprio 1
	v_mfma_f32_16x16x32_bf16 v[52:55], v[172:175], v[192:195], v[52:55]
	v_mfma_f32_16x16x32_bf16 v[48:51], v[180:183], v[192:195], v[48:51]
	v_mfma_f32_16x16x32_bf16 v[36:39], v[172:175], v[200:203], v[36:39]
	v_mfma_f32_16x16x32_bf16 v[32:35], v[180:183], v[200:203], v[32:35]
	v_mfma_f32_16x16x32_bf16 v[20:23], v[172:175], v[208:211], v[20:23]
	v_mfma_f32_16x16x32_bf16 v[16:19], v[180:183], v[208:211], v[16:19]
	v_mfma_f32_16x16x32_bf16 v[4:7], v[172:175], v[216:219], v[4:7]
	v_mfma_f32_16x16x32_bf16 v[0:3], v[180:183], v[216:219], v[0:3]
	v_mfma_f32_16x16x32_bf16 v[52:55], v[176:179], v[196:199], v[52:55]
	v_mfma_f32_16x16x32_bf16 v[48:51], v[184:187], v[196:199], v[48:51]
	v_mfma_f32_16x16x32_bf16 v[36:39], v[176:179], v[204:207], v[36:39]
	v_mfma_f32_16x16x32_bf16 v[32:35], v[184:187], v[204:207], v[32:35]
	v_mfma_f32_16x16x32_bf16 v[20:23], v[176:179], v[212:215], v[20:23]
	v_mfma_f32_16x16x32_bf16 v[16:19], v[184:187], v[212:215], v[16:19]
	v_mfma_f32_16x16x32_bf16 v[4:7], v[176:179], v[220:223], v[4:7]
	v_mfma_f32_16x16x32_bf16 v[0:3], v[184:187], v[220:223], v[0:3]
	s_setprio 0
	s_add_i32 s61, s61, 2
	s_add_u32 s33, s33, 0x100
	s_addc_u32 s60, s60, 0
	s_add_u32 s30, s30, 0x100
	s_addc_u32 s31, s31, 0
	s_cmp_gt_u32 s61, 13
	s_barrier
	s_cbranch_scc0 .LBB0_1917
	v_lshl_add_u32 v214, s0, 8, v139
	v_ashrrev_i32_e32 v215, 31, v214
	v_lshl_add_u64 v[212:213], v[214:215], 2, s[14:15]
	global_load_dword v204, v[212:213], off
	global_load_dword v205, v[212:213], off offset:64
	global_load_dword v206, v[212:213], off offset:128
	global_load_dword v207, v[212:213], off offset:192
	global_load_dword v208, v[212:213], off offset:512
	global_load_dword v209, v[212:213], off offset:576
	global_load_dword v210, v[212:213], off offset:640
	global_load_dword v211, v[212:213], off offset:704
	s_and_b64 vcc, exec, s[18:19]
	s_cbranch_vccz .LBB0_1920
	s_barrier

.LBB0_1998:
	ds_read_b128 v[128:131], v171
	ds_read_b128 v[132:135], v171 offset:1024
	ds_read_b128 v[136:139], v171 offset:2048
	ds_read_b128 v[140:143], v171 offset:3072
	ds_read_b128 v[156:159], v172
	ds_read_b128 v[160:163], v172 offset:1024
	ds_read_b128 v[164:167], v172 offset:2048
	ds_read_b128 v[176:179], v172 offset:3072
	s_add_u32 s24, s22, 0x100
	s_addc_u32 s25, s23, 0
	s_cmp_eq_u32 s55, 40
	s_cselect_b32 s29, s7, s25
	s_cselect_b32 s28, s6, s24
	s_cselect_b32 s27, s21, s54
	s_cselect_b32 s26, s20, s53
	v_lshl_add_u64 v[188:189], s[22:23], 0, v[150:151]
	s_add_i32 m0, s36, 0xc000
	ds_read_b128 v[180:183], v173
	ds_read_b128 v[184:187], v173 offset:1024
	ds_read_b128 v[192:195], v173 offset:2048
	ds_read_b128 v[196:199], v173 offset:3072
	ds_read_b128 v[200:203], v173 offset:4096
	ds_read_b128 v[204:207], v173 offset:5120
	ds_read_b128 v[208:211], v173 offset:6144
	ds_read_b128 v[212:215], v173 offset:7168
	global_load_lds_dwordx4 v[188:189], off
	v_lshl_add_u64 v[188:189], s[22:23], 0, v[148:149]
	s_add_i32 m0, s36, 0xe000
	s_nop 0
	global_load_lds_dwordx4 v[188:189], off
	s_waitcnt vmcnt(8)
	s_waitcnt lgkmcnt(0)
	s_barrier
	s_setprio 1
	s_waitcnt lgkmcnt(0)
	v_mfma_f32_16x16x32_bf16 v[124:127], v[128:131], v[180:183], v[124:127]
	v_mfma_f32_16x16x32_bf16 v[120:123], v[136:139], v[180:183], v[120:123]
	v_mfma_f32_16x16x32_bf16 v[108:111], v[128:131], v[192:195], v[108:111]
	v_mfma_f32_16x16x32_bf16 v[104:107], v[136:139], v[192:195], v[104:107]
	v_mfma_f32_16x16x32_bf16 v[92:95], v[128:131], v[200:203], v[92:95]
	v_mfma_f32_16x16x32_bf16 v[88:91], v[136:139], v[200:203], v[88:91]
	v_mfma_f32_16x16x32_bf16 v[76:79], v[128:131], v[208:211], v[76:79]
	v_mfma_f32_16x16x32_bf16 v[72:75], v[136:139], v[208:211], v[72:75]
	v_mfma_f32_16x16x32_bf16 v[124:127], v[132:135], v[184:187], v[124:127]
	v_mfma_f32_16x16x32_bf16 v[120:123], v[140:143], v[184:187], v[120:123]
	v_mfma_f32_16x16x32_bf16 v[108:111], v[132:135], v[196:199], v[108:111]
	v_mfma_f32_16x16x32_bf16 v[104:107], v[140:143], v[196:199], v[104:107]
	v_mfma_f32_16x16x32_bf16 v[92:95], v[132:135], v[204:207], v[92:95]
	v_mfma_f32_16x16x32_bf16 v[88:91], v[140:143], v[204:207], v[88:91]
	v_mfma_f32_16x16x32_bf16 v[76:79], v[132:135], v[212:215], v[76:79]
	v_mfma_f32_16x16x32_bf16 v[72:75], v[140:143], v[212:215], v[72:75]
	s_setprio 0
	s_setprio 1
	v_mfma_f32_16x16x32_bf16 v[116:119], v[156:159], v[180:183], v[116:119]
	v_mfma_f32_16x16x32_bf16 v[112:115], v[164:167], v[180:183], v[112:115]
	v_mfma_f32_16x16x32_bf16 v[100:103], v[156:159], v[192:195], v[100:103]
	v_mfma_f32_16x16x32_bf16 v[96:99], v[164:167], v[192:195], v[96:99]
	v_mfma_f32_16x16x32_bf16 v[84:87], v[156:159], v[200:203], v[84:87]
	v_mfma_f32_16x16x32_bf16 v[80:83], v[164:167], v[200:203], v[80:83]
	v_mfma_f32_16x16x32_bf16 v[68:71], v[156:159], v[208:211], v[68:71]
	v_mfma_f32_16x16x32_bf16 v[64:67], v[164:167], v[208:211], v[64:67]
	v_mfma_f32_16x16x32_bf16 v[116:119], v[160:163], v[184:187], v[116:119]
	v_mfma_f32_16x16x32_bf16 v[112:115], v[176:179], v[184:187], v[112:115]
	v_mfma_f32_16x16x32_bf16 v[100:103], v[160:163], v[196:199], v[100:103]
	v_mfma_f32_16x16x32_bf16 v[96:99], v[176:179], v[196:199], v[96:99]
	v_mfma_f32_16x16x32_bf16 v[84:87], v[160:163], v[204:207], v[84:87]
	v_mfma_f32_16x16x32_bf16 v[80:83], v[176:179], v[204:207], v[80:83]
	v_mfma_f32_16x16x32_bf16 v[68:71], v[160:163], v[212:215], v[68:71]
	v_mfma_f32_16x16x32_bf16 v[64:67], v[176:179], v[212:215], v[64:67]
	s_setprio 0
	s_barrier
	s_add_i32 s22, s47, s35
	v_lshl_add_u64 v[188:189], s[26:27], 0, v[144:145]
	s_mov_b32 m0, s22
	ds_read_b128 v[180:183], v173 offset:16384
	ds_read_b128 v[184:187], v173 offset:17408
	ds_read_b128 v[192:195], v173 offset:18432
	ds_read_b128 v[196:199], v173 offset:19456
	ds_read_b128 v[200:203], v173 offset:20480
	ds_read_b128 v[204:207], v173 offset:21504
	ds_read_b128 v[208:211], v173 offset:22528
	ds_read_b128 v[212:215], v173 offset:23552
	global_load_lds_dwordx4 v[188:189], off
	s_add_i32 m0, s22, 0x2000
	s_add_u32 s22, s26, 0xb0000
	v_lshl_add_u64 v[216:217], s[26:27], 0, v[146:147]
	s_addc_u32 s23, s27, 0
	s_add_i32 s56, s48, s35
	global_load_lds_dwordx4 v[216:217], off
	v_lshl_add_u64 v[218:219], s[22:23], 0, v[144:145]
	s_mov_b32 m0, s56
	v_lshl_add_u64 v[220:221], s[28:29], 0, v[146:147]
	global_load_lds_dwordx4 v[218:219], off
	v_lshl_add_u64 v[218:219], s[22:23], 0, v[146:147]
	s_add_i32 m0, s56, 0x2000
	s_nop 0
	global_load_lds_dwordx4 v[218:219], off
	v_lshl_add_u64 v[218:219], s[28:29], 0, v[144:145]
	s_mov_b32 m0, s36
	s_nop 0
	global_load_lds_dwordx4 v[218:219], off
	s_mov_b32 m0, s37
	s_nop 0
	global_load_lds_dwordx4 v[220:221], off
	s_waitcnt vmcnt(8)
	s_waitcnt lgkmcnt(0)
	s_barrier
	s_setprio 1
	s_waitcnt lgkmcnt(0)
	v_mfma_f32_16x16x32_bf16 v[60:63], v[128:131], v[180:183], v[60:63]
	v_mfma_f32_16x16x32_bf16 v[56:59], v[136:139], v[180:183], v[56:59]
	v_mfma_f32_16x16x32_bf16 v[44:47], v[128:131], v[192:195], v[44:47]
	v_mfma_f32_16x16x32_bf16 v[40:43], v[136:139], v[192:195], v[40:43]
	v_mfma_f32_16x16x32_bf16 v[28:31], v[128:131], v[200:203], v[28:31]
	v_mfma_f32_16x16x32_bf16 v[24:27], v[136:139], v[200:203], v[24:27]
	v_mfma_f32_16x16x32_bf16 v[12:15], v[128:131], v[208:211], v[12:15]
	v_mfma_f32_16x16x32_bf16 v[8:11], v[136:139], v[208:211], v[8:11]
	v_mfma_f32_16x16x32_bf16 v[60:63], v[132:135], v[184:187], v[60:63]
	v_mfma_f32_16x16x32_bf16 v[56:59], v[140:143], v[184:187], v[56:59]
	v_mfma_f32_16x16x32_bf16 v[44:47], v[132:135], v[196:199], v[44:47]
	v_mfma_f32_16x16x32_bf16 v[40:43], v[140:143], v[196:199], v[40:43]
	v_mfma_f32_16x16x32_bf16 v[28:31], v[132:135], v[204:207], v[28:31]
	v_mfma_f32_16x16x32_bf16 v[24:27], v[140:143], v[204:207], v[24:27]
	v_mfma_f32_16x16x32_bf16 v[12:15], v[132:135], v[212:215], v[12:15]
	v_mfma_f32_16x16x32_bf16 v[8:11], v[140:143], v[212:215], v[8:11]
	s_setprio 0
	s_setprio 1
	v_mfma_f32_16x16x32_bf16 v[52:55], v[156:159], v[180:183], v[52:55]
	v_mfma_f32_16x16x32_bf16 v[48:51], v[164:167], v[180:183], v[48:51]
	v_mfma_f32_16x16x32_bf16 v[36:39], v[156:159], v[192:195], v[36:39]
	v_mfma_f32_16x16x32_bf16 v[32:35], v[164:167], v[192:195], v[32:35]
	v_mfma_f32_16x16x32_bf16 v[20:23], v[156:159], v[200:203], v[20:23]
	v_mfma_f32_16x16x32_bf16 v[16:19], v[164:167], v[200:203], v[16:19]
	v_mfma_f32_16x16x32_bf16 v[4:7], v[156:159], v[208:211], v[4:7]
	v_mfma_f32_16x16x32_bf16 v[0:3], v[164:167], v[208:211], v[0:3]
	v_mfma_f32_16x16x32_bf16 v[52:55], v[160:163], v[184:187], v[52:55]
	v_mfma_f32_16x16x32_bf16 v[48:51], v[176:179], v[184:187], v[48:51]
	v_mfma_f32_16x16x32_bf16 v[36:39], v[160:163], v[196:199], v[36:39]
	v_mfma_f32_16x16x32_bf16 v[32:35], v[176:179], v[196:199], v[32:35]
	v_mfma_f32_16x16x32_bf16 v[20:23], v[160:163], v[204:207], v[20:23]
	v_mfma_f32_16x16x32_bf16 v[16:19], v[176:179], v[204:207], v[16:19]
	v_mfma_f32_16x16x32_bf16 v[4:7], v[160:163], v[212:215], v[4:7]
	v_mfma_f32_16x16x32_bf16 v[0:3], v[176:179], v[212:215], v[0:3]
	s_setprio 0
	s_barrier
	s_add_i32 s56, 0, 0x18000
	s_add_i32 s57, 0, 0x1c000
	v_add_u32_e32 v140, s56, v169
	v_add_u32_e32 v175, s57, v169
	ds_read_b128 v[128:131], v140
	ds_read_b128 v[132:135], v140 offset:1024
	ds_read_b128 v[136:139], v140 offset:2048
	ds_read_b128 v[140:143], v140 offset:3072
	ds_read_b128 v[156:159], v175
	ds_read_b128 v[160:163], v175 offset:1024
	ds_read_b128 v[164:167], v175 offset:2048
	ds_read_b128 v[176:179], v175 offset:3072
	s_add_u32 s22, s28, 0xb0000
	s_addc_u32 s23, s29, 0
	s_mov_b32 m0, s38
	v_lshl_add_u64 v[222:223], s[22:23], 0, v[144:145]
	ds_read_b128 v[180:183], v173 offset:32768
	ds_read_b128 v[184:187], v173 offset:33792
	ds_read_b128 v[192:195], v173 offset:34816
	ds_read_b128 v[196:199], v173 offset:35840
	ds_read_b128 v[200:203], v173 offset:36864
	ds_read_b128 v[204:207], v173 offset:37888
	ds_read_b128 v[208:211], v173 offset:38912
	ds_read_b128 v[212:215], v173 offset:39936
	global_load_lds_dwordx4 v[222:223], off
	v_lshl_add_u64 v[222:223], s[22:23], 0, v[146:147]
	s_mov_b32 m0, s39
	s_nop 0
	global_load_lds_dwordx4 v[222:223], off
	s_waitcnt vmcnt(8)
	s_waitcnt lgkmcnt(0)
	s_barrier
	s_setprio 1
	s_waitcnt lgkmcnt(0)
	v_mfma_f32_16x16x32_bf16 v[124:127], v[128:131], v[180:183], v[124:127]
	v_mfma_f32_16x16x32_bf16 v[120:123], v[136:139], v[180:183], v[120:123]
	v_mfma_f32_16x16x32_bf16 v[108:111], v[128:131], v[192:195], v[108:111]
	v_mfma_f32_16x16x32_bf16 v[104:107], v[136:139], v[192:195], v[104:107]
	v_mfma_f32_16x16x32_bf16 v[92:95], v[128:131], v[200:203], v[92:95]
	v_mfma_f32_16x16x32_bf16 v[88:91], v[136:139], v[200:203], v[88:91]
	v_mfma_f32_16x16x32_bf16 v[76:79], v[128:131], v[208:211], v[76:79]
	v_mfma_f32_16x16x32_bf16 v[72:75], v[136:139], v[208:211], v[72:75]
	v_mfma_f32_16x16x32_bf16 v[124:127], v[132:135], v[184:187], v[124:127]
	v_mfma_f32_16x16x32_bf16 v[120:123], v[140:143], v[184:187], v[120:123]
	v_mfma_f32_16x16x32_bf16 v[108:111], v[132:135], v[196:199], v[108:111]
	v_mfma_f32_16x16x32_bf16 v[104:107], v[140:143], v[196:199], v[104:107]
	v_mfma_f32_16x16x32_bf16 v[92:95], v[132:135], v[204:207], v[92:95]
	v_mfma_f32_16x16x32_bf16 v[88:91], v[140:143], v[204:207], v[88:91]
	v_mfma_f32_16x16x32_bf16 v[76:79], v[132:135], v[212:215], v[76:79]
	v_mfma_f32_16x16x32_bf16 v[72:75], v[140:143], v[212:215], v[72:75]
	s_setprio 0
	s_setprio 1
	v_mfma_f32_16x16x32_bf16 v[116:119], v[156:159], v[180:183], v[116:119]
	v_mfma_f32_16x16x32_bf16 v[112:115], v[164:167], v[180:183], v[112:115]
	v_mfma_f32_16x16x32_bf16 v[100:103], v[156:159], v[192:195], v[100:103]
	v_mfma_f32_16x16x32_bf16 v[96:99], v[164:167], v[192:195], v[96:99]
	v_mfma_f32_16x16x32_bf16 v[84:87], v[156:159], v[200:203], v[84:87]
	v_mfma_f32_16x16x32_bf16 v[80:83], v[164:167], v[200:203], v[80:83]
	v_mfma_f32_16x16x32_bf16 v[68:71], v[156:159], v[208:211], v[68:71]
	v_mfma_f32_16x16x32_bf16 v[64:67], v[164:167], v[208:211], v[64:67]
	v_mfma_f32_16x16x32_bf16 v[116:119], v[160:163], v[184:187], v[116:119]
	v_mfma_f32_16x16x32_bf16 v[112:115], v[176:179], v[184:187], v[112:115]
	v_mfma_f32_16x16x32_bf16 v[100:103], v[160:163], v[196:199], v[100:103]
	v_mfma_f32_16x16x32_bf16 v[96:99], v[176:179], v[196:199], v[96:99]
	v_mfma_f32_16x16x32_bf16 v[84:87], v[160:163], v[204:207], v[84:87]
	v_mfma_f32_16x16x32_bf16 v[80:83], v[176:179], v[204:207], v[80:83]
	v_mfma_f32_16x16x32_bf16 v[68:71], v[160:163], v[212:215], v[68:71]
	v_mfma_f32_16x16x32_bf16 v[64:67], v[176:179], v[212:215], v[64:67]
	s_setprio 0
	s_barrier
	s_add_i32 s22, s56, s35
	v_lshl_add_u64 v[188:189], v[188:189], 0, s[16:17]
	s_mov_b32 m0, s22
	ds_read_b128 v[180:183], v173 offset:49152
	ds_read_b128 v[184:187], v173 offset:50176
	ds_read_b128 v[192:195], v173 offset:51200
	ds_read_b128 v[196:199], v173 offset:52224
	ds_read_b128 v[200:203], v173 offset:53248
	ds_read_b128 v[204:207], v173 offset:54272
	ds_read_b128 v[208:211], v173 offset:55296
	ds_read_b128 v[212:215], v173 offset:56320
	global_load_lds_dwordx4 v[188:189], off
	s_add_i32 m0, s22, 0x2000
	s_add_u32 s22, s26, 0xb0080
	v_lshl_add_u64 v[188:189], v[216:217], 0, s[16:17]
	s_addc_u32 s23, s27, 0
	s_add_i32 s26, s57, s35
	global_load_lds_dwordx4 v[188:189], off
	v_lshl_add_u64 v[188:189], s[22:23], 0, v[144:145]
	s_mov_b32 m0, s26
	s_nop 0
	global_load_lds_dwordx4 v[188:189], off
	v_lshl_add_u64 v[188:189], s[22:23], 0, v[146:147]
	s_add_i32 m0, s26, 0x2000
	s_nop 0
	global_load_lds_dwordx4 v[188:189], off
	v_lshl_add_u64 v[188:189], v[218:219], 0, s[16:17]
	s_mov_b32 m0, s41
	s_nop 0
	global_load_lds_dwordx4 v[188:189], off
	v_lshl_add_u64 v[188:189], v[220:221], 0, s[16:17]
	s_mov_b32 m0, s42
	s_nop 0
	global_load_lds_dwordx4 v[188:189], off
	s_waitcnt vmcnt(8)
	s_waitcnt lgkmcnt(0)
	s_barrier
	s_setprio 1
	s_waitcnt lgkmcnt(0)
	v_mfma_f32_16x16x32_bf16 v[60:63], v[128:131], v[180:183], v[60:63]
	v_mfma_f32_16x16x32_bf16 v[56:59], v[136:139], v[180:183], v[56:59]
	v_mfma_f32_16x16x32_bf16 v[44:47], v[128:131], v[192:195], v[44:47]
	v_mfma_f32_16x16x32_bf16 v[40:43], v[136:139], v[192:195], v[40:43]
	v_mfma_f32_16x16x32_bf16 v[28:31], v[128:131], v[200:203], v[28:31]
	v_mfma_f32_16x16x32_bf16 v[24:27], v[136:139], v[200:203], v[24:27]
	v_mfma_f32_16x16x32_bf16 v[12:15], v[128:131], v[208:211], v[12:15]
	v_mfma_f32_16x16x32_bf16 v[8:11], v[136:139], v[208:211], v[8:11]
	v_mfma_f32_16x16x32_bf16 v[60:63], v[132:135], v[184:187], v[60:63]
	v_mfma_f32_16x16x32_bf16 v[56:59], v[140:143], v[184:187], v[56:59]
	v_mfma_f32_16x16x32_bf16 v[44:47], v[132:135], v[196:199], v[44:47]
	v_mfma_f32_16x16x32_bf16 v[40:43], v[140:143], v[196:199], v[40:43]
	v_mfma_f32_16x16x32_bf16 v[28:31], v[132:135], v[204:207], v[28:31]
	v_mfma_f32_16x16x32_bf16 v[24:27], v[140:143], v[204:207], v[24:27]
	v_mfma_f32_16x16x32_bf16 v[12:15], v[132:135], v[212:215], v[12:15]
	v_mfma_f32_16x16x32_bf16 v[8:11], v[140:143], v[212:215], v[8:11]
	s_setprio 0
	s_setprio 1
	v_mfma_f32_16x16x32_bf16 v[52:55], v[156:159], v[180:183], v[52:55]
	v_mfma_f32_16x16x32_bf16 v[48:51], v[164:167], v[180:183], v[48:51]
	v_mfma_f32_16x16x32_bf16 v[36:39], v[156:159], v[192:195], v[36:39]
	v_mfma_f32_16x16x32_bf16 v[32:35], v[164:167], v[192:195], v[32:35]
	v_mfma_f32_16x16x32_bf16 v[20:23], v[156:159], v[200:203], v[20:23]
	v_mfma_f32_16x16x32_bf16 v[16:19], v[164:167], v[200:203], v[16:19]
	v_mfma_f32_16x16x32_bf16 v[4:7], v[156:159], v[208:211], v[4:7]
	v_mfma_f32_16x16x32_bf16 v[0:3], v[164:167], v[208:211], v[0:3]
	v_mfma_f32_16x16x32_bf16 v[52:55], v[160:163], v[184:187], v[52:55]
	v_mfma_f32_16x16x32_bf16 v[48:51], v[176:179], v[184:187], v[48:51]
	v_mfma_f32_16x16x32_bf16 v[36:39], v[160:163], v[196:199], v[36:39]
	v_mfma_f32_16x16x32_bf16 v[32:35], v[176:179], v[196:199], v[32:35]
	v_mfma_f32_16x16x32_bf16 v[20:23], v[160:163], v[204:207], v[20:23]
	v_mfma_f32_16x16x32_bf16 v[16:19], v[176:179], v[204:207], v[16:19]
	v_mfma_f32_16x16x32_bf16 v[4:7], v[160:163], v[212:215], v[4:7]
	v_mfma_f32_16x16x32_bf16 v[0:3], v[176:179], v[212:215], v[0:3]
	s_setprio 0
	s_add_i32 s55, s55, 2
	s_add_u32 s53, s53, 0x100
	s_addc_u32 s54, s54, 0
	s_cmp_gt_u32 s55, 41
	s_mov_b64 s[22:23], s[24:25]
	s_barrier
	s_cbranch_scc0 .LBB0_1998
	v_mbcnt_lo_u32_b32 v235, -1, 0
	v_mbcnt_hi_u32_b32 v235, -1, v235
	v_lshrrev_b32_e32 v236, 2, v235
	v_and_b32_e32 v237, 3, v235
	v_lshl_add_u32 v232, v237, 4, v236
	v_lshlrev_b32_e32 v232, 2, v232
	v_and_b32_e32 v233, -16, v168
	v_or_b32_e32 v233, v233, v236
	v_lshlrev_b32_e32 v237, 2, v237
	v_and_b32_e32 v234, -13, v170
	v_or_b32_e32 v234, v234, v237
	v_lshl_add_u32 v158, s52, 8, v233
	v_lshl_or_b32 v156, s51, 8, v234
	v_ashrrev_i32_e32 v159, 31, v158
	v_lshlrev_b64 v[128:129], 12, v[158:159]
	v_ashrrev_i32_e32 v157, 31, v156
	v_lshl_add_u64 v[128:129], s[8:9], 0, v[128:129]
	v_lshlrev_b64 v[130:131], 2, v[156:157]
	v_lshl_add_u64 v[188:189], v[128:129], 0, v[130:131]
	global_load_dwordx4 v[164:167], v[188:189], off
	global_load_dwordx4 v[176:179], v[188:189], off offset:64
	global_load_dwordx4 v[180:183], v[188:189], off offset:512
	global_load_dwordx4 v[184:187], v[188:189], off offset:576
	v_or_b32_e32 v160, 16, v158
	v_ashrrev_i32_e32 v161, 31, v160
	v_lshlrev_b64 v[128:129], 12, v[160:161]
	v_lshl_add_u64 v[128:129], s[8:9], 0, v[128:129]
	v_lshl_add_u64 v[162:163], v[128:129], 0, v[130:131]
	global_load_dwordx4 v[140:143], v[162:163], off
	global_load_dwordx4 v[136:139], v[162:163], off offset:64
	global_load_dwordx4 v[132:135], v[162:163], off offset:512
	global_load_dwordx4 v[128:131], v[162:163], off offset:576
	v_lshlrev_b64 v[192:193], 11, v[158:159]
	v_lshl_add_u64 v[192:193], s[12:13], 0, v[192:193]
	v_and_b32_e32 v191, 64, v174
	v_lshl_add_u64 v[192:193], v[156:157], 1, v[192:193]
	v_xor_b32_e32 v175, 1, v174
	v_add_u32_e32 v191, 64, v191
	v_cmp_lt_i32_e32 vcc, v175, v191
	v_xor_b32_e32 v194, 2, v174
	ds_bpermute_b32 v127, v232, v127
	ds_bpermute_b32 v126, v232, v126
	ds_bpermute_b32 v125, v232, v125
	ds_bpermute_b32 v124, v232, v124
	ds_bpermute_b32 v123, v232, v123
	ds_bpermute_b32 v122, v232, v122
	ds_bpermute_b32 v121, v232, v121
	ds_bpermute_b32 v120, v232, v120
	ds_bpermute_b32 v119, v232, v119
	ds_bpermute_b32 v118, v232, v118
	ds_bpermute_b32 v117, v232, v117
	ds_bpermute_b32 v116, v232, v116
	ds_bpermute_b32 v115, v232, v115
	ds_bpermute_b32 v114, v232, v114
	ds_bpermute_b32 v113, v232, v113
	ds_bpermute_b32 v112, v232, v112
	ds_bpermute_b32 v111, v232, v111
	ds_bpermute_b32 v110, v232, v110
	ds_bpermute_b32 v109, v232, v109
	ds_bpermute_b32 v108, v232, v108
	ds_bpermute_b32 v107, v232, v107
	ds_bpermute_b32 v106, v232, v106
	ds_bpermute_b32 v105, v232, v105
	ds_bpermute_b32 v104, v232, v104
	ds_bpermute_b32 v103, v232, v103
	ds_bpermute_b32 v102, v232, v102
	ds_bpermute_b32 v101, v232, v101
	ds_bpermute_b32 v100, v232, v100
	ds_bpermute_b32 v99, v232, v99
	ds_bpermute_b32 v98, v232, v98
	ds_bpermute_b32 v97, v232, v97
	ds_bpermute_b32 v96, v232, v96
	ds_bpermute_b32 v95, v232, v95
	ds_bpermute_b32 v94, v232, v94
	ds_bpermute_b32 v93, v232, v93
	ds_bpermute_b32 v92, v232, v92
	ds_bpermute_b32 v91, v232, v91
	ds_bpermute_b32 v90, v232, v90
	ds_bpermute_b32 v89, v232, v89
	ds_bpermute_b32 v88, v232, v88
	ds_bpermute_b32 v87, v232, v87
	ds_bpermute_b32 v86, v232, v86
	ds_bpermute_b32 v85, v232, v85
	ds_bpermute_b32 v84, v232, v84
	ds_bpermute_b32 v83, v232, v83
	ds_bpermute_b32 v82, v232, v82
	ds_bpermute_b32 v81, v232, v81
	ds_bpermute_b32 v80, v232, v80
	ds_bpermute_b32 v79, v232, v79
	ds_bpermute_b32 v78, v232, v78
	ds_bpermute_b32 v77, v232, v77
	ds_bpermute_b32 v76, v232, v76
	ds_bpermute_b32 v75, v232, v75
	ds_bpermute_b32 v74, v232, v74
	ds_bpermute_b32 v73, v232, v73
	ds_bpermute_b32 v72, v232, v72
	ds_bpermute_b32 v71, v232, v71
	ds_bpermute_b32 v70, v232, v70
	ds_bpermute_b32 v69, v232, v69
	ds_bpermute_b32 v68, v232, v68
	ds_bpermute_b32 v67, v232, v67
	ds_bpermute_b32 v66, v232, v66
	ds_bpermute_b32 v65, v232, v65
	ds_bpermute_b32 v64, v232, v64
	ds_bpermute_b32 v63, v232, v63
	ds_bpermute_b32 v62, v232, v62
	ds_bpermute_b32 v61, v232, v61
	ds_bpermute_b32 v60, v232, v60
	ds_bpermute_b32 v59, v232, v59
	ds_bpermute_b32 v58, v232, v58
	ds_bpermute_b32 v57, v232, v57
	ds_bpermute_b32 v56, v232, v56
	ds_bpermute_b32 v55, v232, v55
	ds_bpermute_b32 v54, v232, v54
	ds_bpermute_b32 v53, v232, v53
	ds_bpermute_b32 v52, v232, v52
	ds_bpermute_b32 v51, v232, v51
	ds_bpermute_b32 v50, v232, v50
	ds_bpermute_b32 v49, v232, v49
	ds_bpermute_b32 v48, v232, v48
	ds_bpermute_b32 v47, v232, v47
	ds_bpermute_b32 v46, v232, v46
	ds_bpermute_b32 v45, v232, v45
	ds_bpermute_b32 v44, v232, v44
	ds_bpermute_b32 v43, v232, v43
	ds_bpermute_b32 v42, v232, v42
	ds_bpermute_b32 v41, v232, v41
	ds_bpermute_b32 v40, v232, v40
	ds_bpermute_b32 v39, v232, v39
	ds_bpermute_b32 v38, v232, v38
	ds_bpermute_b32 v37, v232, v37
	ds_bpermute_b32 v36, v232, v36
	ds_bpermute_b32 v35, v232, v35
	ds_bpermute_b32 v34, v232, v34
	ds_bpermute_b32 v33, v232, v33
	ds_bpermute_b32 v32, v232, v32
	ds_bpermute_b32 v31, v232, v31
	ds_bpermute_b32 v30, v232, v30
	ds_bpermute_b32 v29, v232, v29
	ds_bpermute_b32 v28, v232, v28
	ds_bpermute_b32 v27, v232, v27
	ds_bpermute_b32 v26, v232, v26
	ds_bpermute_b32 v25, v232, v25
	ds_bpermute_b32 v24, v232, v24
	ds_bpermute_b32 v23, v232, v23
	ds_bpermute_b32 v22, v232, v22
	ds_bpermute_b32 v21, v232, v21
	ds_bpermute_b32 v20, v232, v20
	ds_bpermute_b32 v19, v232, v19
	ds_bpermute_b32 v18, v232, v18
	ds_bpermute_b32 v17, v232, v17
	ds_bpermute_b32 v16, v232, v16
	ds_bpermute_b32 v15, v232, v15
	ds_bpermute_b32 v14, v232, v14
	ds_bpermute_b32 v13, v232, v13
	ds_bpermute_b32 v12, v232, v12
	ds_bpermute_b32 v11, v232, v11
	ds_bpermute_b32 v10, v232, v10
	ds_bpermute_b32 v9, v232, v9
	ds_bpermute_b32 v8, v232, v8
	ds_bpermute_b32 v7, v232, v7
	ds_bpermute_b32 v6, v232, v6
	ds_bpermute_b32 v5, v232, v5
	ds_bpermute_b32 v4, v232, v4
	ds_bpermute_b32 v3, v232, v3
	ds_bpermute_b32 v2, v232, v2
	ds_bpermute_b32 v1, v232, v1
	ds_bpermute_b32 v0, v232, v0
	s_waitcnt lgkmcnt(0)
	s_waitcnt lgkmcnt(0)
	s_cmp_eq_u64 s[18:19], 0
	s_cbranch_scc1 .LBB0_2001
	s_barrier

.LBB0_2118:
	ds_read_b128 v[128:131], v189
	ds_read_b128 v[132:135], v189 offset:1024
	ds_read_b128 v[136:139], v189 offset:2048
	ds_read_b128 v[140:143], v189 offset:3072
	ds_read_b128 v[156:159], v191
	ds_read_b128 v[160:163], v191 offset:1024
	ds_read_b128 v[164:167], v191 offset:2048
	ds_read_b128 v[168:171], v191 offset:3072
	s_add_u32 s34, s30, 0xfffc0080
	s_addc_u32 s35, s31, -1
	s_cmp_eq_u32 s58, 12
	s_cselect_b32 s37, s21, s35
	s_cselect_b32 s36, s27, s34
	s_cselect_b32 s35, s19, s57
	s_cselect_b32 s34, s33, s56
	v_lshl_add_u64 v[184:185], s[30:31], 0, v[150:151]
	s_add_i32 m0, s29, 0xc000
	ds_read_b128 v[172:175], v192
	ds_read_b128 v[176:179], v192 offset:1024
	ds_read_b128 v[180:183], v192 offset:2048
	ds_read_b128 v[196:199], v192 offset:3072
	ds_read_b128 v[200:203], v192 offset:4096
	ds_read_b128 v[204:207], v192 offset:5120
	ds_read_b128 v[208:211], v192 offset:6144
	ds_read_b128 v[212:215], v192 offset:7168
	global_load_lds_dwordx4 v[184:185], off
	v_lshl_add_u64 v[184:185], s[30:31], 0, v[148:149]
	s_add_i32 m0, s29, 0xe000
	s_nop 0
	global_load_lds_dwordx4 v[184:185], off
	s_waitcnt vmcnt(8)
	s_waitcnt lgkmcnt(0)
	s_barrier
	s_setprio 1
	s_waitcnt lgkmcnt(0)
	v_mfma_f32_16x16x32_bf16 v[124:127], v[128:131], v[172:175], v[124:127]
	v_mfma_f32_16x16x32_bf16 v[120:123], v[136:139], v[172:175], v[120:123]
	v_mfma_f32_16x16x32_bf16 v[108:111], v[128:131], v[180:183], v[108:111]
	v_mfma_f32_16x16x32_bf16 v[104:107], v[136:139], v[180:183], v[104:107]
	v_mfma_f32_16x16x32_bf16 v[92:95], v[128:131], v[200:203], v[92:95]
	v_mfma_f32_16x16x32_bf16 v[88:91], v[136:139], v[200:203], v[88:91]
	v_mfma_f32_16x16x32_bf16 v[76:79], v[128:131], v[208:211], v[76:79]
	v_mfma_f32_16x16x32_bf16 v[72:75], v[136:139], v[208:211], v[72:75]
	v_mfma_f32_16x16x32_bf16 v[124:127], v[132:135], v[176:179], v[124:127]
	v_mfma_f32_16x16x32_bf16 v[120:123], v[140:143], v[176:179], v[120:123]
	v_mfma_f32_16x16x32_bf16 v[108:111], v[132:135], v[196:199], v[108:111]
	v_mfma_f32_16x16x32_bf16 v[104:107], v[140:143], v[196:199], v[104:107]
	v_mfma_f32_16x16x32_bf16 v[92:95], v[132:135], v[204:207], v[92:95]
	v_mfma_f32_16x16x32_bf16 v[88:91], v[140:143], v[204:207], v[88:91]
	v_mfma_f32_16x16x32_bf16 v[76:79], v[132:135], v[212:215], v[76:79]
	v_mfma_f32_16x16x32_bf16 v[72:75], v[140:143], v[212:215], v[72:75]
	s_setprio 0
	s_setprio 1
	v_mfma_f32_16x16x32_bf16 v[116:119], v[156:159], v[172:175], v[116:119]
	v_mfma_f32_16x16x32_bf16 v[112:115], v[164:167], v[172:175], v[112:115]
	v_mfma_f32_16x16x32_bf16 v[100:103], v[156:159], v[180:183], v[100:103]
	v_mfma_f32_16x16x32_bf16 v[96:99], v[164:167], v[180:183], v[96:99]
	v_mfma_f32_16x16x32_bf16 v[84:87], v[156:159], v[200:203], v[84:87]
	v_mfma_f32_16x16x32_bf16 v[80:83], v[164:167], v[200:203], v[80:83]
	v_mfma_f32_16x16x32_bf16 v[68:71], v[156:159], v[208:211], v[68:71]
	v_mfma_f32_16x16x32_bf16 v[64:67], v[164:167], v[208:211], v[64:67]
	v_mfma_f32_16x16x32_bf16 v[116:119], v[160:163], v[176:179], v[116:119]
	v_mfma_f32_16x16x32_bf16 v[112:115], v[168:171], v[176:179], v[112:115]
	v_mfma_f32_16x16x32_bf16 v[100:103], v[160:163], v[196:199], v[100:103]
	v_mfma_f32_16x16x32_bf16 v[96:99], v[168:171], v[196:199], v[96:99]
	v_mfma_f32_16x16x32_bf16 v[84:87], v[160:163], v[204:207], v[84:87]
	v_mfma_f32_16x16x32_bf16 v[80:83], v[168:171], v[204:207], v[80:83]
	v_mfma_f32_16x16x32_bf16 v[68:71], v[160:163], v[212:215], v[68:71]
	v_mfma_f32_16x16x32_bf16 v[64:67], v[168:171], v[212:215], v[64:67]
	s_setprio 0
	s_barrier
	s_add_i32 s59, s53, s40
	v_lshl_add_u64 v[184:185], s[34:35], 0, v[144:145]
	s_mov_b32 m0, s59
	ds_read_b128 v[172:175], v192 offset:16384
	ds_read_b128 v[176:179], v192 offset:17408
	ds_read_b128 v[180:183], v192 offset:18432
	ds_read_b128 v[196:199], v192 offset:19456
	ds_read_b128 v[200:203], v192 offset:20480
	ds_read_b128 v[204:207], v192 offset:21504
	ds_read_b128 v[208:211], v192 offset:22528
	ds_read_b128 v[212:215], v192 offset:23552
	global_load_lds_dwordx4 v[184:185], off
	s_add_i32 m0, s59, 0x2000
	s_add_u32 s60, s34, 0x40000
	v_lshl_add_u64 v[216:217], s[34:35], 0, v[146:147]
	s_addc_u32 s61, s35, 0
	s_add_i32 s59, s54, s40
	global_load_lds_dwordx4 v[216:217], off
	v_lshl_add_u64 v[218:219], s[60:61], 0, v[144:145]
	s_mov_b32 m0, s59
	v_lshl_add_u64 v[220:221], s[36:37], 0, v[146:147]
	global_load_lds_dwordx4 v[218:219], off
	v_lshl_add_u64 v[218:219], s[60:61], 0, v[146:147]
	s_add_i32 m0, s59, 0x2000
	s_nop 0
	global_load_lds_dwordx4 v[218:219], off
	v_lshl_add_u64 v[218:219], s[36:37], 0, v[144:145]
	s_mov_b32 m0, s29
	s_nop 0
	global_load_lds_dwordx4 v[218:219], off
	s_mov_b32 m0, s43
	s_nop 0
	global_load_lds_dwordx4 v[220:221], off
	s_waitcnt vmcnt(8)
	s_waitcnt lgkmcnt(0)
	s_barrier
	s_setprio 1
	s_waitcnt lgkmcnt(0)
	v_mfma_f32_16x16x32_bf16 v[60:63], v[128:131], v[172:175], v[60:63]
	v_mfma_f32_16x16x32_bf16 v[56:59], v[136:139], v[172:175], v[56:59]
	v_mfma_f32_16x16x32_bf16 v[44:47], v[128:131], v[180:183], v[44:47]
	v_mfma_f32_16x16x32_bf16 v[40:43], v[136:139], v[180:183], v[40:43]
	v_mfma_f32_16x16x32_bf16 v[28:31], v[128:131], v[200:203], v[28:31]
	v_mfma_f32_16x16x32_bf16 v[24:27], v[136:139], v[200:203], v[24:27]
	v_mfma_f32_16x16x32_bf16 v[12:15], v[128:131], v[208:211], v[12:15]
	v_mfma_f32_16x16x32_bf16 v[8:11], v[136:139], v[208:211], v[8:11]
	v_mfma_f32_16x16x32_bf16 v[60:63], v[132:135], v[176:179], v[60:63]
	v_mfma_f32_16x16x32_bf16 v[56:59], v[140:143], v[176:179], v[56:59]
	v_mfma_f32_16x16x32_bf16 v[44:47], v[132:135], v[196:199], v[44:47]
	v_mfma_f32_16x16x32_bf16 v[40:43], v[140:143], v[196:199], v[40:43]
	v_mfma_f32_16x16x32_bf16 v[28:31], v[132:135], v[204:207], v[28:31]
	v_mfma_f32_16x16x32_bf16 v[24:27], v[140:143], v[204:207], v[24:27]
	v_mfma_f32_16x16x32_bf16 v[12:15], v[132:135], v[212:215], v[12:15]
	v_mfma_f32_16x16x32_bf16 v[8:11], v[140:143], v[212:215], v[8:11]
	s_setprio 0
	s_setprio 1
	v_mfma_f32_16x16x32_bf16 v[52:55], v[156:159], v[172:175], v[52:55]
	v_mfma_f32_16x16x32_bf16 v[48:51], v[164:167], v[172:175], v[48:51]
	v_mfma_f32_16x16x32_bf16 v[36:39], v[156:159], v[180:183], v[36:39]
	v_mfma_f32_16x16x32_bf16 v[32:35], v[164:167], v[180:183], v[32:35]
	v_mfma_f32_16x16x32_bf16 v[20:23], v[156:159], v[200:203], v[20:23]
	v_mfma_f32_16x16x32_bf16 v[16:19], v[164:167], v[200:203], v[16:19]
	v_mfma_f32_16x16x32_bf16 v[4:7], v[156:159], v[208:211], v[4:7]
	v_mfma_f32_16x16x32_bf16 v[0:3], v[164:167], v[208:211], v[0:3]
	v_mfma_f32_16x16x32_bf16 v[52:55], v[160:163], v[176:179], v[52:55]
	v_mfma_f32_16x16x32_bf16 v[48:51], v[168:171], v[176:179], v[48:51]
	v_mfma_f32_16x16x32_bf16 v[36:39], v[160:163], v[196:199], v[36:39]
	v_mfma_f32_16x16x32_bf16 v[32:35], v[168:171], v[196:199], v[32:35]
	v_mfma_f32_16x16x32_bf16 v[20:23], v[160:163], v[204:207], v[20:23]
	v_mfma_f32_16x16x32_bf16 v[16:19], v[168:171], v[204:207], v[16:19]
	v_mfma_f32_16x16x32_bf16 v[4:7], v[160:163], v[212:215], v[4:7]
	v_mfma_f32_16x16x32_bf16 v[0:3], v[168:171], v[212:215], v[0:3]
	s_setprio 0
	s_barrier
	s_add_i32 s59, 0, 0x18000
	s_add_i32 s60, 0, 0x1c000
	v_add_u32_e32 v140, s59, v187
	v_add_u32_e32 v168, s60, v187
	ds_read_b128 v[128:131], v140
	ds_read_b128 v[132:135], v140 offset:1024
	ds_read_b128 v[136:139], v140 offset:2048
	ds_read_b128 v[140:143], v140 offset:3072
	ds_read_b128 v[156:159], v168
	ds_read_b128 v[160:163], v168 offset:1024
	ds_read_b128 v[164:167], v168 offset:2048
	ds_read_b128 v[168:171], v168 offset:3072
	s_add_u32 s36, s36, 0x40000
	s_addc_u32 s37, s37, 0
	s_mov_b32 m0, s44
	v_lshl_add_u64 v[222:223], s[36:37], 0, v[144:145]
	ds_read_b128 v[172:175], v192 offset:32768
	ds_read_b128 v[176:179], v192 offset:33792
	ds_read_b128 v[180:183], v192 offset:34816
	ds_read_b128 v[196:199], v192 offset:35840
	ds_read_b128 v[200:203], v192 offset:36864
	ds_read_b128 v[204:207], v192 offset:37888
	ds_read_b128 v[208:211], v192 offset:38912
	ds_read_b128 v[212:215], v192 offset:39936
	global_load_lds_dwordx4 v[222:223], off
	v_lshl_add_u64 v[222:223], s[36:37], 0, v[146:147]
	s_mov_b32 m0, s45
	s_nop 0
	global_load_lds_dwordx4 v[222:223], off
	s_waitcnt vmcnt(8)
	s_waitcnt lgkmcnt(0)
	s_barrier
	s_setprio 1
	s_waitcnt lgkmcnt(0)
	v_mfma_f32_16x16x32_bf16 v[124:127], v[128:131], v[172:175], v[124:127]
	v_mfma_f32_16x16x32_bf16 v[120:123], v[136:139], v[172:175], v[120:123]
	v_mfma_f32_16x16x32_bf16 v[108:111], v[128:131], v[180:183], v[108:111]
	v_mfma_f32_16x16x32_bf16 v[104:107], v[136:139], v[180:183], v[104:107]
	v_mfma_f32_16x16x32_bf16 v[92:95], v[128:131], v[200:203], v[92:95]
	v_mfma_f32_16x16x32_bf16 v[88:91], v[136:139], v[200:203], v[88:91]
	v_mfma_f32_16x16x32_bf16 v[76:79], v[128:131], v[208:211], v[76:79]
	v_mfma_f32_16x16x32_bf16 v[72:75], v[136:139], v[208:211], v[72:75]
	v_mfma_f32_16x16x32_bf16 v[124:127], v[132:135], v[176:179], v[124:127]
	v_mfma_f32_16x16x32_bf16 v[120:123], v[140:143], v[176:179], v[120:123]
	v_mfma_f32_16x16x32_bf16 v[108:111], v[132:135], v[196:199], v[108:111]
	v_mfma_f32_16x16x32_bf16 v[104:107], v[140:143], v[196:199], v[104:107]
	v_mfma_f32_16x16x32_bf16 v[92:95], v[132:135], v[204:207], v[92:95]
	v_mfma_f32_16x16x32_bf16 v[88:91], v[140:143], v[204:207], v[88:91]
	v_mfma_f32_16x16x32_bf16 v[76:79], v[132:135], v[212:215], v[76:79]
	v_mfma_f32_16x16x32_bf16 v[72:75], v[140:143], v[212:215], v[72:75]
	s_setprio 0
	s_setprio 1
	v_mfma_f32_16x16x32_bf16 v[116:119], v[156:159], v[172:175], v[116:119]
	v_mfma_f32_16x16x32_bf16 v[112:115], v[164:167], v[172:175], v[112:115]
	v_mfma_f32_16x16x32_bf16 v[100:103], v[156:159], v[180:183], v[100:103]
	v_mfma_f32_16x16x32_bf16 v[96:99], v[164:167], v[180:183], v[96:99]
	v_mfma_f32_16x16x32_bf16 v[84:87], v[156:159], v[200:203], v[84:87]
	v_mfma_f32_16x16x32_bf16 v[80:83], v[164:167], v[200:203], v[80:83]
	v_mfma_f32_16x16x32_bf16 v[68:71], v[156:159], v[208:211], v[68:71]
	v_mfma_f32_16x16x32_bf16 v[64:67], v[164:167], v[208:211], v[64:67]
	v_mfma_f32_16x16x32_bf16 v[116:119], v[160:163], v[176:179], v[116:119]
	v_mfma_f32_16x16x32_bf16 v[112:115], v[168:171], v[176:179], v[112:115]
	v_mfma_f32_16x16x32_bf16 v[100:103], v[160:163], v[196:199], v[100:103]
	v_mfma_f32_16x16x32_bf16 v[96:99], v[168:171], v[196:199], v[96:99]
	v_mfma_f32_16x16x32_bf16 v[84:87], v[160:163], v[204:207], v[84:87]
	v_mfma_f32_16x16x32_bf16 v[80:83], v[168:171], v[204:207], v[80:83]
	v_mfma_f32_16x16x32_bf16 v[68:71], v[160:163], v[212:215], v[68:71]
	v_mfma_f32_16x16x32_bf16 v[64:67], v[168:171], v[212:215], v[64:67]
	s_setprio 0
	s_barrier
	s_add_i32 s36, s59, s40
	v_lshl_add_u64 v[184:185], v[184:185], 0, s[14:15]
	s_mov_b32 m0, s36
	ds_read_b128 v[172:175], v192 offset:49152
	ds_read_b128 v[176:179], v192 offset:50176
	ds_read_b128 v[180:183], v192 offset:51200
	ds_read_b128 v[196:199], v192 offset:52224
	ds_read_b128 v[200:203], v192 offset:53248
	ds_read_b128 v[204:207], v192 offset:54272
	ds_read_b128 v[208:211], v192 offset:55296
	ds_read_b128 v[212:215], v192 offset:56320
	global_load_lds_dwordx4 v[184:185], off
	s_add_i32 m0, s36, 0x2000
	s_add_u32 s34, s34, 0x40080
	v_lshl_add_u64 v[184:185], v[216:217], 0, s[14:15]
	s_addc_u32 s35, s35, 0
	s_add_i32 s36, s60, s40
	global_load_lds_dwordx4 v[184:185], off
	v_lshl_add_u64 v[184:185], s[34:35], 0, v[144:145]
	s_mov_b32 m0, s36
	s_nop 0
	global_load_lds_dwordx4 v[184:185], off
	v_lshl_add_u64 v[184:185], s[34:35], 0, v[146:147]
	s_add_i32 m0, s36, 0x2000
	s_nop 0
	global_load_lds_dwordx4 v[184:185], off
	v_lshl_add_u64 v[184:185], v[218:219], 0, s[14:15]
	s_mov_b32 m0, s47
	s_nop 0
	global_load_lds_dwordx4 v[184:185], off
	v_lshl_add_u64 v[184:185], v[220:221], 0, s[14:15]
	s_mov_b32 m0, s48
	s_nop 0
	global_load_lds_dwordx4 v[184:185], off
	s_waitcnt vmcnt(8)
	s_waitcnt lgkmcnt(0)
	s_barrier
	s_setprio 1
	s_waitcnt lgkmcnt(0)
	v_mfma_f32_16x16x32_bf16 v[60:63], v[128:131], v[172:175], v[60:63]
	v_mfma_f32_16x16x32_bf16 v[56:59], v[136:139], v[172:175], v[56:59]
	v_mfma_f32_16x16x32_bf16 v[44:47], v[128:131], v[180:183], v[44:47]
	v_mfma_f32_16x16x32_bf16 v[40:43], v[136:139], v[180:183], v[40:43]
	v_mfma_f32_16x16x32_bf16 v[28:31], v[128:131], v[200:203], v[28:31]
	v_mfma_f32_16x16x32_bf16 v[24:27], v[136:139], v[200:203], v[24:27]
	v_mfma_f32_16x16x32_bf16 v[12:15], v[128:131], v[208:211], v[12:15]
	v_mfma_f32_16x16x32_bf16 v[8:11], v[136:139], v[208:211], v[8:11]
	v_mfma_f32_16x16x32_bf16 v[60:63], v[132:135], v[176:179], v[60:63]
	v_mfma_f32_16x16x32_bf16 v[56:59], v[140:143], v[176:179], v[56:59]
	v_mfma_f32_16x16x32_bf16 v[44:47], v[132:135], v[196:199], v[44:47]
	v_mfma_f32_16x16x32_bf16 v[40:43], v[140:143], v[196:199], v[40:43]
	v_mfma_f32_16x16x32_bf16 v[28:31], v[132:135], v[204:207], v[28:31]
	v_mfma_f32_16x16x32_bf16 v[24:27], v[140:143], v[204:207], v[24:27]
	v_mfma_f32_16x16x32_bf16 v[12:15], v[132:135], v[212:215], v[12:15]
	v_mfma_f32_16x16x32_bf16 v[8:11], v[140:143], v[212:215], v[8:11]
	s_setprio 0
	s_setprio 1
	v_mfma_f32_16x16x32_bf16 v[52:55], v[156:159], v[172:175], v[52:55]
	v_mfma_f32_16x16x32_bf16 v[48:51], v[164:167], v[172:175], v[48:51]
	v_mfma_f32_16x16x32_bf16 v[36:39], v[156:159], v[180:183], v[36:39]
	v_mfma_f32_16x16x32_bf16 v[32:35], v[164:167], v[180:183], v[32:35]
	v_mfma_f32_16x16x32_bf16 v[20:23], v[156:159], v[200:203], v[20:23]
	v_mfma_f32_16x16x32_bf16 v[16:19], v[164:167], v[200:203], v[16:19]
	v_mfma_f32_16x16x32_bf16 v[4:7], v[156:159], v[208:211], v[4:7]
	v_mfma_f32_16x16x32_bf16 v[0:3], v[164:167], v[208:211], v[0:3]
	v_mfma_f32_16x16x32_bf16 v[52:55], v[160:163], v[176:179], v[52:55]
	v_mfma_f32_16x16x32_bf16 v[48:51], v[168:171], v[176:179], v[48:51]
	v_mfma_f32_16x16x32_bf16 v[36:39], v[160:163], v[196:199], v[36:39]
	v_mfma_f32_16x16x32_bf16 v[32:35], v[168:171], v[196:199], v[32:35]
	v_mfma_f32_16x16x32_bf16 v[20:23], v[160:163], v[204:207], v[20:23]
	v_mfma_f32_16x16x32_bf16 v[16:19], v[168:171], v[204:207], v[16:19]
	v_mfma_f32_16x16x32_bf16 v[4:7], v[160:163], v[212:215], v[4:7]
	v_mfma_f32_16x16x32_bf16 v[0:3], v[168:171], v[212:215], v[0:3]
	s_setprio 0
	s_add_i32 s58, s58, 2
	s_add_u32 s56, s56, 0x100
	s_addc_u32 s57, s57, 0
	s_add_u32 s30, s30, 0x100
	s_addc_u32 s31, s31, 0
	s_cmp_gt_u32 s58, 13
	s_barrier
	s_cbranch_scc0 .LBB0_2118
	v_mbcnt_lo_u32_b32 v235, -1, 0
	v_mbcnt_hi_u32_b32 v235, -1, v235
	v_lshrrev_b32_e32 v236, 2, v235
	v_and_b32_e32 v237, 3, v235
	v_lshl_add_u32 v232, v237, 4, v236
	v_lshlrev_b32_e32 v232, 2, v232
	v_and_b32_e32 v233, -16, v186
	v_or_b32_e32 v233, v233, v236
	v_lshlrev_b32_e32 v237, 2, v237
	v_and_b32_e32 v234, -13, v188
	v_or_b32_e32 v234, v234, v237
	v_lshl_add_u32 v160, s26, 8, v233
	v_ashrrev_i32_e32 v161, 31, v160
	v_lshl_add_u64 v[158:159], v[160:161], 2, s[12:13]
	global_load_dword v169, v[158:159], off
	v_lshl_or_b32 v156, s28, 8, v234
	v_lshlrev_b64 v[128:129], 11, v[160:161]
	v_ashrrev_i32_e32 v157, 31, v156
	v_lshlrev_b64 v[132:133], 12, v[160:161]
	v_lshl_add_u64 v[128:129], s[6:7], 0, v[128:129]
	v_lshlrev_b64 v[130:131], 1, v[156:157]
	v_lshlrev_b64 v[134:135], 2, v[156:157]
	v_lshl_add_u64 v[132:133], s[4:5], 0, v[132:133]
	v_lshl_add_u64 v[128:129], v[128:129], 0, v[130:131]
	v_lshl_add_u64 v[166:167], v[132:133], 0, v[134:135]
	global_load_dwordx2 v[172:173], v[128:129], off
	global_load_dwordx2 v[176:177], v[128:129], off offset:32
	global_load_dwordx4 v[196:199], v[166:167], off
	global_load_dwordx4 v[200:203], v[166:167], off offset:64
	v_or_b32_e32 v162, 16, v160
	v_ashrrev_i32_e32 v163, 31, v162
	v_lshl_add_u64 v[138:139], v[162:163], 2, s[12:13]
	global_load_dword v168, v[138:139], off
	global_load_dwordx4 v[204:207], v[166:167], off offset:512
	global_load_dwordx4 v[208:211], v[166:167], off offset:576
	global_load_dwordx2 v[180:181], v[128:129], off offset:256
	global_load_dwordx2 v[184:185], v[128:129], off offset:288
	v_lshlrev_b64 v[132:133], 12, v[162:163]
	v_lshlrev_b64 v[136:137], 11, v[162:163]
	v_lshl_add_u64 v[132:133], s[4:5], 0, v[132:133]
	v_lshl_add_u64 v[136:137], s[6:7], 0, v[136:137]
	v_lshl_add_u64 v[164:165], v[132:133], 0, v[134:135]
	v_lshl_add_u64 v[170:171], v[136:137], 0, v[130:131]
	global_load_dwordx4 v[140:143], v[164:165], off
	global_load_dwordx4 v[136:139], v[164:165], off offset:64
	global_load_dwordx4 v[132:135], v[164:165], off offset:512
	global_load_dwordx4 v[128:131], v[164:165], off offset:576
	global_load_dwordx2 v[182:183], v[170:171], off
	global_load_dwordx2 v[178:179], v[170:171], off offset:32
	global_load_dwordx2 v[174:175], v[170:171], off offset:256
	s_nop 0
	global_load_dwordx2 v[170:171], v[170:171], off offset:288
	ds_bpermute_b32 v127, v232, v127
	ds_bpermute_b32 v126, v232, v126
	ds_bpermute_b32 v125, v232, v125
	ds_bpermute_b32 v124, v232, v124
	ds_bpermute_b32 v123, v232, v123
	ds_bpermute_b32 v122, v232, v122
	ds_bpermute_b32 v121, v232, v121
	ds_bpermute_b32 v120, v232, v120
	ds_bpermute_b32 v119, v232, v119
	ds_bpermute_b32 v118, v232, v118
	ds_bpermute_b32 v117, v232, v117
	ds_bpermute_b32 v116, v232, v116
	ds_bpermute_b32 v115, v232, v115
	ds_bpermute_b32 v114, v232, v114
	ds_bpermute_b32 v113, v232, v113
	ds_bpermute_b32 v112, v232, v112
	ds_bpermute_b32 v111, v232, v111
	ds_bpermute_b32 v110, v232, v110
	ds_bpermute_b32 v109, v232, v109
	ds_bpermute_b32 v108, v232, v108
	ds_bpermute_b32 v107, v232, v107
	ds_bpermute_b32 v106, v232, v106
	ds_bpermute_b32 v105, v232, v105
	ds_bpermute_b32 v104, v232, v104
	ds_bpermute_b32 v103, v232, v103
	ds_bpermute_b32 v102, v232, v102
	ds_bpermute_b32 v101, v232, v101
	ds_bpermute_b32 v100, v232, v100
	ds_bpermute_b32 v99, v232, v99
	ds_bpermute_b32 v98, v232, v98
	ds_bpermute_b32 v97, v232, v97
	ds_bpermute_b32 v96, v232, v96
	ds_bpermute_b32 v95, v232, v95
	ds_bpermute_b32 v94, v232, v94
	ds_bpermute_b32 v93, v232, v93
	ds_bpermute_b32 v92, v232, v92
	ds_bpermute_b32 v91, v232, v91
	ds_bpermute_b32 v90, v232, v90
	ds_bpermute_b32 v89, v232, v89
	ds_bpermute_b32 v88, v232, v88
	ds_bpermute_b32 v87, v232, v87
	ds_bpermute_b32 v86, v232, v86
	ds_bpermute_b32 v85, v232, v85
	ds_bpermute_b32 v84, v232, v84
	ds_bpermute_b32 v83, v232, v83
	ds_bpermute_b32 v82, v232, v82
	ds_bpermute_b32 v81, v232, v81
	ds_bpermute_b32 v80, v232, v80
	ds_bpermute_b32 v79, v232, v79
	ds_bpermute_b32 v78, v232, v78
	ds_bpermute_b32 v77, v232, v77
	ds_bpermute_b32 v76, v232, v76
	ds_bpermute_b32 v75, v232, v75
	ds_bpermute_b32 v74, v232, v74
	ds_bpermute_b32 v73, v232, v73
	ds_bpermute_b32 v72, v232, v72
	ds_bpermute_b32 v71, v232, v71
	ds_bpermute_b32 v70, v232, v70
	ds_bpermute_b32 v69, v232, v69
	ds_bpermute_b32 v68, v232, v68
	ds_bpermute_b32 v67, v232, v67
	ds_bpermute_b32 v66, v232, v66
	ds_bpermute_b32 v65, v232, v65
	ds_bpermute_b32 v64, v232, v64
	ds_bpermute_b32 v63, v232, v63
	ds_bpermute_b32 v62, v232, v62
	ds_bpermute_b32 v61, v232, v61
	ds_bpermute_b32 v60, v232, v60
	ds_bpermute_b32 v59, v232, v59
	ds_bpermute_b32 v58, v232, v58
	ds_bpermute_b32 v57, v232, v57
	ds_bpermute_b32 v56, v232, v56
	ds_bpermute_b32 v55, v232, v55
	ds_bpermute_b32 v54, v232, v54
	ds_bpermute_b32 v53, v232, v53
	ds_bpermute_b32 v52, v232, v52
	ds_bpermute_b32 v51, v232, v51
	ds_bpermute_b32 v50, v232, v50
	ds_bpermute_b32 v49, v232, v49
	ds_bpermute_b32 v48, v232, v48
	ds_bpermute_b32 v47, v232, v47
	ds_bpermute_b32 v46, v232, v46
	ds_bpermute_b32 v45, v232, v45
	ds_bpermute_b32 v44, v232, v44
	ds_bpermute_b32 v43, v232, v43
	ds_bpermute_b32 v42, v232, v42
	ds_bpermute_b32 v41, v232, v41
	ds_bpermute_b32 v40, v232, v40
	ds_bpermute_b32 v39, v232, v39
	ds_bpermute_b32 v38, v232, v38
	ds_bpermute_b32 v37, v232, v37
	ds_bpermute_b32 v36, v232, v36
	ds_bpermute_b32 v35, v232, v35
	ds_bpermute_b32 v34, v232, v34
	ds_bpermute_b32 v33, v232, v33
	ds_bpermute_b32 v32, v232, v32
	ds_bpermute_b32 v31, v232, v31
	ds_bpermute_b32 v30, v232, v30
	ds_bpermute_b32 v29, v232, v29
	ds_bpermute_b32 v28, v232, v28
	ds_bpermute_b32 v27, v232, v27
	ds_bpermute_b32 v26, v232, v26
	ds_bpermute_b32 v25, v232, v25
	ds_bpermute_b32 v24, v232, v24
	ds_bpermute_b32 v23, v232, v23
	ds_bpermute_b32 v22, v232, v22
	ds_bpermute_b32 v21, v232, v21
	ds_bpermute_b32 v20, v232, v20
	ds_bpermute_b32 v19, v232, v19
	ds_bpermute_b32 v18, v232, v18
	ds_bpermute_b32 v17, v232, v17
	ds_bpermute_b32 v16, v232, v16
	ds_bpermute_b32 v15, v232, v15
	ds_bpermute_b32 v14, v232, v14
	ds_bpermute_b32 v13, v232, v13
	ds_bpermute_b32 v12, v232, v12
	ds_bpermute_b32 v11, v232, v11
	ds_bpermute_b32 v10, v232, v10
	ds_bpermute_b32 v9, v232, v9
	ds_bpermute_b32 v8, v232, v8
	ds_bpermute_b32 v7, v232, v7
	ds_bpermute_b32 v6, v232, v6
	ds_bpermute_b32 v5, v232, v5
	ds_bpermute_b32 v4, v232, v4
	ds_bpermute_b32 v3, v232, v3
	ds_bpermute_b32 v2, v232, v2
	ds_bpermute_b32 v1, v232, v1
	ds_bpermute_b32 v0, v232, v0
	s_waitcnt lgkmcnt(0)
	s_waitcnt lgkmcnt(0)
	s_and_b64 vcc, exec, s[16:17]
	s_cbranch_vccz .LBB0_2121
	s_barrier
